# peeled first K-loop iteration per unit with srcC=0, per-unit zeroing of 128 accumulators removed (on top of v27)
# speedup vs baseline: 1.0185x; 1.0185x over previous
; #define PG8_STAGE(bufoff, gbase, voff) do { _Pragma("unroll") for (int _i = 0; _i < 2; ++_i) \
;         __builtin_amdgcn_global_load_lds((const unsigned*)((const char*)(gbase) + (voff)[_i]), (PG8_LAS unsigned*)(lds + (bufoff) + ldsw + _i * 8192), 16, 0, 0); } while (0)
; #define PG8_LDA(dst, b, h) do { _Pragma("unroll") for (int m = 0; m < 4; ++m) _Pragma("unroll") for (int k = 0; k < 2; ++k) dst[m][k] = *(const PG8_LAS bf16x8*)(lds + PG8_SA(b, h) + aoff + m * 2048 + k * 1024); } while (0)
; #define PG8_LDB(dst, b, h) do { _Pragma("unroll") for (int n = 0; n < 2; ++n) _Pragma("unroll") for (int k = 0; k < 2; ++k) dst[n][k] = *(const PG8_LAS bf16x8*)(lds + PG8_SB(b, h) + boff + n * 2048 + k * 1024); } while (0)
; #define PG8_WAIT_V(n) asm volatile("s_waitcnt vmcnt(" #n ")" ::: "memory")
; #define PG8_WAIT_L(n) asm volatile("s_waitcnt lgkmcnt(" #n ")" ::: "memory")
; template <class Epi, class Sched, bool ALIGN_EPI = false, bool SP2 = false>
; __device__ __forceinline__ void gemm_phase(PG8_LAS unsigned char* lds, const Gemm g, const Sched& S, const Epi& E) {
;     ...
;         const bool has_next = S.next(ui + 1, nxt);
;         const char* nA = has_next ? (const char*)g.A + (size_t)nxt.pm * tstep : cA; const char* nB = has_next ? (const char*)g.Bt + (size_t)nxt.pn * tstep : cB;
;         for (int t = 0; t < nt; t += 2) {
;             const bool last = (t == nt - 2);
;             if constexpr (Epi::PREFETCH) { if (t == nt - 4) E.prefetch(cur, lds + STAGE_BYTES + 1024, tid); }
;             const char* a1 = cA + (size_t)(t + 1) * kstep;
;             const char* a2 = last ? nA : cA + (size_t)(t + 2) * kstep; const char* b2 = last ? nB : cB + (size_t)(t + 2) * kstep;
;             const char* a3 = a2 + kstep; const char* b3 = b2 + kstep;
;             if (last && has_next) S.a_ready(nxt);
;             if constexpr (SP2) {
;             PG8_LDB(B0, 0, 0); PG8_LDB(B1, 0, 1); PG8_SCHED; PG8_LDA(At, 0, 0); PG8_STAGE(PG8_SA(1, 1), a1 + hstep, voffA);
;             PG8_WAIT_V(8); PG8_WAIT_L(0); PG8_BAR; PG8_MMA(0, 0, At, B0); PG8_MMA(0, 1, At, B1); PG8_BAR; PG8_SCHED;
;             PG8_LDA(At, 0, 1); PG8_STAGE(PG8_SB(0, 0), b2, voffB); PG8_STAGE(PG8_SB(0, 1), b2 + hstep, voffB); PG8_STAGE(PG8_SA(0, 0), a2, voffA);
;             PG8_WAIT_V(8); PG8_WAIT_L(0); PG8_BAR; PG8_MMA(1, 0, At, B0); PG8_MMA(1, 1, At, B1); PG8_BAR; PG8_SCHED;
.LBB0_231:
	s_ashr_i32 s21, s20, 31
	s_lshl_b64 s[22:23], s[20:21], 19
	s_add_u32 s22, s44, s22
	s_addc_u32 s23, s45, s23
	s_and_b64 s[34:35], s[4:5], exec
	s_cselect_b32 s21, s23, s39
	s_cselect_b32 s64, s22, s38
	s_ashr_i32 s19, s18, 31
	s_lshl_b64 s[34:35], s[18:19], 19
	s_add_u32 s34, s46, s34
	s_addc_u32 s35, s47, s35
	s_and_b64 s[42:43], s[4:5], exec
	s_cselect_b32 s19, s35, s41
	s_cselect_b32 s65, s34, s40
	s_add_u32 s38, s38, 0x40080
	s_addc_u32 s39, s39, 0
	s_add_u32 s66, s40, 0x100
	s_addc_u32 s67, s41, 0
	s_mov_b32 s68, -2
	ds_read_b128 v[154:157], v149
	ds_read_b128 v[158:161], v149 offset:1024
	ds_read_b128 v[162:165], v149 offset:2048
	ds_read_b128 v[166:169], v149 offset:3072
	ds_read_b128 v[170:173], v150
	ds_read_b128 v[174:177], v150 offset:1024
	ds_read_b128 v[178:181], v150 offset:2048
	ds_read_b128 v[182:185], v150 offset:3072
	s_add_u32 s40, s38, 0xfffc0080
	s_addc_u32 s41, s39, -1
	s_cmp_eq_u32 s68, 12
	s_cselect_b32 s43, s21, s41
	s_cselect_b32 s42, s64, s40
	s_cselect_b32 s41, s19, s67
	s_cselect_b32 s40, s65, s66
	v_lshl_add_u64 v[144:145], s[38:39], 0, v[136:137]
	s_add_i32 m0, s37, 0xc000
	ds_read_b128 v[186:189], v151
	ds_read_b128 v[190:193], v151 offset:1024
	ds_read_b128 v[194:197], v151 offset:2048
	ds_read_b128 v[198:201], v151 offset:3072
	ds_read_b128 v[202:205], v151 offset:4096
	ds_read_b128 v[206:209], v151 offset:5120
	ds_read_b128 v[210:213], v151 offset:6144
	ds_read_b128 v[214:217], v151 offset:7168
	global_load_lds_dwordx4 v[144:145], off
	v_lshl_add_u64 v[144:145], s[38:39], 0, v[138:139]
	s_add_i32 m0, s37, 0xe000
	s_nop 0
	global_load_lds_dwordx4 v[144:145], off
	s_waitcnt vmcnt(8)
	s_waitcnt lgkmcnt(0)
	s_barrier
	s_setprio 1
	v_mfma_f32_16x16x32_bf16 v[120:123], v[154:157], v[186:189], 0
	v_mfma_f32_16x16x32_bf16 v[116:119], v[162:165], v[186:189], 0
	v_mfma_f32_16x16x32_bf16 v[108:111], v[154:157], v[194:197], 0
	v_mfma_f32_16x16x32_bf16 v[100:103], v[162:165], v[194:197], 0
	v_mfma_f32_16x16x32_bf16 v[92:95], v[154:157], v[202:205], 0
	v_mfma_f32_16x16x32_bf16 v[84:87], v[162:165], v[202:205], 0
	v_mfma_f32_16x16x32_bf16 v[76:79], v[154:157], v[210:213], 0
	v_mfma_f32_16x16x32_bf16 v[68:71], v[162:165], v[210:213], 0
	v_mfma_f32_16x16x32_bf16 v[120:123], v[158:161], v[190:193], v[120:123]
	v_mfma_f32_16x16x32_bf16 v[116:119], v[166:169], v[190:193], v[116:119]
	v_mfma_f32_16x16x32_bf16 v[108:111], v[158:161], v[198:201], v[108:111]
	v_mfma_f32_16x16x32_bf16 v[100:103], v[166:169], v[198:201], v[100:103]
	v_mfma_f32_16x16x32_bf16 v[92:95], v[158:161], v[206:209], v[92:95]
	v_mfma_f32_16x16x32_bf16 v[84:87], v[166:169], v[206:209], v[84:87]
	v_mfma_f32_16x16x32_bf16 v[76:79], v[158:161], v[214:217], v[76:79]
	v_mfma_f32_16x16x32_bf16 v[68:71], v[166:169], v[214:217], v[68:71]
	v_mfma_f32_16x16x32_bf16 v[124:127], v[170:173], v[186:189], 0
	v_mfma_f32_16x16x32_bf16 v[112:115], v[178:181], v[186:189], 0
	v_mfma_f32_16x16x32_bf16 v[104:107], v[170:173], v[194:197], 0
	v_mfma_f32_16x16x32_bf16 v[96:99], v[178:181], v[194:197], 0
	v_mfma_f32_16x16x32_bf16 v[88:91], v[170:173], v[202:205], 0
	v_mfma_f32_16x16x32_bf16 v[80:83], v[178:181], v[202:205], 0
	v_mfma_f32_16x16x32_bf16 v[72:75], v[170:173], v[210:213], 0
	v_mfma_f32_16x16x32_bf16 v[64:67], v[178:181], v[210:213], 0
	v_mfma_f32_16x16x32_bf16 v[124:127], v[174:177], v[190:193], v[124:127]
	v_mfma_f32_16x16x32_bf16 v[112:115], v[182:185], v[190:193], v[112:115]
	v_mfma_f32_16x16x32_bf16 v[104:107], v[174:177], v[198:201], v[104:107]
	v_mfma_f32_16x16x32_bf16 v[96:99], v[182:185], v[198:201], v[96:99]
	v_mfma_f32_16x16x32_bf16 v[88:91], v[174:177], v[206:209], v[88:91]
	v_mfma_f32_16x16x32_bf16 v[80:83], v[182:185], v[206:209], v[80:83]
	v_mfma_f32_16x16x32_bf16 v[72:75], v[174:177], v[214:217], v[72:75]
	v_mfma_f32_16x16x32_bf16 v[64:67], v[182:185], v[214:217], v[64:67]
	s_barrier
	s_setprio 0
	s_add_i32 s69, s57, s48
	v_lshl_add_u64 v[144:145], s[40:41], 0, v[132:133]
	s_mov_b32 m0, s69
	ds_read_b128 v[186:189], v151 offset:16384
	ds_read_b128 v[190:193], v151 offset:17408
	ds_read_b128 v[194:197], v151 offset:18432
	ds_read_b128 v[198:201], v151 offset:19456
	ds_read_b128 v[202:205], v151 offset:20480
	ds_read_b128 v[206:209], v151 offset:21504
	ds_read_b128 v[210:213], v151 offset:22528
	ds_read_b128 v[214:217], v151 offset:23552
	global_load_lds_dwordx4 v[144:145], off
	s_add_i32 m0, s69, 0x2000
	s_add_u32 s70, s40, 0x40000
	v_lshl_add_u64 v[218:219], s[40:41], 0, v[128:129]
	s_addc_u32 s71, s41, 0
	s_add_i32 s69, s58, s48
	global_load_lds_dwordx4 v[218:219], off
	v_lshl_add_u64 v[220:221], s[70:71], 0, v[132:133]
	s_mov_b32 m0, s69
	v_lshl_add_u64 v[222:223], s[42:43], 0, v[130:131]
	global_load_lds_dwordx4 v[220:221], off
	v_lshl_add_u64 v[220:221], s[70:71], 0, v[128:129]
	s_add_i32 m0, s69, 0x2000
	s_nop 0
	global_load_lds_dwordx4 v[220:221], off
	v_lshl_add_u64 v[220:221], s[42:43], 0, v[134:135]
	s_mov_b32 m0, s37
	s_nop 0
	global_load_lds_dwordx4 v[220:221], off
	s_mov_b32 m0, s50
	s_nop 0
	global_load_lds_dwordx4 v[222:223], off
	s_waitcnt vmcnt(8)
	s_waitcnt lgkmcnt(0)
	s_barrier
; #define PG8_STAGE(bufoff, gbase, voff) do { _Pragma("unroll") for (int _i = 0; _i < 2; ++_i) \
;         __builtin_amdgcn_global_load_lds((const unsigned*)((const char*)(gbase) + (voff)[_i]), (PG8_LAS unsigned*)(lds + (bufoff) + ldsw + _i * 8192), 16, 0, 0); } while (0)
; #define PG8_LDA(dst, b, h) do { _Pragma("unroll") for (int m = 0; m < 4; ++m) _Pragma("unroll") for (int k = 0; k < 2; ++k) dst[m][k] = *(const PG8_LAS bf16x8*)(lds + PG8_SA(b, h) + aoff + m * 2048 + k * 1024); } while (0)
; #define PG8_LDB(dst, b, h) do { _Pragma("unroll") for (int n = 0; n < 2; ++n) _Pragma("unroll") for (int k = 0; k < 2; ++k) dst[n][k] = *(const PG8_LAS bf16x8*)(lds + PG8_SB(b, h) + boff + n * 2048 + k * 1024); } while (0)
; #define PG8_MMA(ai, bj, At, Bt) do { __builtin_amdgcn_s_setprio(1); _Pragma("unroll") for (int m = 0; m < 4; ++m) _Pragma("unroll") for (int n = 0; n < 2; ++n) _Pragma("unroll") for (int k = 0; k < 2; ++k) \
;         acc[ai][bj][m][n] = __builtin_amdgcn_mfma_f32_16x16x32_bf16(Bt[n][k], At[m][k], acc[ai][bj][m][n], 0, 0, 0); __builtin_amdgcn_s_setprio(0); } while (0)
; #define PG8_WAIT_V(n) asm volatile("s_waitcnt vmcnt(" #n ")" ::: "memory")
; #define PG8_WAIT_L(n) asm volatile("s_waitcnt lgkmcnt(" #n ")" ::: "memory")
; #define PG8_BAR __builtin_amdgcn_s_barrier()
; #define PG8_SCHED __builtin_amdgcn_sched_barrier(0)
; template <class Epi, class Sched, bool ALIGN_EPI = false, bool SP2 = false>
; __device__ __forceinline__ void gemm_phase(PG8_LAS unsigned char* lds, const Gemm g, const Sched& S, const Epi& E) {
;     ...
;             PG8_WAIT_V(8); PG8_WAIT_L(0); PG8_BAR; PG8_MMA(1, 0, At, B0); PG8_MMA(1, 1, At, B1); PG8_BAR; PG8_SCHED;
;             PG8_LDB(B0, 1, 0); PG8_LDB(B1, 1, 1); PG8_SCHED; PG8_LDA(At, 1, 0); PG8_STAGE(PG8_SA(0, 1), a2 + hstep, voffA);
;             PG8_WAIT_V(8); PG8_WAIT_L(0); PG8_BAR; PG8_MMA(0, 0, At, B0); PG8_MMA(0, 1, At, B1); PG8_BAR; PG8_SCHED;
	s_setprio 1
	v_mfma_f32_16x16x32_bf16 v[60:63], v[154:157], v[186:189], 0
	v_mfma_f32_16x16x32_bf16 v[52:55], v[162:165], v[186:189], 0
	v_mfma_f32_16x16x32_bf16 v[44:47], v[154:157], v[194:197], 0
	v_mfma_f32_16x16x32_bf16 v[36:39], v[162:165], v[194:197], 0
	v_mfma_f32_16x16x32_bf16 v[28:31], v[154:157], v[202:205], 0
	v_mfma_f32_16x16x32_bf16 v[20:23], v[162:165], v[202:205], 0
	v_mfma_f32_16x16x32_bf16 v[12:15], v[154:157], v[210:213], 0
	v_mfma_f32_16x16x32_bf16 v[4:7], v[162:165], v[210:213], 0
	v_mfma_f32_16x16x32_bf16 v[60:63], v[158:161], v[190:193], v[60:63]
	v_mfma_f32_16x16x32_bf16 v[52:55], v[166:169], v[190:193], v[52:55]
	v_mfma_f32_16x16x32_bf16 v[44:47], v[158:161], v[198:201], v[44:47]
	v_mfma_f32_16x16x32_bf16 v[36:39], v[166:169], v[198:201], v[36:39]
	v_mfma_f32_16x16x32_bf16 v[28:31], v[158:161], v[206:209], v[28:31]
	v_mfma_f32_16x16x32_bf16 v[20:23], v[166:169], v[206:209], v[20:23]
	v_mfma_f32_16x16x32_bf16 v[12:15], v[158:161], v[214:217], v[12:15]
	v_mfma_f32_16x16x32_bf16 v[4:7], v[166:169], v[214:217], v[4:7]
	v_mfma_f32_16x16x32_bf16 v[56:59], v[170:173], v[186:189], 0
	v_mfma_f32_16x16x32_bf16 v[48:51], v[178:181], v[186:189], 0
	v_mfma_f32_16x16x32_bf16 v[40:43], v[170:173], v[194:197], 0
	v_mfma_f32_16x16x32_bf16 v[32:35], v[178:181], v[194:197], 0
	v_mfma_f32_16x16x32_bf16 v[24:27], v[170:173], v[202:205], 0
	v_mfma_f32_16x16x32_bf16 v[16:19], v[178:181], v[202:205], 0
	v_mfma_f32_16x16x32_bf16 v[8:11], v[170:173], v[210:213], 0
	v_mfma_f32_16x16x32_bf16 v[0:3], v[178:181], v[210:213], 0
	v_mfma_f32_16x16x32_bf16 v[56:59], v[174:177], v[190:193], v[56:59]
	v_mfma_f32_16x16x32_bf16 v[48:51], v[182:185], v[190:193], v[48:51]
	v_mfma_f32_16x16x32_bf16 v[40:43], v[174:177], v[198:201], v[40:43]
	v_mfma_f32_16x16x32_bf16 v[32:35], v[182:185], v[198:201], v[32:35]
	v_mfma_f32_16x16x32_bf16 v[24:27], v[174:177], v[206:209], v[24:27]
	v_mfma_f32_16x16x32_bf16 v[16:19], v[182:185], v[206:209], v[16:19]
	v_mfma_f32_16x16x32_bf16 v[8:11], v[174:177], v[214:217], v[8:11]
	v_mfma_f32_16x16x32_bf16 v[0:3], v[182:185], v[214:217], v[0:3]
	s_barrier
	s_setprio 0
	s_add_i32 s69, 0, 0x18000
	v_add_u32_e32 v153, s69, v147
	s_add_i32 s70, 0, 0x1c000
	ds_read_b128 v[154:157], v153
	ds_read_b128 v[158:161], v153 offset:1024
	ds_read_b128 v[162:165], v153 offset:2048
	ds_read_b128 v[166:169], v153 offset:3072
	v_add_u32_e32 v153, s70, v147
	ds_read_b128 v[170:173], v153
	ds_read_b128 v[174:177], v153 offset:1024
	ds_read_b128 v[178:181], v153 offset:2048
	ds_read_b128 v[182:185], v153 offset:3072
	s_add_u32 s42, s42, 0x40000
	s_addc_u32 s43, s43, 0
	s_mov_b32 m0, s51
	v_lshl_add_u64 v[224:225], s[42:43], 0, v[134:135]
	ds_read_b128 v[186:189], v151 offset:32768
	ds_read_b128 v[190:193], v151 offset:33792
	ds_read_b128 v[194:197], v151 offset:34816
	ds_read_b128 v[198:201], v151 offset:35840
	ds_read_b128 v[202:205], v151 offset:36864
	ds_read_b128 v[206:209], v151 offset:37888
	ds_read_b128 v[210:213], v151 offset:38912
	ds_read_b128 v[214:217], v151 offset:39936
	global_load_lds_dwordx4 v[224:225], off
	v_lshl_add_u64 v[224:225], s[42:43], 0, v[130:131]
	s_mov_b32 m0, s52
	s_nop 0
	global_load_lds_dwordx4 v[224:225], off
	s_waitcnt vmcnt(8)
	s_waitcnt lgkmcnt(0)
	s_barrier
	s_setprio 1
	v_mfma_f32_16x16x32_bf16 v[120:123], v[154:157], v[186:189], v[120:123]
	v_mfma_f32_16x16x32_bf16 v[116:119], v[162:165], v[186:189], v[116:119]
	v_mfma_f32_16x16x32_bf16 v[108:111], v[154:157], v[194:197], v[108:111]
	v_mfma_f32_16x16x32_bf16 v[100:103], v[162:165], v[194:197], v[100:103]
	v_mfma_f32_16x16x32_bf16 v[92:95], v[154:157], v[202:205], v[92:95]
	v_mfma_f32_16x16x32_bf16 v[84:87], v[162:165], v[202:205], v[84:87]
	v_mfma_f32_16x16x32_bf16 v[76:79], v[154:157], v[210:213], v[76:79]
	v_mfma_f32_16x16x32_bf16 v[68:71], v[162:165], v[210:213], v[68:71]
	v_mfma_f32_16x16x32_bf16 v[120:123], v[158:161], v[190:193], v[120:123]
	v_mfma_f32_16x16x32_bf16 v[116:119], v[166:169], v[190:193], v[116:119]
	v_mfma_f32_16x16x32_bf16 v[108:111], v[158:161], v[198:201], v[108:111]
	v_mfma_f32_16x16x32_bf16 v[100:103], v[166:169], v[198:201], v[100:103]
	v_mfma_f32_16x16x32_bf16 v[92:95], v[158:161], v[206:209], v[92:95]
	v_mfma_f32_16x16x32_bf16 v[84:87], v[166:169], v[206:209], v[84:87]
	v_mfma_f32_16x16x32_bf16 v[76:79], v[158:161], v[214:217], v[76:79]
	v_mfma_f32_16x16x32_bf16 v[68:71], v[166:169], v[214:217], v[68:71]
	v_mfma_f32_16x16x32_bf16 v[124:127], v[170:173], v[186:189], v[124:127]
	v_mfma_f32_16x16x32_bf16 v[112:115], v[178:181], v[186:189], v[112:115]
	v_mfma_f32_16x16x32_bf16 v[104:107], v[170:173], v[194:197], v[104:107]
	v_mfma_f32_16x16x32_bf16 v[96:99], v[178:181], v[194:197], v[96:99]
	v_mfma_f32_16x16x32_bf16 v[88:91], v[170:173], v[202:205], v[88:91]
	v_mfma_f32_16x16x32_bf16 v[80:83], v[178:181], v[202:205], v[80:83]
	v_mfma_f32_16x16x32_bf16 v[72:75], v[170:173], v[210:213], v[72:75]
	v_mfma_f32_16x16x32_bf16 v[64:67], v[178:181], v[210:213], v[64:67]
	v_mfma_f32_16x16x32_bf16 v[124:127], v[174:177], v[190:193], v[124:127]
	v_mfma_f32_16x16x32_bf16 v[112:115], v[182:185], v[190:193], v[112:115]
	v_mfma_f32_16x16x32_bf16 v[104:107], v[174:177], v[198:201], v[104:107]
	v_mfma_f32_16x16x32_bf16 v[96:99], v[182:185], v[198:201], v[96:99]
	v_mfma_f32_16x16x32_bf16 v[88:91], v[174:177], v[206:209], v[88:91]
	v_mfma_f32_16x16x32_bf16 v[80:83], v[182:185], v[206:209], v[80:83]
	v_mfma_f32_16x16x32_bf16 v[72:75], v[174:177], v[214:217], v[72:75]
	v_mfma_f32_16x16x32_bf16 v[64:67], v[182:185], v[214:217], v[64:67]
	s_barrier
; #define PG8_STAGE(bufoff, gbase, voff) do { _Pragma("unroll") for (int _i = 0; _i < 2; ++_i) \
;         __builtin_amdgcn_global_load_lds((const unsigned*)((const char*)(gbase) + (voff)[_i]), (PG8_LAS unsigned*)(lds + (bufoff) + ldsw + _i * 8192), 16, 0, 0); } while (0)
; #define PG8_LDA(dst, b, h) do { _Pragma("unroll") for (int m = 0; m < 4; ++m) _Pragma("unroll") for (int k = 0; k < 2; ++k) dst[m][k] = *(const PG8_LAS bf16x8*)(lds + PG8_SA(b, h) + aoff + m * 2048 + k * 1024); } while (0)
; #define PG8_MMA(ai, bj, At, Bt) do { __builtin_amdgcn_s_setprio(1); _Pragma("unroll") for (int m = 0; m < 4; ++m) _Pragma("unroll") for (int n = 0; n < 2; ++n) _Pragma("unroll") for (int k = 0; k < 2; ++k) \
;         acc[ai][bj][m][n] = __builtin_amdgcn_mfma_f32_16x16x32_bf16(Bt[n][k], At[m][k], acc[ai][bj][m][n], 0, 0, 0); __builtin_amdgcn_s_setprio(0); } while (0)
; #define PG8_WAIT_V(n) asm volatile("s_waitcnt vmcnt(" #n ")" ::: "memory")
; #define PG8_WAIT_L(n) asm volatile("s_waitcnt lgkmcnt(" #n ")" ::: "memory")
; #define PG8_BAR __builtin_amdgcn_s_barrier()
; #define PG8_SCHED __builtin_amdgcn_sched_barrier(0)
; template <class Epi, class Sched, bool ALIGN_EPI = false, bool SP2 = false>
; __device__ __forceinline__ void gemm_phase(PG8_LAS unsigned char* lds, const Gemm g, const Sched& S, const Epi& E) {
;     ...
;         for (int t = 0; t < nt; t += 2) {
;     ...
;             PG8_LDA(At, 1, 1); PG8_STAGE(PG8_SB(1, 0), b3, voffB); PG8_STAGE(PG8_SB(1, 1), b3 + hstep, voffB); PG8_STAGE(PG8_SA(1, 0), a3, voffA);
;             PG8_WAIT_V(8); PG8_WAIT_L(0); PG8_BAR; PG8_MMA(1, 0, At, B0); PG8_MMA(1, 1, At, B1); PG8_BAR; PG8_SCHED;
	s_setprio 0
	s_add_i32 s42, s69, s48
	v_lshl_add_u64 v[144:145], v[144:145], 0, s[14:15]
	s_mov_b32 m0, s42
	ds_read_b128 v[186:189], v151 offset:49152
	ds_read_b128 v[190:193], v151 offset:50176
	ds_read_b128 v[194:197], v151 offset:51200
	ds_read_b128 v[198:201], v151 offset:52224
	ds_read_b128 v[202:205], v151 offset:53248
	ds_read_b128 v[206:209], v151 offset:54272
	ds_read_b128 v[210:213], v151 offset:55296
	ds_read_b128 v[214:217], v151 offset:56320
	global_load_lds_dwordx4 v[144:145], off
	s_add_i32 m0, s42, 0x2000
	s_add_u32 s40, s40, 0x40080
	v_lshl_add_u64 v[144:145], v[218:219], 0, s[14:15]
	s_addc_u32 s41, s41, 0
	s_add_i32 s42, s70, s48
	global_load_lds_dwordx4 v[144:145], off
	v_lshl_add_u64 v[144:145], s[40:41], 0, v[132:133]
	s_mov_b32 m0, s42
	s_nop 0
	global_load_lds_dwordx4 v[144:145], off
	v_lshl_add_u64 v[144:145], s[40:41], 0, v[128:129]
	s_add_i32 m0, s42, 0x2000
	s_nop 0
	global_load_lds_dwordx4 v[144:145], off
	v_lshl_add_u64 v[144:145], v[220:221], 0, s[14:15]
	s_mov_b32 m0, s54
	s_nop 0
	global_load_lds_dwordx4 v[144:145], off
	v_lshl_add_u64 v[144:145], v[222:223], 0, s[14:15]
	s_mov_b32 m0, s55
	s_nop 0
	global_load_lds_dwordx4 v[144:145], off
	s_waitcnt vmcnt(8)
	s_waitcnt lgkmcnt(0)
	s_barrier
	s_setprio 1
	v_mfma_f32_16x16x32_bf16 v[60:63], v[154:157], v[186:189], v[60:63]
	v_mfma_f32_16x16x32_bf16 v[52:55], v[162:165], v[186:189], v[52:55]
	v_mfma_f32_16x16x32_bf16 v[44:47], v[154:157], v[194:197], v[44:47]
	v_mfma_f32_16x16x32_bf16 v[36:39], v[162:165], v[194:197], v[36:39]
	v_mfma_f32_16x16x32_bf16 v[28:31], v[154:157], v[202:205], v[28:31]
	v_mfma_f32_16x16x32_bf16 v[20:23], v[162:165], v[202:205], v[20:23]
	v_mfma_f32_16x16x32_bf16 v[12:15], v[154:157], v[210:213], v[12:15]
	v_mfma_f32_16x16x32_bf16 v[4:7], v[162:165], v[210:213], v[4:7]
	v_mfma_f32_16x16x32_bf16 v[60:63], v[158:161], v[190:193], v[60:63]
	v_mfma_f32_16x16x32_bf16 v[52:55], v[166:169], v[190:193], v[52:55]
	v_mfma_f32_16x16x32_bf16 v[44:47], v[158:161], v[198:201], v[44:47]
	v_mfma_f32_16x16x32_bf16 v[36:39], v[166:169], v[198:201], v[36:39]
	v_mfma_f32_16x16x32_bf16 v[28:31], v[158:161], v[206:209], v[28:31]
	v_mfma_f32_16x16x32_bf16 v[20:23], v[166:169], v[206:209], v[20:23]
	v_mfma_f32_16x16x32_bf16 v[12:15], v[158:161], v[214:217], v[12:15]
	v_mfma_f32_16x16x32_bf16 v[4:7], v[166:169], v[214:217], v[4:7]
	v_mfma_f32_16x16x32_bf16 v[56:59], v[170:173], v[186:189], v[56:59]
	v_mfma_f32_16x16x32_bf16 v[48:51], v[178:181], v[186:189], v[48:51]
	v_mfma_f32_16x16x32_bf16 v[40:43], v[170:173], v[194:197], v[40:43]
	v_mfma_f32_16x16x32_bf16 v[32:35], v[178:181], v[194:197], v[32:35]
	v_mfma_f32_16x16x32_bf16 v[24:27], v[170:173], v[202:205], v[24:27]
	v_mfma_f32_16x16x32_bf16 v[16:19], v[178:181], v[202:205], v[16:19]
	v_mfma_f32_16x16x32_bf16 v[8:11], v[170:173], v[210:213], v[8:11]
	v_mfma_f32_16x16x32_bf16 v[0:3], v[178:181], v[210:213], v[0:3]
	v_mfma_f32_16x16x32_bf16 v[56:59], v[174:177], v[190:193], v[56:59]
	v_mfma_f32_16x16x32_bf16 v[48:51], v[182:185], v[190:193], v[48:51]
	v_mfma_f32_16x16x32_bf16 v[40:43], v[174:177], v[198:201], v[40:43]
	v_mfma_f32_16x16x32_bf16 v[32:35], v[182:185], v[198:201], v[32:35]
	v_mfma_f32_16x16x32_bf16 v[24:27], v[174:177], v[206:209], v[24:27]
	v_mfma_f32_16x16x32_bf16 v[16:19], v[182:185], v[206:209], v[16:19]
	v_mfma_f32_16x16x32_bf16 v[8:11], v[174:177], v[214:217], v[8:11]
	v_mfma_f32_16x16x32_bf16 v[0:3], v[182:185], v[214:217], v[0:3]
	s_barrier
	s_setprio 0
	s_add_i32 s68, s68, 2
	s_add_u32 s38, s38, 0x100
	s_addc_u32 s39, s39, 0
	s_add_u32 s66, s66, 0x100
	s_addc_u32 s67, s67, 0

; #define PG8_STAGE(bufoff, gbase, voff) do { _Pragma("unroll") for (int _i = 0; _i < 2; ++_i) \
;         __builtin_amdgcn_global_load_lds((const unsigned*)((const char*)(gbase) + (voff)[_i]), (PG8_LAS unsigned*)(lds + (bufoff) + ldsw + _i * 8192), 16, 0, 0); } while (0)
; #define PG8_LDA(dst, b, h) do { _Pragma("unroll") for (int m = 0; m < 4; ++m) _Pragma("unroll") for (int k = 0; k < 2; ++k) dst[m][k] = *(const PG8_LAS bf16x8*)(lds + PG8_SA(b, h) + aoff + m * 2048 + k * 1024); } while (0)
; #define PG8_LDB(dst, b, h) do { _Pragma("unroll") for (int n = 0; n < 2; ++n) _Pragma("unroll") for (int k = 0; k < 2; ++k) dst[n][k] = *(const PG8_LAS bf16x8*)(lds + PG8_SB(b, h) + boff + n * 2048 + k * 1024); } while (0)
; #define PG8_WAIT_V(n) asm volatile("s_waitcnt vmcnt(" #n ")" ::: "memory")
; #define PG8_WAIT_L(n) asm volatile("s_waitcnt lgkmcnt(" #n ")" ::: "memory")
; template <class Epi, class Sched, bool ALIGN_EPI = false, bool SP2 = false>
; __device__ __forceinline__ void gemm_phase(PG8_LAS unsigned char* lds, const Gemm g, const Sched& S, const Epi& E) {
;     ...
;         const bool has_next = S.next(ui + 1, nxt);
;         const char* nA = has_next ? (const char*)g.A + (size_t)nxt.pm * tstep : cA; const char* nB = has_next ? (const char*)g.Bt + (size_t)nxt.pn * tstep : cB;
;         for (int t = 0; t < nt; t += 2) {
;             const bool last = (t == nt - 2);
;             if constexpr (Epi::PREFETCH) { if (t == nt - 4) E.prefetch(cur, lds + STAGE_BYTES + 1024, tid); }
;             const char* a1 = cA + (size_t)(t + 1) * kstep;
;             const char* a2 = last ? nA : cA + (size_t)(t + 2) * kstep; const char* b2 = last ? nB : cB + (size_t)(t + 2) * kstep;
;             const char* a3 = a2 + kstep; const char* b3 = b2 + kstep;
;             if (last && has_next) S.a_ready(nxt);
;             if constexpr (SP2) {
;             PG8_LDB(B0, 0, 0); PG8_LDB(B1, 0, 1); PG8_SCHED; PG8_LDA(At, 0, 0); PG8_STAGE(PG8_SA(1, 1), a1 + hstep, voffA);
;             PG8_WAIT_V(8); PG8_WAIT_L(0); PG8_BAR; PG8_MMA(0, 0, At, B0); PG8_MMA(0, 1, At, B1); PG8_BAR; PG8_SCHED;
;             PG8_LDA(At, 0, 1); PG8_STAGE(PG8_SB(0, 0), b2, voffB); PG8_STAGE(PG8_SB(0, 1), b2 + hstep, voffB); PG8_STAGE(PG8_SA(0, 0), a2, voffA);
;             PG8_WAIT_V(8); PG8_WAIT_L(0); PG8_BAR; PG8_MMA(1, 0, At, B0); PG8_MMA(1, 1, At, B1); PG8_BAR; PG8_SCHED;
.LBB0_405:
	s_add_u32 s34, s34, 0xb0080
	s_addc_u32 s35, s35, 0
	s_add_u32 s59, s36, 0x100
	s_addc_u32 s63, s37, 0
	s_mov_b32 s64, -2
	ds_read_b128 v[112:115], v246
	ds_read_b128 v[116:119], v246 offset:1024
	ds_read_b128 v[120:123], v246 offset:2048
	ds_read_b128 v[124:127], v246 offset:3072
	ds_read_b128 v[136:139], v247
	ds_read_b128 v[140:143], v247 offset:1024
	ds_read_b128 v[152:155], v247 offset:2048
	ds_read_b128 v[156:159], v247 offset:3072
	s_add_u32 s36, s34, 0xfff50080
	s_addc_u32 s37, s35, -1
	s_cmp_eq_u32 s64, 40
	s_cselect_b32 s39, s9, s37
	s_cselect_b32 s38, s8, s36
	s_cselect_b32 s37, s23, s63
	s_cselect_b32 s36, s22, s59
	v_lshl_add_u64 v[206:207], s[34:35], 0, v[200:201]
	s_add_i32 m0, s45, 0xc000
	ds_read_b128 v[160:163], v248
	ds_read_b128 v[164:167], v248 offset:1024
	ds_read_b128 v[168:171], v248 offset:2048
	ds_read_b128 v[172:175], v248 offset:3072
	ds_read_b128 v[176:179], v248 offset:4096
	ds_read_b128 v[180:183], v248 offset:5120
	ds_read_b128 v[184:187], v248 offset:6144
	ds_read_b128 v[188:191], v248 offset:7168
	global_load_lds_dwordx4 v[206:207], off
	v_lshl_add_u64 v[206:207], s[34:35], 0, v[202:203]
	s_add_i32 m0, s45, 0xe000
	s_nop 0
	global_load_lds_dwordx4 v[206:207], off
	s_waitcnt vmcnt(8)
	s_waitcnt lgkmcnt(0)
	s_barrier
	s_setprio 1
	v_mfma_f32_16x16x32_bf16 v[148:151], v[112:115], v[160:163], 0
	v_mfma_f32_16x16x32_bf16 v[144:147], v[120:123], v[160:163], 0
	v_mfma_f32_16x16x32_bf16 v[108:111], v[112:115], v[168:171], 0
	v_mfma_f32_16x16x32_bf16 v[104:107], v[120:123], v[168:171], 0
	v_mfma_f32_16x16x32_bf16 v[92:95], v[112:115], v[176:179], 0
	v_mfma_f32_16x16x32_bf16 v[88:91], v[120:123], v[176:179], 0
	v_mfma_f32_16x16x32_bf16 v[76:79], v[112:115], v[184:187], 0
	v_mfma_f32_16x16x32_bf16 v[72:75], v[120:123], v[184:187], 0
	v_mfma_f32_16x16x32_bf16 v[148:151], v[116:119], v[164:167], v[148:151]
	v_mfma_f32_16x16x32_bf16 v[144:147], v[124:127], v[164:167], v[144:147]
	v_mfma_f32_16x16x32_bf16 v[108:111], v[116:119], v[172:175], v[108:111]
	v_mfma_f32_16x16x32_bf16 v[104:107], v[124:127], v[172:175], v[104:107]
	v_mfma_f32_16x16x32_bf16 v[92:95], v[116:119], v[180:183], v[92:95]
	v_mfma_f32_16x16x32_bf16 v[88:91], v[124:127], v[180:183], v[88:91]
	v_mfma_f32_16x16x32_bf16 v[76:79], v[116:119], v[188:191], v[76:79]
	v_mfma_f32_16x16x32_bf16 v[72:75], v[124:127], v[188:191], v[72:75]
	v_mfma_f32_16x16x32_bf16 v[132:135], v[136:139], v[160:163], 0
	v_mfma_f32_16x16x32_bf16 v[128:131], v[152:155], v[160:163], 0
	v_mfma_f32_16x16x32_bf16 v[100:103], v[136:139], v[168:171], 0
	v_mfma_f32_16x16x32_bf16 v[96:99], v[152:155], v[168:171], 0
	v_mfma_f32_16x16x32_bf16 v[84:87], v[136:139], v[176:179], 0
	v_mfma_f32_16x16x32_bf16 v[80:83], v[152:155], v[176:179], 0
	v_mfma_f32_16x16x32_bf16 v[68:71], v[136:139], v[184:187], 0
	v_mfma_f32_16x16x32_bf16 v[64:67], v[152:155], v[184:187], 0
	v_mfma_f32_16x16x32_bf16 v[132:135], v[140:143], v[164:167], v[132:135]
	v_mfma_f32_16x16x32_bf16 v[128:131], v[156:159], v[164:167], v[128:131]
	v_mfma_f32_16x16x32_bf16 v[100:103], v[140:143], v[172:175], v[100:103]
	v_mfma_f32_16x16x32_bf16 v[96:99], v[156:159], v[172:175], v[96:99]
	v_mfma_f32_16x16x32_bf16 v[84:87], v[140:143], v[180:183], v[84:87]
	v_mfma_f32_16x16x32_bf16 v[80:83], v[156:159], v[180:183], v[80:83]
	v_mfma_f32_16x16x32_bf16 v[68:71], v[140:143], v[188:191], v[68:71]
	v_mfma_f32_16x16x32_bf16 v[64:67], v[156:159], v[188:191], v[64:67]
	s_barrier
	s_setprio 0
	s_add_i32 s65, s53, s44
	v_lshl_add_u64 v[206:207], s[36:37], 0, v[194:195]
	s_mov_b32 m0, s65
	ds_read_b128 v[160:163], v248 offset:16384
	ds_read_b128 v[164:167], v248 offset:17408
	ds_read_b128 v[168:171], v248 offset:18432
	ds_read_b128 v[172:175], v248 offset:19456
	ds_read_b128 v[176:179], v248 offset:20480
	ds_read_b128 v[180:183], v248 offset:21504
	ds_read_b128 v[184:187], v248 offset:22528
	ds_read_b128 v[188:191], v248 offset:23552
	global_load_lds_dwordx4 v[206:207], off
	s_add_i32 m0, s65, 0x2000
	s_add_u32 s66, s36, 0xb0000
	v_lshl_add_u64 v[208:209], s[36:37], 0, v[198:199]
	s_addc_u32 s67, s37, 0
	s_add_i32 s65, s54, s44
	global_load_lds_dwordx4 v[208:209], off
	v_lshl_add_u64 v[210:211], s[66:67], 0, v[194:195]
	s_mov_b32 m0, s65
	v_lshl_add_u64 v[212:213], s[38:39], 0, v[196:197]
	global_load_lds_dwordx4 v[210:211], off
	v_lshl_add_u64 v[210:211], s[66:67], 0, v[198:199]
	s_add_i32 m0, s65, 0x2000
	s_nop 0
	global_load_lds_dwordx4 v[210:211], off
	v_lshl_add_u64 v[210:211], s[38:39], 0, v[192:193]
	s_mov_b32 m0, s45
	s_nop 0
	global_load_lds_dwordx4 v[210:211], off
	s_mov_b32 m0, s46
	s_nop 0
	global_load_lds_dwordx4 v[212:213], off
	s_waitcnt vmcnt(8)
	s_waitcnt lgkmcnt(0)
	s_barrier
; #define PG8_STAGE(bufoff, gbase, voff) do { _Pragma("unroll") for (int _i = 0; _i < 2; ++_i) \
;         __builtin_amdgcn_global_load_lds((const unsigned*)((const char*)(gbase) + (voff)[_i]), (PG8_LAS unsigned*)(lds + (bufoff) + ldsw + _i * 8192), 16, 0, 0); } while (0)
; #define PG8_LDA(dst, b, h) do { _Pragma("unroll") for (int m = 0; m < 4; ++m) _Pragma("unroll") for (int k = 0; k < 2; ++k) dst[m][k] = *(const PG8_LAS bf16x8*)(lds + PG8_SA(b, h) + aoff + m * 2048 + k * 1024); } while (0)
; #define PG8_LDB(dst, b, h) do { _Pragma("unroll") for (int n = 0; n < 2; ++n) _Pragma("unroll") for (int k = 0; k < 2; ++k) dst[n][k] = *(const PG8_LAS bf16x8*)(lds + PG8_SB(b, h) + boff + n * 2048 + k * 1024); } while (0)
; #define PG8_MMA(ai, bj, At, Bt) do { __builtin_amdgcn_s_setprio(1); _Pragma("unroll") for (int m = 0; m < 4; ++m) _Pragma("unroll") for (int n = 0; n < 2; ++n) _Pragma("unroll") for (int k = 0; k < 2; ++k) \
;         acc[ai][bj][m][n] = __builtin_amdgcn_mfma_f32_16x16x32_bf16(Bt[n][k], At[m][k], acc[ai][bj][m][n], 0, 0, 0); __builtin_amdgcn_s_setprio(0); } while (0)
; #define PG8_WAIT_V(n) asm volatile("s_waitcnt vmcnt(" #n ")" ::: "memory")
; #define PG8_WAIT_L(n) asm volatile("s_waitcnt lgkmcnt(" #n ")" ::: "memory")
; #define PG8_BAR __builtin_amdgcn_s_barrier()
; #define PG8_SCHED __builtin_amdgcn_sched_barrier(0)
; template <class Epi, class Sched, bool ALIGN_EPI = false, bool SP2 = false>
; __device__ __forceinline__ void gemm_phase(PG8_LAS unsigned char* lds, const Gemm g, const Sched& S, const Epi& E) {
;     ...
;             PG8_WAIT_V(8); PG8_WAIT_L(0); PG8_BAR; PG8_MMA(1, 0, At, B0); PG8_MMA(1, 1, At, B1); PG8_BAR; PG8_SCHED;
;             PG8_LDB(B0, 1, 0); PG8_LDB(B1, 1, 1); PG8_SCHED; PG8_LDA(At, 1, 0); PG8_STAGE(PG8_SA(0, 1), a2 + hstep, voffA);
;             PG8_WAIT_V(8); PG8_WAIT_L(0); PG8_BAR; PG8_MMA(0, 0, At, B0); PG8_MMA(0, 1, At, B1); PG8_BAR; PG8_SCHED;
	s_setprio 1
	v_mfma_f32_16x16x32_bf16 v[60:63], v[112:115], v[160:163], 0
	v_mfma_f32_16x16x32_bf16 v[56:59], v[120:123], v[160:163], 0
	v_mfma_f32_16x16x32_bf16 v[44:47], v[112:115], v[168:171], 0
	v_mfma_f32_16x16x32_bf16 v[40:43], v[120:123], v[168:171], 0
	v_mfma_f32_16x16x32_bf16 v[28:31], v[112:115], v[176:179], 0
	v_mfma_f32_16x16x32_bf16 v[24:27], v[120:123], v[176:179], 0
	v_mfma_f32_16x16x32_bf16 v[12:15], v[112:115], v[184:187], 0
	v_mfma_f32_16x16x32_bf16 v[8:11], v[120:123], v[184:187], 0
	v_mfma_f32_16x16x32_bf16 v[60:63], v[116:119], v[164:167], v[60:63]
	v_mfma_f32_16x16x32_bf16 v[56:59], v[124:127], v[164:167], v[56:59]
	v_mfma_f32_16x16x32_bf16 v[44:47], v[116:119], v[172:175], v[44:47]
	v_mfma_f32_16x16x32_bf16 v[40:43], v[124:127], v[172:175], v[40:43]
	v_mfma_f32_16x16x32_bf16 v[28:31], v[116:119], v[180:183], v[28:31]
	v_mfma_f32_16x16x32_bf16 v[24:27], v[124:127], v[180:183], v[24:27]
	v_mfma_f32_16x16x32_bf16 v[12:15], v[116:119], v[188:191], v[12:15]
	v_mfma_f32_16x16x32_bf16 v[8:11], v[124:127], v[188:191], v[8:11]
	v_mfma_f32_16x16x32_bf16 v[52:55], v[136:139], v[160:163], 0
	v_mfma_f32_16x16x32_bf16 v[48:51], v[152:155], v[160:163], 0
	v_mfma_f32_16x16x32_bf16 v[36:39], v[136:139], v[168:171], 0
	v_mfma_f32_16x16x32_bf16 v[32:35], v[152:155], v[168:171], 0
	v_mfma_f32_16x16x32_bf16 v[20:23], v[136:139], v[176:179], 0
	v_mfma_f32_16x16x32_bf16 v[16:19], v[152:155], v[176:179], 0
	v_mfma_f32_16x16x32_bf16 v[4:7], v[136:139], v[184:187], 0
	v_mfma_f32_16x16x32_bf16 v[0:3], v[152:155], v[184:187], 0
	v_mfma_f32_16x16x32_bf16 v[52:55], v[140:143], v[164:167], v[52:55]
	v_mfma_f32_16x16x32_bf16 v[48:51], v[156:159], v[164:167], v[48:51]
	v_mfma_f32_16x16x32_bf16 v[36:39], v[140:143], v[172:175], v[36:39]
	v_mfma_f32_16x16x32_bf16 v[32:35], v[156:159], v[172:175], v[32:35]
	v_mfma_f32_16x16x32_bf16 v[20:23], v[140:143], v[180:183], v[20:23]
	v_mfma_f32_16x16x32_bf16 v[16:19], v[156:159], v[180:183], v[16:19]
	v_mfma_f32_16x16x32_bf16 v[4:7], v[140:143], v[188:191], v[4:7]
	v_mfma_f32_16x16x32_bf16 v[0:3], v[156:159], v[188:191], v[0:3]
	s_barrier
	s_setprio 0
	s_add_i32 s65, 0, 0x18000
	s_add_i32 s66, 0, 0x1c000
	v_add_u32_e32 v124, s65, v244
	v_add_u32_e32 v156, s66, v244
	ds_read_b128 v[112:115], v124
	ds_read_b128 v[116:119], v124 offset:1024
	ds_read_b128 v[120:123], v124 offset:2048
	ds_read_b128 v[124:127], v124 offset:3072
	ds_read_b128 v[136:139], v156
	ds_read_b128 v[140:143], v156 offset:1024
	ds_read_b128 v[152:155], v156 offset:2048
	ds_read_b128 v[156:159], v156 offset:3072
	s_add_u32 s38, s38, 0xb0000
	s_addc_u32 s39, s39, 0
	s_mov_b32 m0, s47
	v_lshl_add_u64 v[214:215], s[38:39], 0, v[192:193]
	ds_read_b128 v[160:163], v248 offset:32768
	ds_read_b128 v[164:167], v248 offset:33792
	ds_read_b128 v[168:171], v248 offset:34816
	ds_read_b128 v[172:175], v248 offset:35840
	ds_read_b128 v[176:179], v248 offset:36864
	ds_read_b128 v[180:183], v248 offset:37888
	ds_read_b128 v[184:187], v248 offset:38912
	ds_read_b128 v[188:191], v248 offset:39936
	global_load_lds_dwordx4 v[214:215], off
	v_lshl_add_u64 v[214:215], s[38:39], 0, v[196:197]
	s_mov_b32 m0, s48
	s_nop 0
	global_load_lds_dwordx4 v[214:215], off
	s_waitcnt vmcnt(8)
	s_waitcnt lgkmcnt(0)
	s_barrier
	s_setprio 1
	v_mfma_f32_16x16x32_bf16 v[148:151], v[112:115], v[160:163], v[148:151]
	v_mfma_f32_16x16x32_bf16 v[144:147], v[120:123], v[160:163], v[144:147]
	v_mfma_f32_16x16x32_bf16 v[108:111], v[112:115], v[168:171], v[108:111]
	v_mfma_f32_16x16x32_bf16 v[104:107], v[120:123], v[168:171], v[104:107]
	v_mfma_f32_16x16x32_bf16 v[92:95], v[112:115], v[176:179], v[92:95]
	v_mfma_f32_16x16x32_bf16 v[88:91], v[120:123], v[176:179], v[88:91]
	v_mfma_f32_16x16x32_bf16 v[76:79], v[112:115], v[184:187], v[76:79]
	v_mfma_f32_16x16x32_bf16 v[72:75], v[120:123], v[184:187], v[72:75]
	v_mfma_f32_16x16x32_bf16 v[148:151], v[116:119], v[164:167], v[148:151]
	v_mfma_f32_16x16x32_bf16 v[144:147], v[124:127], v[164:167], v[144:147]
	v_mfma_f32_16x16x32_bf16 v[108:111], v[116:119], v[172:175], v[108:111]
	v_mfma_f32_16x16x32_bf16 v[104:107], v[124:127], v[172:175], v[104:107]
	v_mfma_f32_16x16x32_bf16 v[92:95], v[116:119], v[180:183], v[92:95]
	v_mfma_f32_16x16x32_bf16 v[88:91], v[124:127], v[180:183], v[88:91]
	v_mfma_f32_16x16x32_bf16 v[76:79], v[116:119], v[188:191], v[76:79]
	v_mfma_f32_16x16x32_bf16 v[72:75], v[124:127], v[188:191], v[72:75]
	v_mfma_f32_16x16x32_bf16 v[132:135], v[136:139], v[160:163], v[132:135]
	v_mfma_f32_16x16x32_bf16 v[128:131], v[152:155], v[160:163], v[128:131]
	v_mfma_f32_16x16x32_bf16 v[100:103], v[136:139], v[168:171], v[100:103]
	v_mfma_f32_16x16x32_bf16 v[96:99], v[152:155], v[168:171], v[96:99]
	v_mfma_f32_16x16x32_bf16 v[84:87], v[136:139], v[176:179], v[84:87]
	v_mfma_f32_16x16x32_bf16 v[80:83], v[152:155], v[176:179], v[80:83]
	v_mfma_f32_16x16x32_bf16 v[68:71], v[136:139], v[184:187], v[68:71]
	v_mfma_f32_16x16x32_bf16 v[64:67], v[152:155], v[184:187], v[64:67]
	v_mfma_f32_16x16x32_bf16 v[132:135], v[140:143], v[164:167], v[132:135]
	v_mfma_f32_16x16x32_bf16 v[128:131], v[156:159], v[164:167], v[128:131]
	v_mfma_f32_16x16x32_bf16 v[100:103], v[140:143], v[172:175], v[100:103]
	v_mfma_f32_16x16x32_bf16 v[96:99], v[156:159], v[172:175], v[96:99]
	v_mfma_f32_16x16x32_bf16 v[84:87], v[140:143], v[180:183], v[84:87]
	v_mfma_f32_16x16x32_bf16 v[80:83], v[156:159], v[180:183], v[80:83]
	v_mfma_f32_16x16x32_bf16 v[68:71], v[140:143], v[188:191], v[68:71]
	v_mfma_f32_16x16x32_bf16 v[64:67], v[156:159], v[188:191], v[64:67]
	s_barrier
; #define PG8_STAGE(bufoff, gbase, voff) do { _Pragma("unroll") for (int _i = 0; _i < 2; ++_i) \
;         __builtin_amdgcn_global_load_lds((const unsigned*)((const char*)(gbase) + (voff)[_i]), (PG8_LAS unsigned*)(lds + (bufoff) + ldsw + _i * 8192), 16, 0, 0); } while (0)
; #define PG8_LDA(dst, b, h) do { _Pragma("unroll") for (int m = 0; m < 4; ++m) _Pragma("unroll") for (int k = 0; k < 2; ++k) dst[m][k] = *(const PG8_LAS bf16x8*)(lds + PG8_SA(b, h) + aoff + m * 2048 + k * 1024); } while (0)
; #define PG8_MMA(ai, bj, At, Bt) do { __builtin_amdgcn_s_setprio(1); _Pragma("unroll") for (int m = 0; m < 4; ++m) _Pragma("unroll") for (int n = 0; n < 2; ++n) _Pragma("unroll") for (int k = 0; k < 2; ++k) \
;         acc[ai][bj][m][n] = __builtin_amdgcn_mfma_f32_16x16x32_bf16(Bt[n][k], At[m][k], acc[ai][bj][m][n], 0, 0, 0); __builtin_amdgcn_s_setprio(0); } while (0)
; #define PG8_WAIT_V(n) asm volatile("s_waitcnt vmcnt(" #n ")" ::: "memory")
; #define PG8_WAIT_L(n) asm volatile("s_waitcnt lgkmcnt(" #n ")" ::: "memory")
; #define PG8_BAR __builtin_amdgcn_s_barrier()
; #define PG8_SCHED __builtin_amdgcn_sched_barrier(0)
; template <class Epi, class Sched, bool ALIGN_EPI = false, bool SP2 = false>
; __device__ __forceinline__ void gemm_phase(PG8_LAS unsigned char* lds, const Gemm g, const Sched& S, const Epi& E) {
;     ...
;         for (int t = 0; t < nt; t += 2) {
;     ...
;             PG8_LDA(At, 1, 1); PG8_STAGE(PG8_SB(1, 0), b3, voffB); PG8_STAGE(PG8_SB(1, 1), b3 + hstep, voffB); PG8_STAGE(PG8_SA(1, 0), a3, voffA);
;             PG8_WAIT_V(8); PG8_WAIT_L(0); PG8_BAR; PG8_MMA(1, 0, At, B0); PG8_MMA(1, 1, At, B1); PG8_BAR; PG8_SCHED;
	s_setprio 0
	s_add_i32 s38, s65, s44
	v_lshl_add_u64 v[206:207], v[206:207], 0, s[18:19]
	s_mov_b32 m0, s38
	ds_read_b128 v[160:163], v248 offset:49152
	ds_read_b128 v[164:167], v248 offset:50176
	ds_read_b128 v[168:171], v248 offset:51200
	ds_read_b128 v[172:175], v248 offset:52224
	ds_read_b128 v[176:179], v248 offset:53248
	ds_read_b128 v[180:183], v248 offset:54272
	ds_read_b128 v[184:187], v248 offset:55296
	ds_read_b128 v[188:191], v248 offset:56320
	global_load_lds_dwordx4 v[206:207], off
	s_add_i32 m0, s38, 0x2000
	s_add_u32 s36, s36, 0xb0080
	v_lshl_add_u64 v[206:207], v[208:209], 0, s[18:19]
	s_addc_u32 s37, s37, 0
	s_add_i32 s38, s66, s44
	global_load_lds_dwordx4 v[206:207], off
	v_lshl_add_u64 v[206:207], s[36:37], 0, v[194:195]
	s_mov_b32 m0, s38
	s_nop 0
	global_load_lds_dwordx4 v[206:207], off
	v_lshl_add_u64 v[206:207], s[36:37], 0, v[198:199]
	s_add_i32 m0, s38, 0x2000
	s_nop 0
	global_load_lds_dwordx4 v[206:207], off
	v_lshl_add_u64 v[206:207], v[210:211], 0, s[18:19]
	s_mov_b32 m0, s50
	s_nop 0
	global_load_lds_dwordx4 v[206:207], off
	v_lshl_add_u64 v[206:207], v[212:213], 0, s[18:19]
	s_mov_b32 m0, s51
	s_nop 0
	global_load_lds_dwordx4 v[206:207], off
	s_waitcnt vmcnt(8)
	s_waitcnt lgkmcnt(0)
	s_barrier
	s_setprio 1
	v_mfma_f32_16x16x32_bf16 v[60:63], v[112:115], v[160:163], v[60:63]
	v_mfma_f32_16x16x32_bf16 v[56:59], v[120:123], v[160:163], v[56:59]
	v_mfma_f32_16x16x32_bf16 v[44:47], v[112:115], v[168:171], v[44:47]
	v_mfma_f32_16x16x32_bf16 v[40:43], v[120:123], v[168:171], v[40:43]
	v_mfma_f32_16x16x32_bf16 v[28:31], v[112:115], v[176:179], v[28:31]
	v_mfma_f32_16x16x32_bf16 v[24:27], v[120:123], v[176:179], v[24:27]
	v_mfma_f32_16x16x32_bf16 v[12:15], v[112:115], v[184:187], v[12:15]
	v_mfma_f32_16x16x32_bf16 v[8:11], v[120:123], v[184:187], v[8:11]
	v_mfma_f32_16x16x32_bf16 v[60:63], v[116:119], v[164:167], v[60:63]
	v_mfma_f32_16x16x32_bf16 v[56:59], v[124:127], v[164:167], v[56:59]
	v_mfma_f32_16x16x32_bf16 v[44:47], v[116:119], v[172:175], v[44:47]
	v_mfma_f32_16x16x32_bf16 v[40:43], v[124:127], v[172:175], v[40:43]
	v_mfma_f32_16x16x32_bf16 v[28:31], v[116:119], v[180:183], v[28:31]
	v_mfma_f32_16x16x32_bf16 v[24:27], v[124:127], v[180:183], v[24:27]
	v_mfma_f32_16x16x32_bf16 v[12:15], v[116:119], v[188:191], v[12:15]
	v_mfma_f32_16x16x32_bf16 v[8:11], v[124:127], v[188:191], v[8:11]
	v_mfma_f32_16x16x32_bf16 v[52:55], v[136:139], v[160:163], v[52:55]
	v_mfma_f32_16x16x32_bf16 v[48:51], v[152:155], v[160:163], v[48:51]
	v_mfma_f32_16x16x32_bf16 v[36:39], v[136:139], v[168:171], v[36:39]
	v_mfma_f32_16x16x32_bf16 v[32:35], v[152:155], v[168:171], v[32:35]
	v_mfma_f32_16x16x32_bf16 v[20:23], v[136:139], v[176:179], v[20:23]
	v_mfma_f32_16x16x32_bf16 v[16:19], v[152:155], v[176:179], v[16:19]
	v_mfma_f32_16x16x32_bf16 v[4:7], v[136:139], v[184:187], v[4:7]
	v_mfma_f32_16x16x32_bf16 v[0:3], v[152:155], v[184:187], v[0:3]
	v_mfma_f32_16x16x32_bf16 v[52:55], v[140:143], v[164:167], v[52:55]
	v_mfma_f32_16x16x32_bf16 v[48:51], v[156:159], v[164:167], v[48:51]
	v_mfma_f32_16x16x32_bf16 v[36:39], v[140:143], v[172:175], v[36:39]
	v_mfma_f32_16x16x32_bf16 v[32:35], v[156:159], v[172:175], v[32:35]
	v_mfma_f32_16x16x32_bf16 v[20:23], v[140:143], v[180:183], v[20:23]
	v_mfma_f32_16x16x32_bf16 v[16:19], v[156:159], v[180:183], v[16:19]
	v_mfma_f32_16x16x32_bf16 v[4:7], v[140:143], v[188:191], v[4:7]
	v_mfma_f32_16x16x32_bf16 v[0:3], v[156:159], v[188:191], v[0:3]
	s_barrier
	s_setprio 0
	s_add_i32 s64, s64, 2
	s_add_u32 s34, s34, 0x100
	s_addc_u32 s35, s35, 0
	s_add_u32 s59, s59, 0x100
	s_addc_u32 s63, s63, 0

; #define PG8_STAGE(bufoff, gbase, voff) do { _Pragma("unroll") for (int _i = 0; _i < 2; ++_i) \
;         __builtin_amdgcn_global_load_lds((const unsigned*)((const char*)(gbase) + (voff)[_i]), (PG8_LAS unsigned*)(lds + (bufoff) + ldsw + _i * 8192), 16, 0, 0); } while (0)
; #define PG8_LDA(dst, b, h) do { _Pragma("unroll") for (int m = 0; m < 4; ++m) _Pragma("unroll") for (int k = 0; k < 2; ++k) dst[m][k] = *(const PG8_LAS bf16x8*)(lds + PG8_SA(b, h) + aoff + m * 2048 + k * 1024); } while (0)
; #define PG8_LDB(dst, b, h) do { _Pragma("unroll") for (int n = 0; n < 2; ++n) _Pragma("unroll") for (int k = 0; k < 2; ++k) dst[n][k] = *(const PG8_LAS bf16x8*)(lds + PG8_SB(b, h) + boff + n * 2048 + k * 1024); } while (0)
; #define PG8_WAIT_V(n) asm volatile("s_waitcnt vmcnt(" #n ")" ::: "memory")
; #define PG8_WAIT_L(n) asm volatile("s_waitcnt lgkmcnt(" #n ")" ::: "memory")
; template <class Epi, class Sched, bool ALIGN_EPI = false, bool SP2 = false>
; __device__ __forceinline__ void gemm_phase(PG8_LAS unsigned char* lds, const Gemm g, const Sched& S, const Epi& E) {
;     ...
;         const bool has_next = S.next(ui + 1, nxt);
;         const char* nA = has_next ? (const char*)g.A + (size_t)nxt.pm * tstep : cA; const char* nB = has_next ? (const char*)g.Bt + (size_t)nxt.pn * tstep : cB;
;         for (int t = 0; t < nt; t += 2) {
;             const bool last = (t == nt - 2);
;             if constexpr (Epi::PREFETCH) { if (t == nt - 4) E.prefetch(cur, lds + STAGE_BYTES + 1024, tid); }
;             const char* a1 = cA + (size_t)(t + 1) * kstep;
;             const char* a2 = last ? nA : cA + (size_t)(t + 2) * kstep; const char* b2 = last ? nB : cB + (size_t)(t + 2) * kstep;
;             const char* a3 = a2 + kstep; const char* b3 = b2 + kstep;
;             if (last && has_next) S.a_ready(nxt);
;             if constexpr (SP2) {
;             PG8_LDB(B0, 0, 0); PG8_LDB(B1, 0, 1); PG8_SCHED; PG8_LDA(At, 0, 0); PG8_STAGE(PG8_SA(1, 1), a1 + hstep, voffA);
;             PG8_WAIT_V(8); PG8_WAIT_L(0); PG8_BAR; PG8_MMA(0, 0, At, B0); PG8_MMA(0, 1, At, B1); PG8_BAR; PG8_SCHED;
;             PG8_LDA(At, 0, 1); PG8_STAGE(PG8_SB(0, 0), b2, voffB); PG8_STAGE(PG8_SB(0, 1), b2 + hstep, voffB); PG8_STAGE(PG8_SA(0, 0), a2, voffA);
;             PG8_WAIT_V(8); PG8_WAIT_L(0); PG8_BAR; PG8_MMA(1, 0, At, B0); PG8_MMA(1, 1, At, B1); PG8_BAR; PG8_SCHED;
.LBB0_592:
	s_ashr_i32 s37, s36, 31
	s_lshl_b64 s[38:39], s[36:37], 19
	s_add_u32 s38, s53, s38
	s_addc_u32 s39, s54, s39
	s_and_b64 s[40:41], s[4:5], exec
	s_cselect_b32 s37, s39, s45
	s_cselect_b32 s76, s38, s44
	s_ashr_i32 s35, s34, 31
	s_lshl_b64 s[40:41], s[34:35], 19
	s_add_u32 s40, s50, s40
	s_addc_u32 s41, s51, s41
	s_and_b64 s[48:49], s[4:5], exec
	s_cselect_b32 s35, s41, s47
	s_cselect_b32 s77, s40, s46
	s_add_u32 s44, s44, 0x40080
	s_addc_u32 s45, s45, 0
	s_add_u32 s78, s46, 0x100
	s_addc_u32 s79, s47, 0
	s_mov_b32 s80, -2
	ds_read_b128 v[144:147], v151
	ds_read_b128 v[156:159], v151 offset:1024
	ds_read_b128 v[160:163], v151 offset:2048
	ds_read_b128 v[164:167], v151 offset:3072
	ds_read_b128 v[168:171], v152
	ds_read_b128 v[172:175], v152 offset:1024
	ds_read_b128 v[176:179], v152 offset:2048
	ds_read_b128 v[180:183], v152 offset:3072
	s_add_u32 s46, s44, 0xfffc0080
	s_addc_u32 s47, s45, -1
	s_cmp_eq_u32 s80, 12
	s_cselect_b32 s49, s37, s47
	s_cselect_b32 s48, s76, s46
	s_cselect_b32 s47, s35, s79
	s_cselect_b32 s46, s77, s78
	v_lshl_add_u64 v[216:217], s[44:45], 0, v[136:137]
	s_add_i32 m0, s43, 0xc000
	ds_read_b128 v[184:187], v153
	ds_read_b128 v[188:191], v153 offset:1024
	ds_read_b128 v[192:195], v153 offset:2048
	ds_read_b128 v[196:199], v153 offset:3072
	ds_read_b128 v[200:203], v153 offset:4096
	ds_read_b128 v[204:207], v153 offset:5120
	ds_read_b128 v[208:211], v153 offset:6144
	ds_read_b128 v[212:215], v153 offset:7168
	global_load_lds_dwordx4 v[216:217], off
	v_lshl_add_u64 v[216:217], s[44:45], 0, v[138:139]
	s_add_i32 m0, s43, 0xe000
	s_nop 0
	global_load_lds_dwordx4 v[216:217], off
	s_waitcnt vmcnt(8)
	s_waitcnt lgkmcnt(0)
	s_barrier
	s_setprio 1
	v_mfma_f32_16x16x32_bf16 v[124:127], v[144:147], v[184:187], 0
	v_mfma_f32_16x16x32_bf16 v[120:123], v[160:163], v[184:187], 0
	v_mfma_f32_16x16x32_bf16 v[108:111], v[144:147], v[192:195], 0
	v_mfma_f32_16x16x32_bf16 v[104:107], v[160:163], v[192:195], 0
	v_mfma_f32_16x16x32_bf16 v[92:95], v[144:147], v[200:203], 0
	v_mfma_f32_16x16x32_bf16 v[88:91], v[160:163], v[200:203], 0
	v_mfma_f32_16x16x32_bf16 v[76:79], v[144:147], v[208:211], 0
	v_mfma_f32_16x16x32_bf16 v[72:75], v[160:163], v[208:211], 0
	v_mfma_f32_16x16x32_bf16 v[124:127], v[156:159], v[188:191], v[124:127]
	v_mfma_f32_16x16x32_bf16 v[120:123], v[164:167], v[188:191], v[120:123]
	v_mfma_f32_16x16x32_bf16 v[108:111], v[156:159], v[196:199], v[108:111]
	v_mfma_f32_16x16x32_bf16 v[104:107], v[164:167], v[196:199], v[104:107]
	v_mfma_f32_16x16x32_bf16 v[92:95], v[156:159], v[204:207], v[92:95]
	v_mfma_f32_16x16x32_bf16 v[88:91], v[164:167], v[204:207], v[88:91]
	v_mfma_f32_16x16x32_bf16 v[76:79], v[156:159], v[212:215], v[76:79]
	v_mfma_f32_16x16x32_bf16 v[72:75], v[164:167], v[212:215], v[72:75]
	v_mfma_f32_16x16x32_bf16 v[116:119], v[168:171], v[184:187], 0
	v_mfma_f32_16x16x32_bf16 v[112:115], v[176:179], v[184:187], 0
	v_mfma_f32_16x16x32_bf16 v[100:103], v[168:171], v[192:195], 0
	v_mfma_f32_16x16x32_bf16 v[96:99], v[176:179], v[192:195], 0
	v_mfma_f32_16x16x32_bf16 v[84:87], v[168:171], v[200:203], 0
	v_mfma_f32_16x16x32_bf16 v[80:83], v[176:179], v[200:203], 0
	v_mfma_f32_16x16x32_bf16 v[68:71], v[168:171], v[208:211], 0
	v_mfma_f32_16x16x32_bf16 v[64:67], v[176:179], v[208:211], 0
	v_mfma_f32_16x16x32_bf16 v[116:119], v[172:175], v[188:191], v[116:119]
	v_mfma_f32_16x16x32_bf16 v[112:115], v[180:183], v[188:191], v[112:115]
	v_mfma_f32_16x16x32_bf16 v[100:103], v[172:175], v[196:199], v[100:103]
	v_mfma_f32_16x16x32_bf16 v[96:99], v[180:183], v[196:199], v[96:99]
	v_mfma_f32_16x16x32_bf16 v[84:87], v[172:175], v[204:207], v[84:87]
	v_mfma_f32_16x16x32_bf16 v[80:83], v[180:183], v[204:207], v[80:83]
	v_mfma_f32_16x16x32_bf16 v[68:71], v[172:175], v[212:215], v[68:71]
	v_mfma_f32_16x16x32_bf16 v[64:67], v[180:183], v[212:215], v[64:67]
	s_barrier
	s_setprio 0
	s_add_i32 s81, s69, s52
	v_lshl_add_u64 v[216:217], s[46:47], 0, v[132:133]
	s_mov_b32 m0, s81
	ds_read_b128 v[184:187], v153 offset:16384
	ds_read_b128 v[188:191], v153 offset:17408
	ds_read_b128 v[192:195], v153 offset:18432
	ds_read_b128 v[196:199], v153 offset:19456
	ds_read_b128 v[200:203], v153 offset:20480
	ds_read_b128 v[204:207], v153 offset:21504
	ds_read_b128 v[208:211], v153 offset:22528
	ds_read_b128 v[212:215], v153 offset:23552
	global_load_lds_dwordx4 v[216:217], off
	s_add_i32 m0, s81, 0x2000
	s_add_u32 s82, s46, 0x40000
	v_lshl_add_u64 v[218:219], s[46:47], 0, v[128:129]
	s_addc_u32 s83, s47, 0
	s_add_i32 s81, s70, s52
	global_load_lds_dwordx4 v[218:219], off
	v_lshl_add_u64 v[220:221], s[82:83], 0, v[132:133]
	s_mov_b32 m0, s81
	v_lshl_add_u64 v[222:223], s[48:49], 0, v[130:131]
	global_load_lds_dwordx4 v[220:221], off
	v_lshl_add_u64 v[220:221], s[82:83], 0, v[128:129]
	s_add_i32 m0, s81, 0x2000
	s_nop 0
	global_load_lds_dwordx4 v[220:221], off
	v_lshl_add_u64 v[220:221], s[48:49], 0, v[134:135]
	s_mov_b32 m0, s43
	s_nop 0
	global_load_lds_dwordx4 v[220:221], off
	s_mov_b32 m0, s56
	s_nop 0
	global_load_lds_dwordx4 v[222:223], off
	s_waitcnt vmcnt(8)
	s_waitcnt lgkmcnt(0)
	s_barrier
; #define PG8_STAGE(bufoff, gbase, voff) do { _Pragma("unroll") for (int _i = 0; _i < 2; ++_i) \
;         __builtin_amdgcn_global_load_lds((const unsigned*)((const char*)(gbase) + (voff)[_i]), (PG8_LAS unsigned*)(lds + (bufoff) + ldsw + _i * 8192), 16, 0, 0); } while (0)
; #define PG8_LDA(dst, b, h) do { _Pragma("unroll") for (int m = 0; m < 4; ++m) _Pragma("unroll") for (int k = 0; k < 2; ++k) dst[m][k] = *(const PG8_LAS bf16x8*)(lds + PG8_SA(b, h) + aoff + m * 2048 + k * 1024); } while (0)
; #define PG8_LDB(dst, b, h) do { _Pragma("unroll") for (int n = 0; n < 2; ++n) _Pragma("unroll") for (int k = 0; k < 2; ++k) dst[n][k] = *(const PG8_LAS bf16x8*)(lds + PG8_SB(b, h) + boff + n * 2048 + k * 1024); } while (0)
; #define PG8_MMA(ai, bj, At, Bt) do { __builtin_amdgcn_s_setprio(1); _Pragma("unroll") for (int m = 0; m < 4; ++m) _Pragma("unroll") for (int n = 0; n < 2; ++n) _Pragma("unroll") for (int k = 0; k < 2; ++k) \
;         acc[ai][bj][m][n] = __builtin_amdgcn_mfma_f32_16x16x32_bf16(Bt[n][k], At[m][k], acc[ai][bj][m][n], 0, 0, 0); __builtin_amdgcn_s_setprio(0); } while (0)
; #define PG8_WAIT_V(n) asm volatile("s_waitcnt vmcnt(" #n ")" ::: "memory")
; #define PG8_WAIT_L(n) asm volatile("s_waitcnt lgkmcnt(" #n ")" ::: "memory")
; #define PG8_BAR __builtin_amdgcn_s_barrier()
; #define PG8_SCHED __builtin_amdgcn_sched_barrier(0)
; template <class Epi, class Sched, bool ALIGN_EPI = false, bool SP2 = false>
; __device__ __forceinline__ void gemm_phase(PG8_LAS unsigned char* lds, const Gemm g, const Sched& S, const Epi& E) {
;     ...
;             PG8_WAIT_V(8); PG8_WAIT_L(0); PG8_BAR; PG8_MMA(1, 0, At, B0); PG8_MMA(1, 1, At, B1); PG8_BAR; PG8_SCHED;
;             PG8_LDB(B0, 1, 0); PG8_LDB(B1, 1, 1); PG8_SCHED; PG8_LDA(At, 1, 0); PG8_STAGE(PG8_SA(0, 1), a2 + hstep, voffA);
;             PG8_WAIT_V(8); PG8_WAIT_L(0); PG8_BAR; PG8_MMA(0, 0, At, B0); PG8_MMA(0, 1, At, B1); PG8_BAR; PG8_SCHED;
	s_setprio 1
	v_mfma_f32_16x16x32_bf16 v[60:63], v[144:147], v[184:187], 0
	v_mfma_f32_16x16x32_bf16 v[56:59], v[160:163], v[184:187], 0
	v_mfma_f32_16x16x32_bf16 v[44:47], v[144:147], v[192:195], 0
	v_mfma_f32_16x16x32_bf16 v[40:43], v[160:163], v[192:195], 0
	v_mfma_f32_16x16x32_bf16 v[28:31], v[144:147], v[200:203], 0
	v_mfma_f32_16x16x32_bf16 v[24:27], v[160:163], v[200:203], 0
	v_mfma_f32_16x16x32_bf16 v[12:15], v[144:147], v[208:211], 0
	v_mfma_f32_16x16x32_bf16 v[8:11], v[160:163], v[208:211], 0
	v_mfma_f32_16x16x32_bf16 v[60:63], v[156:159], v[188:191], v[60:63]
	v_mfma_f32_16x16x32_bf16 v[56:59], v[164:167], v[188:191], v[56:59]
	v_mfma_f32_16x16x32_bf16 v[44:47], v[156:159], v[196:199], v[44:47]
	v_mfma_f32_16x16x32_bf16 v[40:43], v[164:167], v[196:199], v[40:43]
	v_mfma_f32_16x16x32_bf16 v[28:31], v[156:159], v[204:207], v[28:31]
	v_mfma_f32_16x16x32_bf16 v[24:27], v[164:167], v[204:207], v[24:27]
	v_mfma_f32_16x16x32_bf16 v[12:15], v[156:159], v[212:215], v[12:15]
	v_mfma_f32_16x16x32_bf16 v[8:11], v[164:167], v[212:215], v[8:11]
	v_mfma_f32_16x16x32_bf16 v[52:55], v[168:171], v[184:187], 0
	v_mfma_f32_16x16x32_bf16 v[48:51], v[176:179], v[184:187], 0
	v_mfma_f32_16x16x32_bf16 v[36:39], v[168:171], v[192:195], 0
	v_mfma_f32_16x16x32_bf16 v[32:35], v[176:179], v[192:195], 0
	v_mfma_f32_16x16x32_bf16 v[20:23], v[168:171], v[200:203], 0
	v_mfma_f32_16x16x32_bf16 v[16:19], v[176:179], v[200:203], 0
	v_mfma_f32_16x16x32_bf16 v[4:7], v[168:171], v[208:211], 0
	v_mfma_f32_16x16x32_bf16 v[0:3], v[176:179], v[208:211], 0
	v_mfma_f32_16x16x32_bf16 v[52:55], v[172:175], v[188:191], v[52:55]
	v_mfma_f32_16x16x32_bf16 v[48:51], v[180:183], v[188:191], v[48:51]
	v_mfma_f32_16x16x32_bf16 v[36:39], v[172:175], v[196:199], v[36:39]
	v_mfma_f32_16x16x32_bf16 v[32:35], v[180:183], v[196:199], v[32:35]
	v_mfma_f32_16x16x32_bf16 v[20:23], v[172:175], v[204:207], v[20:23]
	v_mfma_f32_16x16x32_bf16 v[16:19], v[180:183], v[204:207], v[16:19]
	v_mfma_f32_16x16x32_bf16 v[4:7], v[172:175], v[212:215], v[4:7]
	v_mfma_f32_16x16x32_bf16 v[0:3], v[180:183], v[212:215], v[0:3]
	s_barrier
	s_setprio 0
	s_add_i32 s81, 0, 0x18000
	s_add_i32 s82, 0, 0x1c000
	v_add_u32_e32 v164, s81, v149
	v_add_u32_e32 v180, s82, v149
	ds_read_b128 v[144:147], v164
	ds_read_b128 v[156:159], v164 offset:1024
	ds_read_b128 v[160:163], v164 offset:2048
	ds_read_b128 v[164:167], v164 offset:3072
	ds_read_b128 v[168:171], v180
	ds_read_b128 v[172:175], v180 offset:1024
	ds_read_b128 v[176:179], v180 offset:2048
	ds_read_b128 v[180:183], v180 offset:3072
	s_add_u32 s48, s48, 0x40000
	s_addc_u32 s49, s49, 0
	s_mov_b32 m0, s57
	v_lshl_add_u64 v[224:225], s[48:49], 0, v[134:135]
	ds_read_b128 v[184:187], v153 offset:32768
	ds_read_b128 v[188:191], v153 offset:33792
	ds_read_b128 v[192:195], v153 offset:34816
	ds_read_b128 v[196:199], v153 offset:35840
	ds_read_b128 v[200:203], v153 offset:36864
	ds_read_b128 v[204:207], v153 offset:37888
	ds_read_b128 v[208:211], v153 offset:38912
	ds_read_b128 v[212:215], v153 offset:39936
	global_load_lds_dwordx4 v[224:225], off
	v_lshl_add_u64 v[224:225], s[48:49], 0, v[130:131]
	s_mov_b32 m0, s58
	s_nop 0
	global_load_lds_dwordx4 v[224:225], off
	s_waitcnt vmcnt(8)
	s_waitcnt lgkmcnt(0)
	s_barrier
	s_setprio 1
	v_mfma_f32_16x16x32_bf16 v[124:127], v[144:147], v[184:187], v[124:127]
	v_mfma_f32_16x16x32_bf16 v[120:123], v[160:163], v[184:187], v[120:123]
	v_mfma_f32_16x16x32_bf16 v[108:111], v[144:147], v[192:195], v[108:111]
	v_mfma_f32_16x16x32_bf16 v[104:107], v[160:163], v[192:195], v[104:107]
	v_mfma_f32_16x16x32_bf16 v[92:95], v[144:147], v[200:203], v[92:95]
	v_mfma_f32_16x16x32_bf16 v[88:91], v[160:163], v[200:203], v[88:91]
	v_mfma_f32_16x16x32_bf16 v[76:79], v[144:147], v[208:211], v[76:79]
	v_mfma_f32_16x16x32_bf16 v[72:75], v[160:163], v[208:211], v[72:75]
	v_mfma_f32_16x16x32_bf16 v[124:127], v[156:159], v[188:191], v[124:127]
	v_mfma_f32_16x16x32_bf16 v[120:123], v[164:167], v[188:191], v[120:123]
	v_mfma_f32_16x16x32_bf16 v[108:111], v[156:159], v[196:199], v[108:111]
	v_mfma_f32_16x16x32_bf16 v[104:107], v[164:167], v[196:199], v[104:107]
	v_mfma_f32_16x16x32_bf16 v[92:95], v[156:159], v[204:207], v[92:95]
	v_mfma_f32_16x16x32_bf16 v[88:91], v[164:167], v[204:207], v[88:91]
	v_mfma_f32_16x16x32_bf16 v[76:79], v[156:159], v[212:215], v[76:79]
	v_mfma_f32_16x16x32_bf16 v[72:75], v[164:167], v[212:215], v[72:75]
	v_mfma_f32_16x16x32_bf16 v[116:119], v[168:171], v[184:187], v[116:119]
	v_mfma_f32_16x16x32_bf16 v[112:115], v[176:179], v[184:187], v[112:115]
	v_mfma_f32_16x16x32_bf16 v[100:103], v[168:171], v[192:195], v[100:103]
	v_mfma_f32_16x16x32_bf16 v[96:99], v[176:179], v[192:195], v[96:99]
	v_mfma_f32_16x16x32_bf16 v[84:87], v[168:171], v[200:203], v[84:87]
	v_mfma_f32_16x16x32_bf16 v[80:83], v[176:179], v[200:203], v[80:83]
	v_mfma_f32_16x16x32_bf16 v[68:71], v[168:171], v[208:211], v[68:71]
	v_mfma_f32_16x16x32_bf16 v[64:67], v[176:179], v[208:211], v[64:67]
	v_mfma_f32_16x16x32_bf16 v[116:119], v[172:175], v[188:191], v[116:119]
	v_mfma_f32_16x16x32_bf16 v[112:115], v[180:183], v[188:191], v[112:115]
	v_mfma_f32_16x16x32_bf16 v[100:103], v[172:175], v[196:199], v[100:103]
	v_mfma_f32_16x16x32_bf16 v[96:99], v[180:183], v[196:199], v[96:99]
	v_mfma_f32_16x16x32_bf16 v[84:87], v[172:175], v[204:207], v[84:87]
	v_mfma_f32_16x16x32_bf16 v[80:83], v[180:183], v[204:207], v[80:83]
	v_mfma_f32_16x16x32_bf16 v[68:71], v[172:175], v[212:215], v[68:71]
	v_mfma_f32_16x16x32_bf16 v[64:67], v[180:183], v[212:215], v[64:67]
	s_barrier
; #define PG8_STAGE(bufoff, gbase, voff) do { _Pragma("unroll") for (int _i = 0; _i < 2; ++_i) \
;         __builtin_amdgcn_global_load_lds((const unsigned*)((const char*)(gbase) + (voff)[_i]), (PG8_LAS unsigned*)(lds + (bufoff) + ldsw + _i * 8192), 16, 0, 0); } while (0)
; #define PG8_LDA(dst, b, h) do { _Pragma("unroll") for (int m = 0; m < 4; ++m) _Pragma("unroll") for (int k = 0; k < 2; ++k) dst[m][k] = *(const PG8_LAS bf16x8*)(lds + PG8_SA(b, h) + aoff + m * 2048 + k * 1024); } while (0)
; #define PG8_MMA(ai, bj, At, Bt) do { __builtin_amdgcn_s_setprio(1); _Pragma("unroll") for (int m = 0; m < 4; ++m) _Pragma("unroll") for (int n = 0; n < 2; ++n) _Pragma("unroll") for (int k = 0; k < 2; ++k) \
;         acc[ai][bj][m][n] = __builtin_amdgcn_mfma_f32_16x16x32_bf16(Bt[n][k], At[m][k], acc[ai][bj][m][n], 0, 0, 0); __builtin_amdgcn_s_setprio(0); } while (0)
; #define PG8_WAIT_V(n) asm volatile("s_waitcnt vmcnt(" #n ")" ::: "memory")
; #define PG8_WAIT_L(n) asm volatile("s_waitcnt lgkmcnt(" #n ")" ::: "memory")
; #define PG8_BAR __builtin_amdgcn_s_barrier()
; #define PG8_SCHED __builtin_amdgcn_sched_barrier(0)
; template <class Epi, class Sched, bool ALIGN_EPI = false, bool SP2 = false>
; __device__ __forceinline__ void gemm_phase(PG8_LAS unsigned char* lds, const Gemm g, const Sched& S, const Epi& E) {
;     ...
;         for (int t = 0; t < nt; t += 2) {
;             const bool last = (t == nt - 2);
;             if constexpr (Epi::PREFETCH) { if (t == nt - 4) E.prefetch(cur, lds + STAGE_BYTES + 1024, tid); }
;             const char* a1 = cA + (size_t)(t + 1) * kstep;
;             const char* a2 = last ? nA : cA + (size_t)(t + 2) * kstep; const char* b2 = last ? nB : cB + (size_t)(t + 2) * kstep;
;             const char* a3 = a2 + kstep; const char* b3 = b2 + kstep;
;     ...
;             PG8_LDA(At, 1, 1); PG8_STAGE(PG8_SB(1, 0), b3, voffB); PG8_STAGE(PG8_SB(1, 1), b3 + hstep, voffB); PG8_STAGE(PG8_SA(1, 0), a3, voffA);
;             PG8_WAIT_V(8); PG8_WAIT_L(0); PG8_BAR; PG8_MMA(1, 0, At, B0); PG8_MMA(1, 1, At, B1); PG8_BAR; PG8_SCHED;
	s_setprio 0
	s_add_i32 s48, s81, s52
	v_lshl_add_u64 v[216:217], v[216:217], 0, s[14:15]
	s_mov_b32 m0, s48
	ds_read_b128 v[184:187], v153 offset:49152
	ds_read_b128 v[188:191], v153 offset:50176
	ds_read_b128 v[192:195], v153 offset:51200
	ds_read_b128 v[196:199], v153 offset:52224
	ds_read_b128 v[200:203], v153 offset:53248
	ds_read_b128 v[204:207], v153 offset:54272
	ds_read_b128 v[208:211], v153 offset:55296
	ds_read_b128 v[212:215], v153 offset:56320
	global_load_lds_dwordx4 v[216:217], off
	s_add_i32 m0, s48, 0x2000
	s_add_u32 s46, s46, 0x40080
	v_lshl_add_u64 v[216:217], v[218:219], 0, s[14:15]
	s_addc_u32 s47, s47, 0
	s_add_i32 s48, s82, s52
	global_load_lds_dwordx4 v[216:217], off
	v_lshl_add_u64 v[216:217], s[46:47], 0, v[132:133]
	s_mov_b32 m0, s48
	s_nop 0
	global_load_lds_dwordx4 v[216:217], off
	v_lshl_add_u64 v[216:217], s[46:47], 0, v[128:129]
	s_add_i32 m0, s48, 0x2000
	s_nop 0
	global_load_lds_dwordx4 v[216:217], off
	v_lshl_add_u64 v[216:217], v[220:221], 0, s[14:15]
	s_mov_b32 m0, s65
	s_nop 0
	global_load_lds_dwordx4 v[216:217], off
	v_lshl_add_u64 v[216:217], v[222:223], 0, s[14:15]
	s_mov_b32 m0, s66
	s_nop 0
	global_load_lds_dwordx4 v[216:217], off
	s_waitcnt vmcnt(8)
	s_waitcnt lgkmcnt(0)
	s_barrier
	s_setprio 1
	v_mfma_f32_16x16x32_bf16 v[60:63], v[144:147], v[184:187], v[60:63]
	v_mfma_f32_16x16x32_bf16 v[56:59], v[160:163], v[184:187], v[56:59]
	v_mfma_f32_16x16x32_bf16 v[44:47], v[144:147], v[192:195], v[44:47]
	v_mfma_f32_16x16x32_bf16 v[40:43], v[160:163], v[192:195], v[40:43]
	v_mfma_f32_16x16x32_bf16 v[28:31], v[144:147], v[200:203], v[28:31]
	v_mfma_f32_16x16x32_bf16 v[24:27], v[160:163], v[200:203], v[24:27]
	v_mfma_f32_16x16x32_bf16 v[12:15], v[144:147], v[208:211], v[12:15]
	v_mfma_f32_16x16x32_bf16 v[8:11], v[160:163], v[208:211], v[8:11]
	v_mfma_f32_16x16x32_bf16 v[60:63], v[156:159], v[188:191], v[60:63]
	v_mfma_f32_16x16x32_bf16 v[56:59], v[164:167], v[188:191], v[56:59]
	v_mfma_f32_16x16x32_bf16 v[44:47], v[156:159], v[196:199], v[44:47]
	v_mfma_f32_16x16x32_bf16 v[40:43], v[164:167], v[196:199], v[40:43]
	v_mfma_f32_16x16x32_bf16 v[28:31], v[156:159], v[204:207], v[28:31]
	v_mfma_f32_16x16x32_bf16 v[24:27], v[164:167], v[204:207], v[24:27]
	v_mfma_f32_16x16x32_bf16 v[12:15], v[156:159], v[212:215], v[12:15]
	v_mfma_f32_16x16x32_bf16 v[8:11], v[164:167], v[212:215], v[8:11]
	v_mfma_f32_16x16x32_bf16 v[52:55], v[168:171], v[184:187], v[52:55]
	v_mfma_f32_16x16x32_bf16 v[48:51], v[176:179], v[184:187], v[48:51]
	v_mfma_f32_16x16x32_bf16 v[36:39], v[168:171], v[192:195], v[36:39]
	v_mfma_f32_16x16x32_bf16 v[32:35], v[176:179], v[192:195], v[32:35]
	v_mfma_f32_16x16x32_bf16 v[20:23], v[168:171], v[200:203], v[20:23]
	v_mfma_f32_16x16x32_bf16 v[16:19], v[176:179], v[200:203], v[16:19]
	v_mfma_f32_16x16x32_bf16 v[4:7], v[168:171], v[208:211], v[4:7]
	v_mfma_f32_16x16x32_bf16 v[0:3], v[176:179], v[208:211], v[0:3]
	v_mfma_f32_16x16x32_bf16 v[52:55], v[172:175], v[188:191], v[52:55]
	v_mfma_f32_16x16x32_bf16 v[48:51], v[180:183], v[188:191], v[48:51]
	v_mfma_f32_16x16x32_bf16 v[36:39], v[172:175], v[196:199], v[36:39]
	v_mfma_f32_16x16x32_bf16 v[32:35], v[180:183], v[196:199], v[32:35]
	v_mfma_f32_16x16x32_bf16 v[20:23], v[172:175], v[204:207], v[20:23]
	v_mfma_f32_16x16x32_bf16 v[16:19], v[180:183], v[204:207], v[16:19]
	v_mfma_f32_16x16x32_bf16 v[4:7], v[172:175], v[212:215], v[4:7]
	v_mfma_f32_16x16x32_bf16 v[0:3], v[180:183], v[212:215], v[0:3]
	s_barrier
	s_setprio 0
	s_add_i32 s80, s80, 2
	s_add_u32 s44, s44, 0x100
	s_addc_u32 s45, s45, 0
	s_add_u32 s78, s78, 0x100
	s_addc_u32 s79, s79, 0

; #define PG8_STAGE(bufoff, gbase, voff) do { _Pragma("unroll") for (int _i = 0; _i < 2; ++_i) \
;         __builtin_amdgcn_global_load_lds((const unsigned*)((const char*)(gbase) + (voff)[_i]), (PG8_LAS unsigned*)(lds + (bufoff) + ldsw + _i * 8192), 16, 0, 0); } while (0)
; #define PG8_LDA(dst, b, h) do { _Pragma("unroll") for (int m = 0; m < 4; ++m) _Pragma("unroll") for (int k = 0; k < 2; ++k) dst[m][k] = *(const PG8_LAS bf16x8*)(lds + PG8_SA(b, h) + aoff + m * 2048 + k * 1024); } while (0)
; #define PG8_LDB(dst, b, h) do { _Pragma("unroll") for (int n = 0; n < 2; ++n) _Pragma("unroll") for (int k = 0; k < 2; ++k) dst[n][k] = *(const PG8_LAS bf16x8*)(lds + PG8_SB(b, h) + boff + n * 2048 + k * 1024); } while (0)
; #define PG8_WAIT_V(n) asm volatile("s_waitcnt vmcnt(" #n ")" ::: "memory")
; #define PG8_WAIT_L(n) asm volatile("s_waitcnt lgkmcnt(" #n ")" ::: "memory")
; #define PG8_BAR __builtin_amdgcn_s_barrier()
; #define PG8_SCHED __builtin_amdgcn_sched_barrier(0)
; template <class Epi, class Sched, bool ALIGN_EPI = false, bool SP2 = false>
; __device__ __forceinline__ void gemm_phase(PG8_LAS unsigned char* lds, const Gemm g, const Sched& S, const Epi& E) {
;     ...
;         const bool has_next = S.next(ui + 1, nxt);
;         const char* nA = has_next ? (const char*)g.A + (size_t)nxt.pm * tstep : cA; const char* nB = has_next ? (const char*)g.Bt + (size_t)nxt.pn * tstep : cB;
;         for (int t = 0; t < nt; t += 2) {
;             const bool last = (t == nt - 2);
;             if constexpr (Epi::PREFETCH) { if (t == nt - 4) E.prefetch(cur, lds + STAGE_BYTES + 1024, tid); }
;             const char* a1 = cA + (size_t)(t + 1) * kstep;
;             const char* a2 = last ? nA : cA + (size_t)(t + 2) * kstep; const char* b2 = last ? nB : cB + (size_t)(t + 2) * kstep;
;             const char* a3 = a2 + kstep; const char* b3 = b2 + kstep;
;             if (last && has_next) S.a_ready(nxt);
;             if constexpr (SP2) {
;             PG8_LDB(B0, 0, 0); PG8_LDB(B1, 0, 1); PG8_SCHED; PG8_LDA(At, 0, 0); PG8_STAGE(PG8_SA(1, 1), a1 + hstep, voffA);
;             PG8_WAIT_V(8); PG8_WAIT_L(0); PG8_BAR; PG8_MMA(0, 0, At, B0); PG8_MMA(0, 1, At, B1); PG8_BAR; PG8_SCHED;
;             PG8_LDA(At, 0, 1); PG8_STAGE(PG8_SB(0, 0), b2, voffB); PG8_STAGE(PG8_SB(0, 1), b2 + hstep, voffB); PG8_STAGE(PG8_SA(0, 0), a2, voffA);
.LBB0_1011:
	s_ashr_i32 s23, s22, 31
	s_lshl_b64 s[34:35], s[22:23], 19
	s_add_u32 s34, s48, s34
	s_addc_u32 s35, s49, s35
	s_and_b64 s[36:37], s[6:7], exec
	s_cselect_b32 s23, s35, s43
	s_cselect_b32 s39, s34, s42
	s_ashr_i32 s21, s20, 31
	s_lshl_b64 s[36:37], s[20:21], 19
	s_add_u32 s36, s50, s36
	s_addc_u32 s37, s51, s37
	s_and_b64 s[46:47], s[6:7], exec
	s_cselect_b32 s21, s37, s45
	s_cselect_b32 s65, s36, s44
	s_add_u32 s42, s42, 0x40080
	s_addc_u32 s43, s43, 0
	s_add_u32 s66, s44, 0x100
	s_addc_u32 s67, s45, 0
	s_mov_b32 s68, -2
	ds_read_b128 v[112:115], v246
	ds_read_b128 v[116:119], v246 offset:1024
	ds_read_b128 v[120:123], v246 offset:2048
	ds_read_b128 v[124:127], v246 offset:3072
	ds_read_b128 v[136:139], v247
	ds_read_b128 v[140:143], v247 offset:1024
	ds_read_b128 v[152:155], v247 offset:2048
	ds_read_b128 v[156:159], v247 offset:3072
	s_add_u32 s44, s42, 0xfffc0080
	s_addc_u32 s45, s43, -1
	s_cmp_eq_u32 s68, 12
	s_cselect_b32 s47, s23, s45
	s_cselect_b32 s46, s39, s44
	s_cselect_b32 s45, s21, s67
	s_cselect_b32 s44, s65, s66
	v_lshl_add_u64 v[206:207], s[42:43], 0, v[200:201]
	s_add_i32 m0, s41, 0xc000
	ds_read_b128 v[160:163], v248
	ds_read_b128 v[164:167], v248 offset:1024
	ds_read_b128 v[168:171], v248 offset:2048
	ds_read_b128 v[172:175], v248 offset:3072
	ds_read_b128 v[176:179], v248 offset:4096
	ds_read_b128 v[180:183], v248 offset:5120
	ds_read_b128 v[184:187], v248 offset:6144
	ds_read_b128 v[188:191], v248 offset:7168
	global_load_lds_dwordx4 v[206:207], off
	v_lshl_add_u64 v[206:207], s[42:43], 0, v[202:203]
	s_add_i32 m0, s41, 0xe000
	s_nop 0
	global_load_lds_dwordx4 v[206:207], off
	s_waitcnt vmcnt(8)
	s_waitcnt lgkmcnt(0)
	s_barrier
	s_setprio 1
	v_mfma_f32_16x16x32_bf16 v[148:151], v[112:115], v[160:163], 0
	v_mfma_f32_16x16x32_bf16 v[144:147], v[120:123], v[160:163], 0
	v_mfma_f32_16x16x32_bf16 v[108:111], v[112:115], v[168:171], 0
	v_mfma_f32_16x16x32_bf16 v[104:107], v[120:123], v[168:171], 0
	v_mfma_f32_16x16x32_bf16 v[92:95], v[112:115], v[176:179], 0
	v_mfma_f32_16x16x32_bf16 v[88:91], v[120:123], v[176:179], 0
	v_mfma_f32_16x16x32_bf16 v[76:79], v[112:115], v[184:187], 0
	v_mfma_f32_16x16x32_bf16 v[72:75], v[120:123], v[184:187], 0
	v_mfma_f32_16x16x32_bf16 v[148:151], v[116:119], v[164:167], v[148:151]
	v_mfma_f32_16x16x32_bf16 v[144:147], v[124:127], v[164:167], v[144:147]
	v_mfma_f32_16x16x32_bf16 v[108:111], v[116:119], v[172:175], v[108:111]
	v_mfma_f32_16x16x32_bf16 v[104:107], v[124:127], v[172:175], v[104:107]
	v_mfma_f32_16x16x32_bf16 v[92:95], v[116:119], v[180:183], v[92:95]
	v_mfma_f32_16x16x32_bf16 v[88:91], v[124:127], v[180:183], v[88:91]
	v_mfma_f32_16x16x32_bf16 v[76:79], v[116:119], v[188:191], v[76:79]
	v_mfma_f32_16x16x32_bf16 v[72:75], v[124:127], v[188:191], v[72:75]
	v_mfma_f32_16x16x32_bf16 v[132:135], v[136:139], v[160:163], 0
	v_mfma_f32_16x16x32_bf16 v[128:131], v[152:155], v[160:163], 0
	v_mfma_f32_16x16x32_bf16 v[100:103], v[136:139], v[168:171], 0
	v_mfma_f32_16x16x32_bf16 v[96:99], v[152:155], v[168:171], 0
	v_mfma_f32_16x16x32_bf16 v[84:87], v[136:139], v[176:179], 0
	v_mfma_f32_16x16x32_bf16 v[80:83], v[152:155], v[176:179], 0
	v_mfma_f32_16x16x32_bf16 v[68:71], v[136:139], v[184:187], 0
	v_mfma_f32_16x16x32_bf16 v[64:67], v[152:155], v[184:187], 0
	v_mfma_f32_16x16x32_bf16 v[132:135], v[140:143], v[164:167], v[132:135]
	v_mfma_f32_16x16x32_bf16 v[128:131], v[156:159], v[164:167], v[128:131]
	v_mfma_f32_16x16x32_bf16 v[100:103], v[140:143], v[172:175], v[100:103]
	v_mfma_f32_16x16x32_bf16 v[96:99], v[156:159], v[172:175], v[96:99]
	v_mfma_f32_16x16x32_bf16 v[84:87], v[140:143], v[180:183], v[84:87]
	v_mfma_f32_16x16x32_bf16 v[80:83], v[156:159], v[180:183], v[80:83]
	v_mfma_f32_16x16x32_bf16 v[68:71], v[140:143], v[188:191], v[68:71]
	v_mfma_f32_16x16x32_bf16 v[64:67], v[156:159], v[188:191], v[64:67]
	s_barrier
	s_setprio 0
	s_add_i32 s69, s63, s52
	v_lshl_add_u64 v[206:207], s[44:45], 0, v[194:195]
	s_mov_b32 m0, s69
	ds_read_b128 v[160:163], v248 offset:16384
	ds_read_b128 v[164:167], v248 offset:17408
	ds_read_b128 v[168:171], v248 offset:18432
	ds_read_b128 v[172:175], v248 offset:19456
	ds_read_b128 v[176:179], v248 offset:20480
	ds_read_b128 v[180:183], v248 offset:21504
	ds_read_b128 v[184:187], v248 offset:22528
	ds_read_b128 v[188:191], v248 offset:23552
	global_load_lds_dwordx4 v[206:207], off
	s_add_i32 m0, s69, 0x2000
	s_add_u32 s70, s44, 0x40000
	v_lshl_add_u64 v[208:209], s[44:45], 0, v[198:199]
	s_addc_u32 s71, s45, 0
	s_add_i32 s69, s64, s52
	global_load_lds_dwordx4 v[208:209], off
	v_lshl_add_u64 v[210:211], s[70:71], 0, v[194:195]
	s_mov_b32 m0, s69
	v_lshl_add_u64 v[212:213], s[46:47], 0, v[196:197]
	global_load_lds_dwordx4 v[210:211], off
	v_lshl_add_u64 v[210:211], s[70:71], 0, v[198:199]
	s_add_i32 m0, s69, 0x2000
	s_nop 0
	global_load_lds_dwordx4 v[210:211], off
	v_lshl_add_u64 v[210:211], s[46:47], 0, v[192:193]
	s_mov_b32 m0, s41
	s_nop 0
	global_load_lds_dwordx4 v[210:211], off
	s_mov_b32 m0, s53
	s_nop 0
	global_load_lds_dwordx4 v[212:213], off
	s_waitcnt vmcnt(8)
	s_waitcnt lgkmcnt(0)
	s_barrier
; #define PG8_STAGE(bufoff, gbase, voff) do { _Pragma("unroll") for (int _i = 0; _i < 2; ++_i) \
;         __builtin_amdgcn_global_load_lds((const unsigned*)((const char*)(gbase) + (voff)[_i]), (PG8_LAS unsigned*)(lds + (bufoff) + ldsw + _i * 8192), 16, 0, 0); } while (0)
; #define PG8_LDA(dst, b, h) do { _Pragma("unroll") for (int m = 0; m < 4; ++m) _Pragma("unroll") for (int k = 0; k < 2; ++k) dst[m][k] = *(const PG8_LAS bf16x8*)(lds + PG8_SA(b, h) + aoff + m * 2048 + k * 1024); } while (0)
; #define PG8_LDB(dst, b, h) do { _Pragma("unroll") for (int n = 0; n < 2; ++n) _Pragma("unroll") for (int k = 0; k < 2; ++k) dst[n][k] = *(const PG8_LAS bf16x8*)(lds + PG8_SB(b, h) + boff + n * 2048 + k * 1024); } while (0)
; #define PG8_MMA(ai, bj, At, Bt) do { __builtin_amdgcn_s_setprio(1); _Pragma("unroll") for (int m = 0; m < 4; ++m) _Pragma("unroll") for (int n = 0; n < 2; ++n) _Pragma("unroll") for (int k = 0; k < 2; ++k) \
;         acc[ai][bj][m][n] = __builtin_amdgcn_mfma_f32_16x16x32_bf16(Bt[n][k], At[m][k], acc[ai][bj][m][n], 0, 0, 0); __builtin_amdgcn_s_setprio(0); } while (0)
; #define PG8_WAIT_V(n) asm volatile("s_waitcnt vmcnt(" #n ")" ::: "memory")
; #define PG8_WAIT_L(n) asm volatile("s_waitcnt lgkmcnt(" #n ")" ::: "memory")
; #define PG8_BAR __builtin_amdgcn_s_barrier()
; #define PG8_SCHED __builtin_amdgcn_sched_barrier(0)
; template <class Epi, class Sched, bool ALIGN_EPI = false, bool SP2 = false>
; __device__ __forceinline__ void gemm_phase(PG8_LAS unsigned char* lds, const Gemm g, const Sched& S, const Epi& E) {
;     ...
;             PG8_WAIT_V(8); PG8_WAIT_L(0); PG8_BAR; PG8_MMA(1, 0, At, B0); PG8_MMA(1, 1, At, B1); PG8_BAR; PG8_SCHED;
;             PG8_LDB(B0, 1, 0); PG8_LDB(B1, 1, 1); PG8_SCHED; PG8_LDA(At, 1, 0); PG8_STAGE(PG8_SA(0, 1), a2 + hstep, voffA);
;             PG8_WAIT_V(8); PG8_WAIT_L(0); PG8_BAR; PG8_MMA(0, 0, At, B0); PG8_MMA(0, 1, At, B1); PG8_BAR; PG8_SCHED;
	s_setprio 1
	v_mfma_f32_16x16x32_bf16 v[60:63], v[112:115], v[160:163], 0
	v_mfma_f32_16x16x32_bf16 v[56:59], v[120:123], v[160:163], 0
	v_mfma_f32_16x16x32_bf16 v[44:47], v[112:115], v[168:171], 0
	v_mfma_f32_16x16x32_bf16 v[40:43], v[120:123], v[168:171], 0
	v_mfma_f32_16x16x32_bf16 v[28:31], v[112:115], v[176:179], 0
	v_mfma_f32_16x16x32_bf16 v[24:27], v[120:123], v[176:179], 0
	v_mfma_f32_16x16x32_bf16 v[12:15], v[112:115], v[184:187], 0
	v_mfma_f32_16x16x32_bf16 v[8:11], v[120:123], v[184:187], 0
	v_mfma_f32_16x16x32_bf16 v[60:63], v[116:119], v[164:167], v[60:63]
	v_mfma_f32_16x16x32_bf16 v[56:59], v[124:127], v[164:167], v[56:59]
	v_mfma_f32_16x16x32_bf16 v[44:47], v[116:119], v[172:175], v[44:47]
	v_mfma_f32_16x16x32_bf16 v[40:43], v[124:127], v[172:175], v[40:43]
	v_mfma_f32_16x16x32_bf16 v[28:31], v[116:119], v[180:183], v[28:31]
	v_mfma_f32_16x16x32_bf16 v[24:27], v[124:127], v[180:183], v[24:27]
	v_mfma_f32_16x16x32_bf16 v[12:15], v[116:119], v[188:191], v[12:15]
	v_mfma_f32_16x16x32_bf16 v[8:11], v[124:127], v[188:191], v[8:11]
	v_mfma_f32_16x16x32_bf16 v[52:55], v[136:139], v[160:163], 0
	v_mfma_f32_16x16x32_bf16 v[48:51], v[152:155], v[160:163], 0
	v_mfma_f32_16x16x32_bf16 v[36:39], v[136:139], v[168:171], 0
	v_mfma_f32_16x16x32_bf16 v[32:35], v[152:155], v[168:171], 0
	v_mfma_f32_16x16x32_bf16 v[20:23], v[136:139], v[176:179], 0
	v_mfma_f32_16x16x32_bf16 v[16:19], v[152:155], v[176:179], 0
	v_mfma_f32_16x16x32_bf16 v[4:7], v[136:139], v[184:187], 0
	v_mfma_f32_16x16x32_bf16 v[0:3], v[152:155], v[184:187], 0
	v_mfma_f32_16x16x32_bf16 v[52:55], v[140:143], v[164:167], v[52:55]
	v_mfma_f32_16x16x32_bf16 v[48:51], v[156:159], v[164:167], v[48:51]
	v_mfma_f32_16x16x32_bf16 v[36:39], v[140:143], v[172:175], v[36:39]
	v_mfma_f32_16x16x32_bf16 v[32:35], v[156:159], v[172:175], v[32:35]
	v_mfma_f32_16x16x32_bf16 v[20:23], v[140:143], v[180:183], v[20:23]
	v_mfma_f32_16x16x32_bf16 v[16:19], v[156:159], v[180:183], v[16:19]
	v_mfma_f32_16x16x32_bf16 v[4:7], v[140:143], v[188:191], v[4:7]
	v_mfma_f32_16x16x32_bf16 v[0:3], v[156:159], v[188:191], v[0:3]
	s_barrier
	s_setprio 0
	s_add_i32 s69, 0, 0x18000
	s_add_i32 s70, 0, 0x1c000
	v_add_u32_e32 v124, s69, v244
	v_add_u32_e32 v156, s70, v244
	ds_read_b128 v[112:115], v124
	ds_read_b128 v[116:119], v124 offset:1024
	ds_read_b128 v[120:123], v124 offset:2048
	ds_read_b128 v[124:127], v124 offset:3072
	ds_read_b128 v[136:139], v156
	ds_read_b128 v[140:143], v156 offset:1024
	ds_read_b128 v[152:155], v156 offset:2048
	ds_read_b128 v[156:159], v156 offset:3072
	s_add_u32 s46, s46, 0x40000
	s_addc_u32 s47, s47, 0
	s_mov_b32 m0, s54
	v_lshl_add_u64 v[214:215], s[46:47], 0, v[192:193]
	ds_read_b128 v[160:163], v248 offset:32768
	ds_read_b128 v[164:167], v248 offset:33792
	ds_read_b128 v[168:171], v248 offset:34816
	ds_read_b128 v[172:175], v248 offset:35840
	ds_read_b128 v[176:179], v248 offset:36864
	ds_read_b128 v[180:183], v248 offset:37888
	ds_read_b128 v[184:187], v248 offset:38912
	ds_read_b128 v[188:191], v248 offset:39936
	global_load_lds_dwordx4 v[214:215], off
	v_lshl_add_u64 v[214:215], s[46:47], 0, v[196:197]
	s_mov_b32 m0, s55
	s_nop 0
	global_load_lds_dwordx4 v[214:215], off
	s_waitcnt vmcnt(8)
	s_waitcnt lgkmcnt(0)
	s_barrier
	s_setprio 1
	v_mfma_f32_16x16x32_bf16 v[148:151], v[112:115], v[160:163], v[148:151]
	v_mfma_f32_16x16x32_bf16 v[144:147], v[120:123], v[160:163], v[144:147]
	v_mfma_f32_16x16x32_bf16 v[108:111], v[112:115], v[168:171], v[108:111]
	v_mfma_f32_16x16x32_bf16 v[104:107], v[120:123], v[168:171], v[104:107]
	v_mfma_f32_16x16x32_bf16 v[92:95], v[112:115], v[176:179], v[92:95]
	v_mfma_f32_16x16x32_bf16 v[88:91], v[120:123], v[176:179], v[88:91]
	v_mfma_f32_16x16x32_bf16 v[76:79], v[112:115], v[184:187], v[76:79]
	v_mfma_f32_16x16x32_bf16 v[72:75], v[120:123], v[184:187], v[72:75]
	v_mfma_f32_16x16x32_bf16 v[148:151], v[116:119], v[164:167], v[148:151]
	v_mfma_f32_16x16x32_bf16 v[144:147], v[124:127], v[164:167], v[144:147]
	v_mfma_f32_16x16x32_bf16 v[108:111], v[116:119], v[172:175], v[108:111]
	v_mfma_f32_16x16x32_bf16 v[104:107], v[124:127], v[172:175], v[104:107]
	v_mfma_f32_16x16x32_bf16 v[92:95], v[116:119], v[180:183], v[92:95]
	v_mfma_f32_16x16x32_bf16 v[88:91], v[124:127], v[180:183], v[88:91]
	v_mfma_f32_16x16x32_bf16 v[76:79], v[116:119], v[188:191], v[76:79]
	v_mfma_f32_16x16x32_bf16 v[72:75], v[124:127], v[188:191], v[72:75]
	v_mfma_f32_16x16x32_bf16 v[132:135], v[136:139], v[160:163], v[132:135]
	v_mfma_f32_16x16x32_bf16 v[128:131], v[152:155], v[160:163], v[128:131]
	v_mfma_f32_16x16x32_bf16 v[100:103], v[136:139], v[168:171], v[100:103]
	v_mfma_f32_16x16x32_bf16 v[96:99], v[152:155], v[168:171], v[96:99]
	v_mfma_f32_16x16x32_bf16 v[84:87], v[136:139], v[176:179], v[84:87]
	v_mfma_f32_16x16x32_bf16 v[80:83], v[152:155], v[176:179], v[80:83]
	v_mfma_f32_16x16x32_bf16 v[68:71], v[136:139], v[184:187], v[68:71]
	v_mfma_f32_16x16x32_bf16 v[64:67], v[152:155], v[184:187], v[64:67]
	v_mfma_f32_16x16x32_bf16 v[132:135], v[140:143], v[164:167], v[132:135]
	v_mfma_f32_16x16x32_bf16 v[128:131], v[156:159], v[164:167], v[128:131]
	v_mfma_f32_16x16x32_bf16 v[100:103], v[140:143], v[172:175], v[100:103]
	v_mfma_f32_16x16x32_bf16 v[96:99], v[156:159], v[172:175], v[96:99]
	v_mfma_f32_16x16x32_bf16 v[84:87], v[140:143], v[180:183], v[84:87]
	v_mfma_f32_16x16x32_bf16 v[80:83], v[156:159], v[180:183], v[80:83]
	v_mfma_f32_16x16x32_bf16 v[68:71], v[140:143], v[188:191], v[68:71]
	v_mfma_f32_16x16x32_bf16 v[64:67], v[156:159], v[188:191], v[64:67]
	s_barrier
; #define PG8_STAGE(bufoff, gbase, voff) do { _Pragma("unroll") for (int _i = 0; _i < 2; ++_i) \
;         __builtin_amdgcn_global_load_lds((const unsigned*)((const char*)(gbase) + (voff)[_i]), (PG8_LAS unsigned*)(lds + (bufoff) + ldsw + _i * 8192), 16, 0, 0); } while (0)
; #define PG8_LDA(dst, b, h) do { _Pragma("unroll") for (int m = 0; m < 4; ++m) _Pragma("unroll") for (int k = 0; k < 2; ++k) dst[m][k] = *(const PG8_LAS bf16x8*)(lds + PG8_SA(b, h) + aoff + m * 2048 + k * 1024); } while (0)
; #define PG8_MMA(ai, bj, At, Bt) do { __builtin_amdgcn_s_setprio(1); _Pragma("unroll") for (int m = 0; m < 4; ++m) _Pragma("unroll") for (int n = 0; n < 2; ++n) _Pragma("unroll") for (int k = 0; k < 2; ++k) \
;         acc[ai][bj][m][n] = __builtin_amdgcn_mfma_f32_16x16x32_bf16(Bt[n][k], At[m][k], acc[ai][bj][m][n], 0, 0, 0); __builtin_amdgcn_s_setprio(0); } while (0)
; #define PG8_WAIT_V(n) asm volatile("s_waitcnt vmcnt(" #n ")" ::: "memory")
; #define PG8_WAIT_L(n) asm volatile("s_waitcnt lgkmcnt(" #n ")" ::: "memory")
; #define PG8_BAR __builtin_amdgcn_s_barrier()
; #define PG8_SCHED __builtin_amdgcn_sched_barrier(0)
; template <class Epi, class Sched, bool ALIGN_EPI = false, bool SP2 = false>
; __device__ __forceinline__ void gemm_phase(PG8_LAS unsigned char* lds, const Gemm g, const Sched& S, const Epi& E) {
;     ...
;         for (int t = 0; t < nt; t += 2) {
;             const bool last = (t == nt - 2);
;             if constexpr (Epi::PREFETCH) { if (t == nt - 4) E.prefetch(cur, lds + STAGE_BYTES + 1024, tid); }
;             const char* a1 = cA + (size_t)(t + 1) * kstep;
;             const char* a2 = last ? nA : cA + (size_t)(t + 2) * kstep; const char* b2 = last ? nB : cB + (size_t)(t + 2) * kstep;
;             const char* a3 = a2 + kstep; const char* b3 = b2 + kstep;
;     ...
;             PG8_LDA(At, 1, 1); PG8_STAGE(PG8_SB(1, 0), b3, voffB); PG8_STAGE(PG8_SB(1, 1), b3 + hstep, voffB); PG8_STAGE(PG8_SA(1, 0), a3, voffA);
;             PG8_WAIT_V(8); PG8_WAIT_L(0); PG8_BAR; PG8_MMA(1, 0, At, B0); PG8_MMA(1, 1, At, B1); PG8_BAR; PG8_SCHED;
	s_setprio 0
	s_add_i32 s46, s69, s52
	v_lshl_add_u64 v[206:207], v[206:207], 0, s[16:17]
	s_mov_b32 m0, s46
	ds_read_b128 v[160:163], v248 offset:49152
	ds_read_b128 v[164:167], v248 offset:50176
	ds_read_b128 v[168:171], v248 offset:51200
	ds_read_b128 v[172:175], v248 offset:52224
	ds_read_b128 v[176:179], v248 offset:53248
	ds_read_b128 v[180:183], v248 offset:54272
	ds_read_b128 v[184:187], v248 offset:55296
	ds_read_b128 v[188:191], v248 offset:56320
	global_load_lds_dwordx4 v[206:207], off
	s_add_i32 m0, s46, 0x2000
	s_add_u32 s44, s44, 0x40080
	v_lshl_add_u64 v[206:207], v[208:209], 0, s[16:17]
	s_addc_u32 s45, s45, 0
	s_add_i32 s46, s70, s52
	global_load_lds_dwordx4 v[206:207], off
	v_lshl_add_u64 v[206:207], s[44:45], 0, v[194:195]
	s_mov_b32 m0, s46
	s_nop 0
	global_load_lds_dwordx4 v[206:207], off
	v_lshl_add_u64 v[206:207], s[44:45], 0, v[198:199]
	s_add_i32 m0, s46, 0x2000
	s_nop 0
	global_load_lds_dwordx4 v[206:207], off
	v_lshl_add_u64 v[206:207], v[210:211], 0, s[16:17]
	s_mov_b32 m0, s57
	s_nop 0
	global_load_lds_dwordx4 v[206:207], off
	v_lshl_add_u64 v[206:207], v[212:213], 0, s[16:17]
	s_mov_b32 m0, s58
	s_nop 0
	global_load_lds_dwordx4 v[206:207], off
	s_waitcnt vmcnt(8)
	s_waitcnt lgkmcnt(0)
	s_barrier
	s_setprio 1
	v_mfma_f32_16x16x32_bf16 v[60:63], v[112:115], v[160:163], v[60:63]
	v_mfma_f32_16x16x32_bf16 v[56:59], v[120:123], v[160:163], v[56:59]
	v_mfma_f32_16x16x32_bf16 v[44:47], v[112:115], v[168:171], v[44:47]
	v_mfma_f32_16x16x32_bf16 v[40:43], v[120:123], v[168:171], v[40:43]
	v_mfma_f32_16x16x32_bf16 v[28:31], v[112:115], v[176:179], v[28:31]
	v_mfma_f32_16x16x32_bf16 v[24:27], v[120:123], v[176:179], v[24:27]
	v_mfma_f32_16x16x32_bf16 v[12:15], v[112:115], v[184:187], v[12:15]
	v_mfma_f32_16x16x32_bf16 v[8:11], v[120:123], v[184:187], v[8:11]
	v_mfma_f32_16x16x32_bf16 v[60:63], v[116:119], v[164:167], v[60:63]
	v_mfma_f32_16x16x32_bf16 v[56:59], v[124:127], v[164:167], v[56:59]
	v_mfma_f32_16x16x32_bf16 v[44:47], v[116:119], v[172:175], v[44:47]
	v_mfma_f32_16x16x32_bf16 v[40:43], v[124:127], v[172:175], v[40:43]
	v_mfma_f32_16x16x32_bf16 v[28:31], v[116:119], v[180:183], v[28:31]
	v_mfma_f32_16x16x32_bf16 v[24:27], v[124:127], v[180:183], v[24:27]
	v_mfma_f32_16x16x32_bf16 v[12:15], v[116:119], v[188:191], v[12:15]
	v_mfma_f32_16x16x32_bf16 v[8:11], v[124:127], v[188:191], v[8:11]
	v_mfma_f32_16x16x32_bf16 v[52:55], v[136:139], v[160:163], v[52:55]
	v_mfma_f32_16x16x32_bf16 v[48:51], v[152:155], v[160:163], v[48:51]
	v_mfma_f32_16x16x32_bf16 v[36:39], v[136:139], v[168:171], v[36:39]
	v_mfma_f32_16x16x32_bf16 v[32:35], v[152:155], v[168:171], v[32:35]
	v_mfma_f32_16x16x32_bf16 v[20:23], v[136:139], v[176:179], v[20:23]
	v_mfma_f32_16x16x32_bf16 v[16:19], v[152:155], v[176:179], v[16:19]
	v_mfma_f32_16x16x32_bf16 v[4:7], v[136:139], v[184:187], v[4:7]
	v_mfma_f32_16x16x32_bf16 v[0:3], v[152:155], v[184:187], v[0:3]
	v_mfma_f32_16x16x32_bf16 v[52:55], v[140:143], v[164:167], v[52:55]
	v_mfma_f32_16x16x32_bf16 v[48:51], v[156:159], v[164:167], v[48:51]
	v_mfma_f32_16x16x32_bf16 v[36:39], v[140:143], v[172:175], v[36:39]
	v_mfma_f32_16x16x32_bf16 v[32:35], v[156:159], v[172:175], v[32:35]
	v_mfma_f32_16x16x32_bf16 v[20:23], v[140:143], v[180:183], v[20:23]
	v_mfma_f32_16x16x32_bf16 v[16:19], v[156:159], v[180:183], v[16:19]
	v_mfma_f32_16x16x32_bf16 v[4:7], v[140:143], v[188:191], v[4:7]
	v_mfma_f32_16x16x32_bf16 v[0:3], v[156:159], v[188:191], v[0:3]
	s_barrier
	s_setprio 0
	s_add_i32 s68, s68, 2
	s_add_u32 s42, s42, 0x100
	s_addc_u32 s43, s43, 0
	s_add_u32 s66, s66, 0x100
	s_addc_u32 s67, s67, 0

; #define PG8_STAGE(bufoff, gbase, voff) do { _Pragma("unroll") for (int _i = 0; _i < 2; ++_i) \
;         __builtin_amdgcn_global_load_lds((const unsigned*)((const char*)(gbase) + (voff)[_i]), (PG8_LAS unsigned*)(lds + (bufoff) + ldsw + _i * 8192), 16, 0, 0); } while (0)
; #define PG8_LDA(dst, b, h) do { _Pragma("unroll") for (int m = 0; m < 4; ++m) _Pragma("unroll") for (int k = 0; k < 2; ++k) dst[m][k] = *(const PG8_LAS bf16x8*)(lds + PG8_SA(b, h) + aoff + m * 2048 + k * 1024); } while (0)
; #define PG8_LDB(dst, b, h) do { _Pragma("unroll") for (int n = 0; n < 2; ++n) _Pragma("unroll") for (int k = 0; k < 2; ++k) dst[n][k] = *(const PG8_LAS bf16x8*)(lds + PG8_SB(b, h) + boff + n * 2048 + k * 1024); } while (0)
; #define PG8_WAIT_V(n) asm volatile("s_waitcnt vmcnt(" #n ")" ::: "memory")
; #define PG8_WAIT_L(n) asm volatile("s_waitcnt lgkmcnt(" #n ")" ::: "memory")
; #define PG8_BAR __builtin_amdgcn_s_barrier()
; #define PG8_SCHED __builtin_amdgcn_sched_barrier(0)
; template <class Epi, class Sched, bool ALIGN_EPI = false, bool SP2 = false>
; __device__ __forceinline__ void gemm_phase(PG8_LAS unsigned char* lds, const Gemm g, const Sched& S, const Epi& E) {
;     ...
;         const bool has_next = S.next(ui + 1, nxt);
;         const char* nA = has_next ? (const char*)g.A + (size_t)nxt.pm * tstep : cA; const char* nB = has_next ? (const char*)g.Bt + (size_t)nxt.pn * tstep : cB;
;         for (int t = 0; t < nt; t += 2) {
;             const bool last = (t == nt - 2);
;             if constexpr (Epi::PREFETCH) { if (t == nt - 4) E.prefetch(cur, lds + STAGE_BYTES + 1024, tid); }
;             const char* a1 = cA + (size_t)(t + 1) * kstep;
;             const char* a2 = last ? nA : cA + (size_t)(t + 2) * kstep; const char* b2 = last ? nB : cB + (size_t)(t + 2) * kstep;
;             const char* a3 = a2 + kstep; const char* b3 = b2 + kstep;
;             if (last && has_next) S.a_ready(nxt);
;             if constexpr (SP2) {
;             PG8_LDB(B0, 0, 0); PG8_LDB(B1, 0, 1); PG8_SCHED; PG8_LDA(At, 0, 0); PG8_STAGE(PG8_SA(1, 1), a1 + hstep, voffA);
;             PG8_WAIT_V(8); PG8_WAIT_L(0); PG8_BAR; PG8_MMA(0, 0, At, B0); PG8_MMA(0, 1, At, B1); PG8_BAR; PG8_SCHED;
;             PG8_LDA(At, 0, 1); PG8_STAGE(PG8_SB(0, 0), b2, voffB); PG8_STAGE(PG8_SB(0, 1), b2 + hstep, voffB); PG8_STAGE(PG8_SA(0, 0), a2, voffA);
.LBB0_1193:
	s_ashr_i32 s21, s20, 31
	s_lshl_b64 s[22:23], s[20:21], 19
	s_add_u32 s22, s44, s22
	s_addc_u32 s23, s45, s23
	s_and_b64 s[34:35], s[4:5], exec
	s_cselect_b32 s21, s23, s39
	s_cselect_b32 s64, s22, s38
	s_ashr_i32 s19, s18, 31
	s_lshl_b64 s[34:35], s[18:19], 19
	s_add_u32 s34, s46, s34
	s_addc_u32 s35, s47, s35
	s_and_b64 s[42:43], s[4:5], exec
	s_cselect_b32 s19, s35, s41
	s_cselect_b32 s65, s34, s40
	s_add_u32 s38, s38, 0x40080
	s_addc_u32 s39, s39, 0
	s_add_u32 s66, s40, 0x100
	s_addc_u32 s67, s41, 0
	s_mov_b32 s68, -2
	ds_read_b128 v[154:157], v149
	ds_read_b128 v[158:161], v149 offset:1024
	ds_read_b128 v[162:165], v149 offset:2048
	ds_read_b128 v[166:169], v149 offset:3072
	ds_read_b128 v[170:173], v150
	ds_read_b128 v[174:177], v150 offset:1024
	ds_read_b128 v[178:181], v150 offset:2048
	ds_read_b128 v[182:185], v150 offset:3072
	s_add_u32 s40, s38, 0xfffc0080
	s_addc_u32 s41, s39, -1
	s_cmp_eq_u32 s68, 12
	s_cselect_b32 s43, s21, s41
	s_cselect_b32 s42, s64, s40
	s_cselect_b32 s41, s19, s67
	s_cselect_b32 s40, s65, s66
	v_lshl_add_u64 v[144:145], s[38:39], 0, v[136:137]
	s_add_i32 m0, s37, 0xc000
	ds_read_b128 v[186:189], v151
	ds_read_b128 v[190:193], v151 offset:1024
	ds_read_b128 v[194:197], v151 offset:2048
	ds_read_b128 v[198:201], v151 offset:3072
	ds_read_b128 v[202:205], v151 offset:4096
	ds_read_b128 v[206:209], v151 offset:5120
	ds_read_b128 v[210:213], v151 offset:6144
	ds_read_b128 v[214:217], v151 offset:7168
	global_load_lds_dwordx4 v[144:145], off
	v_lshl_add_u64 v[144:145], s[38:39], 0, v[138:139]
	s_add_i32 m0, s37, 0xe000
	s_nop 0
	global_load_lds_dwordx4 v[144:145], off
	s_waitcnt vmcnt(8)
	s_waitcnt lgkmcnt(0)
	s_barrier
	s_setprio 1
	v_mfma_f32_16x16x32_bf16 v[120:123], v[154:157], v[186:189], 0
	v_mfma_f32_16x16x32_bf16 v[116:119], v[162:165], v[186:189], 0
	v_mfma_f32_16x16x32_bf16 v[108:111], v[154:157], v[194:197], 0
	v_mfma_f32_16x16x32_bf16 v[100:103], v[162:165], v[194:197], 0
	v_mfma_f32_16x16x32_bf16 v[92:95], v[154:157], v[202:205], 0
	v_mfma_f32_16x16x32_bf16 v[84:87], v[162:165], v[202:205], 0
	v_mfma_f32_16x16x32_bf16 v[76:79], v[154:157], v[210:213], 0
	v_mfma_f32_16x16x32_bf16 v[68:71], v[162:165], v[210:213], 0
	v_mfma_f32_16x16x32_bf16 v[120:123], v[158:161], v[190:193], v[120:123]
	v_mfma_f32_16x16x32_bf16 v[116:119], v[166:169], v[190:193], v[116:119]
	v_mfma_f32_16x16x32_bf16 v[108:111], v[158:161], v[198:201], v[108:111]
	v_mfma_f32_16x16x32_bf16 v[100:103], v[166:169], v[198:201], v[100:103]
	v_mfma_f32_16x16x32_bf16 v[92:95], v[158:161], v[206:209], v[92:95]
	v_mfma_f32_16x16x32_bf16 v[84:87], v[166:169], v[206:209], v[84:87]
	v_mfma_f32_16x16x32_bf16 v[76:79], v[158:161], v[214:217], v[76:79]
	v_mfma_f32_16x16x32_bf16 v[68:71], v[166:169], v[214:217], v[68:71]
	v_mfma_f32_16x16x32_bf16 v[124:127], v[170:173], v[186:189], 0
	v_mfma_f32_16x16x32_bf16 v[112:115], v[178:181], v[186:189], 0
	v_mfma_f32_16x16x32_bf16 v[104:107], v[170:173], v[194:197], 0
	v_mfma_f32_16x16x32_bf16 v[96:99], v[178:181], v[194:197], 0
	v_mfma_f32_16x16x32_bf16 v[88:91], v[170:173], v[202:205], 0
	v_mfma_f32_16x16x32_bf16 v[80:83], v[178:181], v[202:205], 0
	v_mfma_f32_16x16x32_bf16 v[72:75], v[170:173], v[210:213], 0
	v_mfma_f32_16x16x32_bf16 v[64:67], v[178:181], v[210:213], 0
	v_mfma_f32_16x16x32_bf16 v[124:127], v[174:177], v[190:193], v[124:127]
	v_mfma_f32_16x16x32_bf16 v[112:115], v[182:185], v[190:193], v[112:115]
	v_mfma_f32_16x16x32_bf16 v[104:107], v[174:177], v[198:201], v[104:107]
	v_mfma_f32_16x16x32_bf16 v[96:99], v[182:185], v[198:201], v[96:99]
	v_mfma_f32_16x16x32_bf16 v[88:91], v[174:177], v[206:209], v[88:91]
	v_mfma_f32_16x16x32_bf16 v[80:83], v[182:185], v[206:209], v[80:83]
	v_mfma_f32_16x16x32_bf16 v[72:75], v[174:177], v[214:217], v[72:75]
	v_mfma_f32_16x16x32_bf16 v[64:67], v[182:185], v[214:217], v[64:67]
	s_barrier
	s_setprio 0
	s_add_i32 s69, s57, s48
	v_lshl_add_u64 v[144:145], s[40:41], 0, v[132:133]
	s_mov_b32 m0, s69
	ds_read_b128 v[186:189], v151 offset:16384
	ds_read_b128 v[190:193], v151 offset:17408
	ds_read_b128 v[194:197], v151 offset:18432
	ds_read_b128 v[198:201], v151 offset:19456
	ds_read_b128 v[202:205], v151 offset:20480
	ds_read_b128 v[206:209], v151 offset:21504
	ds_read_b128 v[210:213], v151 offset:22528
	ds_read_b128 v[214:217], v151 offset:23552
	global_load_lds_dwordx4 v[144:145], off
	s_add_i32 m0, s69, 0x2000
	s_add_u32 s70, s40, 0x40000
	v_lshl_add_u64 v[218:219], s[40:41], 0, v[128:129]
	s_addc_u32 s71, s41, 0
	s_add_i32 s69, s58, s48
	global_load_lds_dwordx4 v[218:219], off
	v_lshl_add_u64 v[220:221], s[70:71], 0, v[132:133]
	s_mov_b32 m0, s69
	v_lshl_add_u64 v[222:223], s[42:43], 0, v[130:131]
	global_load_lds_dwordx4 v[220:221], off
	v_lshl_add_u64 v[220:221], s[70:71], 0, v[128:129]
	s_add_i32 m0, s69, 0x2000
	s_nop 0
	global_load_lds_dwordx4 v[220:221], off
	v_lshl_add_u64 v[220:221], s[42:43], 0, v[134:135]
	s_mov_b32 m0, s37
	s_nop 0
	global_load_lds_dwordx4 v[220:221], off
	s_mov_b32 m0, s50
	s_nop 0
	global_load_lds_dwordx4 v[222:223], off
	s_waitcnt vmcnt(8)
	s_waitcnt lgkmcnt(0)
	s_barrier
; #define PG8_STAGE(bufoff, gbase, voff) do { _Pragma("unroll") for (int _i = 0; _i < 2; ++_i) \
;         __builtin_amdgcn_global_load_lds((const unsigned*)((const char*)(gbase) + (voff)[_i]), (PG8_LAS unsigned*)(lds + (bufoff) + ldsw + _i * 8192), 16, 0, 0); } while (0)
; #define PG8_LDA(dst, b, h) do { _Pragma("unroll") for (int m = 0; m < 4; ++m) _Pragma("unroll") for (int k = 0; k < 2; ++k) dst[m][k] = *(const PG8_LAS bf16x8*)(lds + PG8_SA(b, h) + aoff + m * 2048 + k * 1024); } while (0)
; #define PG8_LDB(dst, b, h) do { _Pragma("unroll") for (int n = 0; n < 2; ++n) _Pragma("unroll") for (int k = 0; k < 2; ++k) dst[n][k] = *(const PG8_LAS bf16x8*)(lds + PG8_SB(b, h) + boff + n * 2048 + k * 1024); } while (0)
; #define PG8_MMA(ai, bj, At, Bt) do { __builtin_amdgcn_s_setprio(1); _Pragma("unroll") for (int m = 0; m < 4; ++m) _Pragma("unroll") for (int n = 0; n < 2; ++n) _Pragma("unroll") for (int k = 0; k < 2; ++k) \
;         acc[ai][bj][m][n] = __builtin_amdgcn_mfma_f32_16x16x32_bf16(Bt[n][k], At[m][k], acc[ai][bj][m][n], 0, 0, 0); __builtin_amdgcn_s_setprio(0); } while (0)
; #define PG8_WAIT_V(n) asm volatile("s_waitcnt vmcnt(" #n ")" ::: "memory")
; #define PG8_WAIT_L(n) asm volatile("s_waitcnt lgkmcnt(" #n ")" ::: "memory")
; #define PG8_BAR __builtin_amdgcn_s_barrier()
; #define PG8_SCHED __builtin_amdgcn_sched_barrier(0)
; template <class Epi, class Sched, bool ALIGN_EPI = false, bool SP2 = false>
; __device__ __forceinline__ void gemm_phase(PG8_LAS unsigned char* lds, const Gemm g, const Sched& S, const Epi& E) {
;     ...
;             PG8_WAIT_V(8); PG8_WAIT_L(0); PG8_BAR; PG8_MMA(1, 0, At, B0); PG8_MMA(1, 1, At, B1); PG8_BAR; PG8_SCHED;
;             PG8_LDB(B0, 1, 0); PG8_LDB(B1, 1, 1); PG8_SCHED; PG8_LDA(At, 1, 0); PG8_STAGE(PG8_SA(0, 1), a2 + hstep, voffA);
;             PG8_WAIT_V(8); PG8_WAIT_L(0); PG8_BAR; PG8_MMA(0, 0, At, B0); PG8_MMA(0, 1, At, B1); PG8_BAR; PG8_SCHED;
	s_setprio 1
	v_mfma_f32_16x16x32_bf16 v[60:63], v[154:157], v[186:189], 0
	v_mfma_f32_16x16x32_bf16 v[52:55], v[162:165], v[186:189], 0
	v_mfma_f32_16x16x32_bf16 v[44:47], v[154:157], v[194:197], 0
	v_mfma_f32_16x16x32_bf16 v[36:39], v[162:165], v[194:197], 0
	v_mfma_f32_16x16x32_bf16 v[28:31], v[154:157], v[202:205], 0
	v_mfma_f32_16x16x32_bf16 v[20:23], v[162:165], v[202:205], 0
	v_mfma_f32_16x16x32_bf16 v[12:15], v[154:157], v[210:213], 0
	v_mfma_f32_16x16x32_bf16 v[4:7], v[162:165], v[210:213], 0
	v_mfma_f32_16x16x32_bf16 v[60:63], v[158:161], v[190:193], v[60:63]
	v_mfma_f32_16x16x32_bf16 v[52:55], v[166:169], v[190:193], v[52:55]
	v_mfma_f32_16x16x32_bf16 v[44:47], v[158:161], v[198:201], v[44:47]
	v_mfma_f32_16x16x32_bf16 v[36:39], v[166:169], v[198:201], v[36:39]
	v_mfma_f32_16x16x32_bf16 v[28:31], v[158:161], v[206:209], v[28:31]
	v_mfma_f32_16x16x32_bf16 v[20:23], v[166:169], v[206:209], v[20:23]
	v_mfma_f32_16x16x32_bf16 v[12:15], v[158:161], v[214:217], v[12:15]
	v_mfma_f32_16x16x32_bf16 v[4:7], v[166:169], v[214:217], v[4:7]
	v_mfma_f32_16x16x32_bf16 v[56:59], v[170:173], v[186:189], 0
	v_mfma_f32_16x16x32_bf16 v[48:51], v[178:181], v[186:189], 0
	v_mfma_f32_16x16x32_bf16 v[40:43], v[170:173], v[194:197], 0
	v_mfma_f32_16x16x32_bf16 v[32:35], v[178:181], v[194:197], 0
	v_mfma_f32_16x16x32_bf16 v[24:27], v[170:173], v[202:205], 0
	v_mfma_f32_16x16x32_bf16 v[16:19], v[178:181], v[202:205], 0
	v_mfma_f32_16x16x32_bf16 v[8:11], v[170:173], v[210:213], 0
	v_mfma_f32_16x16x32_bf16 v[0:3], v[178:181], v[210:213], 0
	v_mfma_f32_16x16x32_bf16 v[56:59], v[174:177], v[190:193], v[56:59]
	v_mfma_f32_16x16x32_bf16 v[48:51], v[182:185], v[190:193], v[48:51]
	v_mfma_f32_16x16x32_bf16 v[40:43], v[174:177], v[198:201], v[40:43]
	v_mfma_f32_16x16x32_bf16 v[32:35], v[182:185], v[198:201], v[32:35]
	v_mfma_f32_16x16x32_bf16 v[24:27], v[174:177], v[206:209], v[24:27]
	v_mfma_f32_16x16x32_bf16 v[16:19], v[182:185], v[206:209], v[16:19]
	v_mfma_f32_16x16x32_bf16 v[8:11], v[174:177], v[214:217], v[8:11]
	v_mfma_f32_16x16x32_bf16 v[0:3], v[182:185], v[214:217], v[0:3]
	s_barrier
	s_setprio 0
	s_add_i32 s69, 0, 0x18000
	v_add_u32_e32 v153, s69, v147
	s_add_i32 s70, 0, 0x1c000
	ds_read_b128 v[154:157], v153
	ds_read_b128 v[158:161], v153 offset:1024
	ds_read_b128 v[162:165], v153 offset:2048
	ds_read_b128 v[166:169], v153 offset:3072
	v_add_u32_e32 v153, s70, v147
	ds_read_b128 v[170:173], v153
	ds_read_b128 v[174:177], v153 offset:1024
	ds_read_b128 v[178:181], v153 offset:2048
	ds_read_b128 v[182:185], v153 offset:3072
	s_add_u32 s42, s42, 0x40000
	s_addc_u32 s43, s43, 0
	s_mov_b32 m0, s51
	v_lshl_add_u64 v[224:225], s[42:43], 0, v[134:135]
	ds_read_b128 v[186:189], v151 offset:32768
	ds_read_b128 v[190:193], v151 offset:33792
	ds_read_b128 v[194:197], v151 offset:34816
	ds_read_b128 v[198:201], v151 offset:35840
	ds_read_b128 v[202:205], v151 offset:36864
	ds_read_b128 v[206:209], v151 offset:37888
	ds_read_b128 v[210:213], v151 offset:38912
	ds_read_b128 v[214:217], v151 offset:39936
	global_load_lds_dwordx4 v[224:225], off
	v_lshl_add_u64 v[224:225], s[42:43], 0, v[130:131]
	s_mov_b32 m0, s52
	s_nop 0
	global_load_lds_dwordx4 v[224:225], off
	s_waitcnt vmcnt(8)
	s_waitcnt lgkmcnt(0)
	s_barrier
	s_setprio 1
	v_mfma_f32_16x16x32_bf16 v[120:123], v[154:157], v[186:189], v[120:123]
	v_mfma_f32_16x16x32_bf16 v[116:119], v[162:165], v[186:189], v[116:119]
	v_mfma_f32_16x16x32_bf16 v[108:111], v[154:157], v[194:197], v[108:111]
	v_mfma_f32_16x16x32_bf16 v[100:103], v[162:165], v[194:197], v[100:103]
	v_mfma_f32_16x16x32_bf16 v[92:95], v[154:157], v[202:205], v[92:95]
	v_mfma_f32_16x16x32_bf16 v[84:87], v[162:165], v[202:205], v[84:87]
	v_mfma_f32_16x16x32_bf16 v[76:79], v[154:157], v[210:213], v[76:79]
	v_mfma_f32_16x16x32_bf16 v[68:71], v[162:165], v[210:213], v[68:71]
	v_mfma_f32_16x16x32_bf16 v[120:123], v[158:161], v[190:193], v[120:123]
	v_mfma_f32_16x16x32_bf16 v[116:119], v[166:169], v[190:193], v[116:119]
	v_mfma_f32_16x16x32_bf16 v[108:111], v[158:161], v[198:201], v[108:111]
	v_mfma_f32_16x16x32_bf16 v[100:103], v[166:169], v[198:201], v[100:103]
	v_mfma_f32_16x16x32_bf16 v[92:95], v[158:161], v[206:209], v[92:95]
	v_mfma_f32_16x16x32_bf16 v[84:87], v[166:169], v[206:209], v[84:87]
	v_mfma_f32_16x16x32_bf16 v[76:79], v[158:161], v[214:217], v[76:79]
	v_mfma_f32_16x16x32_bf16 v[68:71], v[166:169], v[214:217], v[68:71]
	v_mfma_f32_16x16x32_bf16 v[124:127], v[170:173], v[186:189], v[124:127]
	v_mfma_f32_16x16x32_bf16 v[112:115], v[178:181], v[186:189], v[112:115]
	v_mfma_f32_16x16x32_bf16 v[104:107], v[170:173], v[194:197], v[104:107]
	v_mfma_f32_16x16x32_bf16 v[96:99], v[178:181], v[194:197], v[96:99]
	v_mfma_f32_16x16x32_bf16 v[88:91], v[170:173], v[202:205], v[88:91]
	v_mfma_f32_16x16x32_bf16 v[80:83], v[178:181], v[202:205], v[80:83]
	v_mfma_f32_16x16x32_bf16 v[72:75], v[170:173], v[210:213], v[72:75]
	v_mfma_f32_16x16x32_bf16 v[64:67], v[178:181], v[210:213], v[64:67]
	v_mfma_f32_16x16x32_bf16 v[124:127], v[174:177], v[190:193], v[124:127]
	v_mfma_f32_16x16x32_bf16 v[112:115], v[182:185], v[190:193], v[112:115]
	v_mfma_f32_16x16x32_bf16 v[104:107], v[174:177], v[198:201], v[104:107]
	v_mfma_f32_16x16x32_bf16 v[96:99], v[182:185], v[198:201], v[96:99]
	v_mfma_f32_16x16x32_bf16 v[88:91], v[174:177], v[206:209], v[88:91]
	v_mfma_f32_16x16x32_bf16 v[80:83], v[182:185], v[206:209], v[80:83]
	v_mfma_f32_16x16x32_bf16 v[72:75], v[174:177], v[214:217], v[72:75]
	v_mfma_f32_16x16x32_bf16 v[64:67], v[182:185], v[214:217], v[64:67]
	s_barrier
; #define PG8_STAGE(bufoff, gbase, voff) do { _Pragma("unroll") for (int _i = 0; _i < 2; ++_i) \
;         __builtin_amdgcn_global_load_lds((const unsigned*)((const char*)(gbase) + (voff)[_i]), (PG8_LAS unsigned*)(lds + (bufoff) + ldsw + _i * 8192), 16, 0, 0); } while (0)
; #define PG8_LDA(dst, b, h) do { _Pragma("unroll") for (int m = 0; m < 4; ++m) _Pragma("unroll") for (int k = 0; k < 2; ++k) dst[m][k] = *(const PG8_LAS bf16x8*)(lds + PG8_SA(b, h) + aoff + m * 2048 + k * 1024); } while (0)
; #define PG8_MMA(ai, bj, At, Bt) do { __builtin_amdgcn_s_setprio(1); _Pragma("unroll") for (int m = 0; m < 4; ++m) _Pragma("unroll") for (int n = 0; n < 2; ++n) _Pragma("unroll") for (int k = 0; k < 2; ++k) \
;         acc[ai][bj][m][n] = __builtin_amdgcn_mfma_f32_16x16x32_bf16(Bt[n][k], At[m][k], acc[ai][bj][m][n], 0, 0, 0); __builtin_amdgcn_s_setprio(0); } while (0)
; #define PG8_WAIT_V(n) asm volatile("s_waitcnt vmcnt(" #n ")" ::: "memory")
; #define PG8_WAIT_L(n) asm volatile("s_waitcnt lgkmcnt(" #n ")" ::: "memory")
; #define PG8_BAR __builtin_amdgcn_s_barrier()
; #define PG8_SCHED __builtin_amdgcn_sched_barrier(0)
; template <class Epi, class Sched, bool ALIGN_EPI = false, bool SP2 = false>
; __device__ __forceinline__ void gemm_phase(PG8_LAS unsigned char* lds, const Gemm g, const Sched& S, const Epi& E) {
;     ...
;         for (int t = 0; t < nt; t += 2) {
;             const bool last = (t == nt - 2);
;             if constexpr (Epi::PREFETCH) { if (t == nt - 4) E.prefetch(cur, lds + STAGE_BYTES + 1024, tid); }
;             const char* a1 = cA + (size_t)(t + 1) * kstep;
;             const char* a2 = last ? nA : cA + (size_t)(t + 2) * kstep; const char* b2 = last ? nB : cB + (size_t)(t + 2) * kstep;
;             const char* a3 = a2 + kstep; const char* b3 = b2 + kstep;
;     ...
;             PG8_LDA(At, 1, 1); PG8_STAGE(PG8_SB(1, 0), b3, voffB); PG8_STAGE(PG8_SB(1, 1), b3 + hstep, voffB); PG8_STAGE(PG8_SA(1, 0), a3, voffA);
;             PG8_WAIT_V(8); PG8_WAIT_L(0); PG8_BAR; PG8_MMA(1, 0, At, B0); PG8_MMA(1, 1, At, B1); PG8_BAR; PG8_SCHED;
	s_setprio 0
	s_add_i32 s42, s69, s48
	v_lshl_add_u64 v[144:145], v[144:145], 0, s[14:15]
	s_mov_b32 m0, s42
	ds_read_b128 v[186:189], v151 offset:49152
	ds_read_b128 v[190:193], v151 offset:50176
	ds_read_b128 v[194:197], v151 offset:51200
	ds_read_b128 v[198:201], v151 offset:52224
	ds_read_b128 v[202:205], v151 offset:53248
	ds_read_b128 v[206:209], v151 offset:54272
	ds_read_b128 v[210:213], v151 offset:55296
	ds_read_b128 v[214:217], v151 offset:56320
	global_load_lds_dwordx4 v[144:145], off
	s_add_i32 m0, s42, 0x2000
	s_add_u32 s40, s40, 0x40080
	v_lshl_add_u64 v[144:145], v[218:219], 0, s[14:15]
	s_addc_u32 s41, s41, 0
	s_add_i32 s42, s70, s48
	global_load_lds_dwordx4 v[144:145], off
	v_lshl_add_u64 v[144:145], s[40:41], 0, v[132:133]
	s_mov_b32 m0, s42
	s_nop 0
	global_load_lds_dwordx4 v[144:145], off
	v_lshl_add_u64 v[144:145], s[40:41], 0, v[128:129]
	s_add_i32 m0, s42, 0x2000
	s_nop 0
	global_load_lds_dwordx4 v[144:145], off
	v_lshl_add_u64 v[144:145], v[220:221], 0, s[14:15]
	s_mov_b32 m0, s53
	s_nop 0
	global_load_lds_dwordx4 v[144:145], off
	v_lshl_add_u64 v[144:145], v[222:223], 0, s[14:15]
	s_mov_b32 m0, s54
	s_nop 0
	global_load_lds_dwordx4 v[144:145], off
	s_waitcnt vmcnt(8)
	s_waitcnt lgkmcnt(0)
	s_barrier
	s_setprio 1
	v_mfma_f32_16x16x32_bf16 v[60:63], v[154:157], v[186:189], v[60:63]
	v_mfma_f32_16x16x32_bf16 v[52:55], v[162:165], v[186:189], v[52:55]
	v_mfma_f32_16x16x32_bf16 v[44:47], v[154:157], v[194:197], v[44:47]
	v_mfma_f32_16x16x32_bf16 v[36:39], v[162:165], v[194:197], v[36:39]
	v_mfma_f32_16x16x32_bf16 v[28:31], v[154:157], v[202:205], v[28:31]
	v_mfma_f32_16x16x32_bf16 v[20:23], v[162:165], v[202:205], v[20:23]
	v_mfma_f32_16x16x32_bf16 v[12:15], v[154:157], v[210:213], v[12:15]
	v_mfma_f32_16x16x32_bf16 v[4:7], v[162:165], v[210:213], v[4:7]
	v_mfma_f32_16x16x32_bf16 v[60:63], v[158:161], v[190:193], v[60:63]
	v_mfma_f32_16x16x32_bf16 v[52:55], v[166:169], v[190:193], v[52:55]
	v_mfma_f32_16x16x32_bf16 v[44:47], v[158:161], v[198:201], v[44:47]
	v_mfma_f32_16x16x32_bf16 v[36:39], v[166:169], v[198:201], v[36:39]
	v_mfma_f32_16x16x32_bf16 v[28:31], v[158:161], v[206:209], v[28:31]
	v_mfma_f32_16x16x32_bf16 v[20:23], v[166:169], v[206:209], v[20:23]
	v_mfma_f32_16x16x32_bf16 v[12:15], v[158:161], v[214:217], v[12:15]
	v_mfma_f32_16x16x32_bf16 v[4:7], v[166:169], v[214:217], v[4:7]
	v_mfma_f32_16x16x32_bf16 v[56:59], v[170:173], v[186:189], v[56:59]
	v_mfma_f32_16x16x32_bf16 v[48:51], v[178:181], v[186:189], v[48:51]
	v_mfma_f32_16x16x32_bf16 v[40:43], v[170:173], v[194:197], v[40:43]
	v_mfma_f32_16x16x32_bf16 v[32:35], v[178:181], v[194:197], v[32:35]
	v_mfma_f32_16x16x32_bf16 v[24:27], v[170:173], v[202:205], v[24:27]
	v_mfma_f32_16x16x32_bf16 v[16:19], v[178:181], v[202:205], v[16:19]
	v_mfma_f32_16x16x32_bf16 v[8:11], v[170:173], v[210:213], v[8:11]
	v_mfma_f32_16x16x32_bf16 v[0:3], v[178:181], v[210:213], v[0:3]
	v_mfma_f32_16x16x32_bf16 v[56:59], v[174:177], v[190:193], v[56:59]
	v_mfma_f32_16x16x32_bf16 v[48:51], v[182:185], v[190:193], v[48:51]
	v_mfma_f32_16x16x32_bf16 v[40:43], v[174:177], v[198:201], v[40:43]
	v_mfma_f32_16x16x32_bf16 v[32:35], v[182:185], v[198:201], v[32:35]
	v_mfma_f32_16x16x32_bf16 v[24:27], v[174:177], v[206:209], v[24:27]
	v_mfma_f32_16x16x32_bf16 v[16:19], v[182:185], v[206:209], v[16:19]
	v_mfma_f32_16x16x32_bf16 v[8:11], v[174:177], v[214:217], v[8:11]
	v_mfma_f32_16x16x32_bf16 v[0:3], v[182:185], v[214:217], v[0:3]
	s_barrier
	s_setprio 0
	s_add_i32 s68, s68, 2
	s_add_u32 s38, s38, 0x100
	s_addc_u32 s39, s39, 0
	s_add_u32 s66, s66, 0x100
	s_addc_u32 s67, s67, 0

; #define PG8_STAGE(bufoff, gbase, voff) do { _Pragma("unroll") for (int _i = 0; _i < 2; ++_i) \
;         __builtin_amdgcn_global_load_lds((const unsigned*)((const char*)(gbase) + (voff)[_i]), (PG8_LAS unsigned*)(lds + (bufoff) + ldsw + _i * 8192), 16, 0, 0); } while (0)
; #define PG8_LDA(dst, b, h) do { _Pragma("unroll") for (int m = 0; m < 4; ++m) _Pragma("unroll") for (int k = 0; k < 2; ++k) dst[m][k] = *(const PG8_LAS bf16x8*)(lds + PG8_SA(b, h) + aoff + m * 2048 + k * 1024); } while (0)
; #define PG8_LDB(dst, b, h) do { _Pragma("unroll") for (int n = 0; n < 2; ++n) _Pragma("unroll") for (int k = 0; k < 2; ++k) dst[n][k] = *(const PG8_LAS bf16x8*)(lds + PG8_SB(b, h) + boff + n * 2048 + k * 1024); } while (0)
; #define PG8_WAIT_V(n) asm volatile("s_waitcnt vmcnt(" #n ")" ::: "memory")
; #define PG8_WAIT_L(n) asm volatile("s_waitcnt lgkmcnt(" #n ")" ::: "memory")
; #define PG8_BAR __builtin_amdgcn_s_barrier()
; #define PG8_SCHED __builtin_amdgcn_sched_barrier(0)
; template <class Epi, class Sched, bool ALIGN_EPI = false, bool SP2 = false>
; __device__ __forceinline__ void gemm_phase(PG8_LAS unsigned char* lds, const Gemm g, const Sched& S, const Epi& E) {
;     ...
;         const bool has_next = S.next(ui + 1, nxt);
;         const char* nA = has_next ? (const char*)g.A + (size_t)nxt.pm * tstep : cA; const char* nB = has_next ? (const char*)g.Bt + (size_t)nxt.pn * tstep : cB;
;         for (int t = 0; t < nt; t += 2) {
;             const bool last = (t == nt - 2);
;             if constexpr (Epi::PREFETCH) { if (t == nt - 4) E.prefetch(cur, lds + STAGE_BYTES + 1024, tid); }
;             const char* a1 = cA + (size_t)(t + 1) * kstep;
;             const char* a2 = last ? nA : cA + (size_t)(t + 2) * kstep; const char* b2 = last ? nB : cB + (size_t)(t + 2) * kstep;
;             const char* a3 = a2 + kstep; const char* b3 = b2 + kstep;
;             if (last && has_next) S.a_ready(nxt);
;             if constexpr (SP2) {
;             PG8_LDB(B0, 0, 0); PG8_LDB(B1, 0, 1); PG8_SCHED; PG8_LDA(At, 0, 0); PG8_STAGE(PG8_SA(1, 1), a1 + hstep, voffA);
;             PG8_WAIT_V(8); PG8_WAIT_L(0); PG8_BAR; PG8_MMA(0, 0, At, B0); PG8_MMA(0, 1, At, B1); PG8_BAR; PG8_SCHED;
;             PG8_LDA(At, 0, 1); PG8_STAGE(PG8_SB(0, 0), b2, voffB); PG8_STAGE(PG8_SB(0, 1), b2 + hstep, voffB); PG8_STAGE(PG8_SA(0, 0), a2, voffA);
.LBB0_1905:
	s_ashr_i32 s21, s20, 31
	s_lshl_b64 s[22:23], s[20:21], 19
	s_add_u32 s22, s44, s22
	s_addc_u32 s23, s45, s23
	s_and_b64 s[34:35], s[4:5], exec
	s_cselect_b32 s21, s23, s39
	s_cselect_b32 s64, s22, s38
	s_ashr_i32 s19, s18, 31
	s_lshl_b64 s[34:35], s[18:19], 19
	s_add_u32 s34, s46, s34
	s_addc_u32 s35, s47, s35
	s_and_b64 s[42:43], s[4:5], exec
	s_cselect_b32 s19, s35, s41
	s_cselect_b32 s65, s34, s40
	s_add_u32 s38, s38, 0x40080
	s_addc_u32 s39, s39, 0
	s_add_u32 s66, s40, 0x100
	s_addc_u32 s67, s41, 0
	s_mov_b32 s68, -2
	ds_read_b128 v[144:147], v151
	ds_read_b128 v[156:159], v151 offset:1024
	ds_read_b128 v[160:163], v151 offset:2048
	ds_read_b128 v[164:167], v151 offset:3072
	ds_read_b128 v[168:171], v152
	ds_read_b128 v[172:175], v152 offset:1024
	ds_read_b128 v[176:179], v152 offset:2048
	ds_read_b128 v[180:183], v152 offset:3072
	s_add_u32 s40, s38, 0xfffc0080
	s_addc_u32 s41, s39, -1
	s_cmp_eq_u32 s68, 12
	s_cselect_b32 s43, s21, s41
	s_cselect_b32 s42, s64, s40
	s_cselect_b32 s41, s19, s67
	s_cselect_b32 s40, s65, s66
	v_lshl_add_u64 v[216:217], s[38:39], 0, v[136:137]
	s_add_i32 m0, s37, 0xc000
	ds_read_b128 v[184:187], v153
	ds_read_b128 v[188:191], v153 offset:1024
	ds_read_b128 v[192:195], v153 offset:2048
	ds_read_b128 v[196:199], v153 offset:3072
	ds_read_b128 v[200:203], v153 offset:4096
	ds_read_b128 v[204:207], v153 offset:5120
	ds_read_b128 v[208:211], v153 offset:6144
	ds_read_b128 v[212:215], v153 offset:7168
	global_load_lds_dwordx4 v[216:217], off
	v_lshl_add_u64 v[216:217], s[38:39], 0, v[138:139]
	s_add_i32 m0, s37, 0xe000
	s_nop 0
	global_load_lds_dwordx4 v[216:217], off
	s_waitcnt vmcnt(8)
	s_waitcnt lgkmcnt(0)
	s_barrier
	s_setprio 1
	v_mfma_f32_16x16x32_bf16 v[124:127], v[144:147], v[184:187], 0
	v_mfma_f32_16x16x32_bf16 v[120:123], v[160:163], v[184:187], 0
	v_mfma_f32_16x16x32_bf16 v[108:111], v[144:147], v[192:195], 0
	v_mfma_f32_16x16x32_bf16 v[104:107], v[160:163], v[192:195], 0
	v_mfma_f32_16x16x32_bf16 v[92:95], v[144:147], v[200:203], 0
	v_mfma_f32_16x16x32_bf16 v[88:91], v[160:163], v[200:203], 0
	v_mfma_f32_16x16x32_bf16 v[76:79], v[144:147], v[208:211], 0
	v_mfma_f32_16x16x32_bf16 v[72:75], v[160:163], v[208:211], 0
	v_mfma_f32_16x16x32_bf16 v[124:127], v[156:159], v[188:191], v[124:127]
	v_mfma_f32_16x16x32_bf16 v[120:123], v[164:167], v[188:191], v[120:123]
	v_mfma_f32_16x16x32_bf16 v[108:111], v[156:159], v[196:199], v[108:111]
	v_mfma_f32_16x16x32_bf16 v[104:107], v[164:167], v[196:199], v[104:107]
	v_mfma_f32_16x16x32_bf16 v[92:95], v[156:159], v[204:207], v[92:95]
	v_mfma_f32_16x16x32_bf16 v[88:91], v[164:167], v[204:207], v[88:91]
	v_mfma_f32_16x16x32_bf16 v[76:79], v[156:159], v[212:215], v[76:79]
	v_mfma_f32_16x16x32_bf16 v[72:75], v[164:167], v[212:215], v[72:75]
	v_mfma_f32_16x16x32_bf16 v[116:119], v[168:171], v[184:187], 0
	v_mfma_f32_16x16x32_bf16 v[112:115], v[176:179], v[184:187], 0
	v_mfma_f32_16x16x32_bf16 v[100:103], v[168:171], v[192:195], 0
	v_mfma_f32_16x16x32_bf16 v[96:99], v[176:179], v[192:195], 0
	v_mfma_f32_16x16x32_bf16 v[84:87], v[168:171], v[200:203], 0
	v_mfma_f32_16x16x32_bf16 v[80:83], v[176:179], v[200:203], 0
	v_mfma_f32_16x16x32_bf16 v[68:71], v[168:171], v[208:211], 0
	v_mfma_f32_16x16x32_bf16 v[64:67], v[176:179], v[208:211], 0
	v_mfma_f32_16x16x32_bf16 v[116:119], v[172:175], v[188:191], v[116:119]
	v_mfma_f32_16x16x32_bf16 v[112:115], v[180:183], v[188:191], v[112:115]
	v_mfma_f32_16x16x32_bf16 v[100:103], v[172:175], v[196:199], v[100:103]
	v_mfma_f32_16x16x32_bf16 v[96:99], v[180:183], v[196:199], v[96:99]
	v_mfma_f32_16x16x32_bf16 v[84:87], v[172:175], v[204:207], v[84:87]
	v_mfma_f32_16x16x32_bf16 v[80:83], v[180:183], v[204:207], v[80:83]
	v_mfma_f32_16x16x32_bf16 v[68:71], v[172:175], v[212:215], v[68:71]
	v_mfma_f32_16x16x32_bf16 v[64:67], v[180:183], v[212:215], v[64:67]
	s_barrier
	s_setprio 0
	s_add_i32 s69, s57, s48
	v_lshl_add_u64 v[216:217], s[40:41], 0, v[132:133]
	s_mov_b32 m0, s69
	ds_read_b128 v[184:187], v153 offset:16384
	ds_read_b128 v[188:191], v153 offset:17408
	ds_read_b128 v[192:195], v153 offset:18432
	ds_read_b128 v[196:199], v153 offset:19456
	ds_read_b128 v[200:203], v153 offset:20480
	ds_read_b128 v[204:207], v153 offset:21504
	ds_read_b128 v[208:211], v153 offset:22528
	ds_read_b128 v[212:215], v153 offset:23552
	global_load_lds_dwordx4 v[216:217], off
	s_add_i32 m0, s69, 0x2000
	s_add_u32 s70, s40, 0x40000
	v_lshl_add_u64 v[218:219], s[40:41], 0, v[128:129]
	s_addc_u32 s71, s41, 0
	s_add_i32 s69, s58, s48
	global_load_lds_dwordx4 v[218:219], off
	v_lshl_add_u64 v[220:221], s[70:71], 0, v[132:133]
	s_mov_b32 m0, s69
	v_lshl_add_u64 v[222:223], s[42:43], 0, v[130:131]
	global_load_lds_dwordx4 v[220:221], off
	v_lshl_add_u64 v[220:221], s[70:71], 0, v[128:129]
	s_add_i32 m0, s69, 0x2000
	s_nop 0
	global_load_lds_dwordx4 v[220:221], off
	v_lshl_add_u64 v[220:221], s[42:43], 0, v[134:135]
	s_mov_b32 m0, s37
	s_nop 0
	global_load_lds_dwordx4 v[220:221], off
	s_mov_b32 m0, s50
	s_nop 0
	global_load_lds_dwordx4 v[222:223], off
	s_waitcnt vmcnt(8)
	s_waitcnt lgkmcnt(0)
	s_barrier
; #define PG8_STAGE(bufoff, gbase, voff) do { _Pragma("unroll") for (int _i = 0; _i < 2; ++_i) \
;         __builtin_amdgcn_global_load_lds((const unsigned*)((const char*)(gbase) + (voff)[_i]), (PG8_LAS unsigned*)(lds + (bufoff) + ldsw + _i * 8192), 16, 0, 0); } while (0)
; #define PG8_LDA(dst, b, h) do { _Pragma("unroll") for (int m = 0; m < 4; ++m) _Pragma("unroll") for (int k = 0; k < 2; ++k) dst[m][k] = *(const PG8_LAS bf16x8*)(lds + PG8_SA(b, h) + aoff + m * 2048 + k * 1024); } while (0)
; #define PG8_LDB(dst, b, h) do { _Pragma("unroll") for (int n = 0; n < 2; ++n) _Pragma("unroll") for (int k = 0; k < 2; ++k) dst[n][k] = *(const PG8_LAS bf16x8*)(lds + PG8_SB(b, h) + boff + n * 2048 + k * 1024); } while (0)
; #define PG8_MMA(ai, bj, At, Bt) do { __builtin_amdgcn_s_setprio(1); _Pragma("unroll") for (int m = 0; m < 4; ++m) _Pragma("unroll") for (int n = 0; n < 2; ++n) _Pragma("unroll") for (int k = 0; k < 2; ++k) \
;         acc[ai][bj][m][n] = __builtin_amdgcn_mfma_f32_16x16x32_bf16(Bt[n][k], At[m][k], acc[ai][bj][m][n], 0, 0, 0); __builtin_amdgcn_s_setprio(0); } while (0)
; #define PG8_WAIT_V(n) asm volatile("s_waitcnt vmcnt(" #n ")" ::: "memory")
; #define PG8_WAIT_L(n) asm volatile("s_waitcnt lgkmcnt(" #n ")" ::: "memory")
; #define PG8_BAR __builtin_amdgcn_s_barrier()
; #define PG8_SCHED __builtin_amdgcn_sched_barrier(0)
; template <class Epi, class Sched, bool ALIGN_EPI = false, bool SP2 = false>
; __device__ __forceinline__ void gemm_phase(PG8_LAS unsigned char* lds, const Gemm g, const Sched& S, const Epi& E) {
;     ...
;             PG8_WAIT_V(8); PG8_WAIT_L(0); PG8_BAR; PG8_MMA(1, 0, At, B0); PG8_MMA(1, 1, At, B1); PG8_BAR; PG8_SCHED;
;             PG8_LDB(B0, 1, 0); PG8_LDB(B1, 1, 1); PG8_SCHED; PG8_LDA(At, 1, 0); PG8_STAGE(PG8_SA(0, 1), a2 + hstep, voffA);
;             PG8_WAIT_V(8); PG8_WAIT_L(0); PG8_BAR; PG8_MMA(0, 0, At, B0); PG8_MMA(0, 1, At, B1); PG8_BAR; PG8_SCHED;
	s_setprio 1
	v_mfma_f32_16x16x32_bf16 v[60:63], v[144:147], v[184:187], 0
	v_mfma_f32_16x16x32_bf16 v[56:59], v[160:163], v[184:187], 0
	v_mfma_f32_16x16x32_bf16 v[44:47], v[144:147], v[192:195], 0
	v_mfma_f32_16x16x32_bf16 v[40:43], v[160:163], v[192:195], 0
	v_mfma_f32_16x16x32_bf16 v[28:31], v[144:147], v[200:203], 0
	v_mfma_f32_16x16x32_bf16 v[24:27], v[160:163], v[200:203], 0
	v_mfma_f32_16x16x32_bf16 v[12:15], v[144:147], v[208:211], 0
	v_mfma_f32_16x16x32_bf16 v[8:11], v[160:163], v[208:211], 0
	v_mfma_f32_16x16x32_bf16 v[60:63], v[156:159], v[188:191], v[60:63]
	v_mfma_f32_16x16x32_bf16 v[56:59], v[164:167], v[188:191], v[56:59]
	v_mfma_f32_16x16x32_bf16 v[44:47], v[156:159], v[196:199], v[44:47]
	v_mfma_f32_16x16x32_bf16 v[40:43], v[164:167], v[196:199], v[40:43]
	v_mfma_f32_16x16x32_bf16 v[28:31], v[156:159], v[204:207], v[28:31]
	v_mfma_f32_16x16x32_bf16 v[24:27], v[164:167], v[204:207], v[24:27]
	v_mfma_f32_16x16x32_bf16 v[12:15], v[156:159], v[212:215], v[12:15]
	v_mfma_f32_16x16x32_bf16 v[8:11], v[164:167], v[212:215], v[8:11]
	v_mfma_f32_16x16x32_bf16 v[52:55], v[168:171], v[184:187], 0
	v_mfma_f32_16x16x32_bf16 v[48:51], v[176:179], v[184:187], 0
	v_mfma_f32_16x16x32_bf16 v[36:39], v[168:171], v[192:195], 0
	v_mfma_f32_16x16x32_bf16 v[32:35], v[176:179], v[192:195], 0
	v_mfma_f32_16x16x32_bf16 v[20:23], v[168:171], v[200:203], 0
	v_mfma_f32_16x16x32_bf16 v[16:19], v[176:179], v[200:203], 0
	v_mfma_f32_16x16x32_bf16 v[4:7], v[168:171], v[208:211], 0
	v_mfma_f32_16x16x32_bf16 v[0:3], v[176:179], v[208:211], 0
	v_mfma_f32_16x16x32_bf16 v[52:55], v[172:175], v[188:191], v[52:55]
	v_mfma_f32_16x16x32_bf16 v[48:51], v[180:183], v[188:191], v[48:51]
	v_mfma_f32_16x16x32_bf16 v[36:39], v[172:175], v[196:199], v[36:39]
	v_mfma_f32_16x16x32_bf16 v[32:35], v[180:183], v[196:199], v[32:35]
	v_mfma_f32_16x16x32_bf16 v[20:23], v[172:175], v[204:207], v[20:23]
	v_mfma_f32_16x16x32_bf16 v[16:19], v[180:183], v[204:207], v[16:19]
	v_mfma_f32_16x16x32_bf16 v[4:7], v[172:175], v[212:215], v[4:7]
	v_mfma_f32_16x16x32_bf16 v[0:3], v[180:183], v[212:215], v[0:3]
	s_barrier
	s_setprio 0
	s_add_i32 s69, 0, 0x18000
	s_add_i32 s70, 0, 0x1c000
	v_add_u32_e32 v164, s69, v149
	v_add_u32_e32 v180, s70, v149
	ds_read_b128 v[144:147], v164
	ds_read_b128 v[156:159], v164 offset:1024
	ds_read_b128 v[160:163], v164 offset:2048
	ds_read_b128 v[164:167], v164 offset:3072
	ds_read_b128 v[168:171], v180
	ds_read_b128 v[172:175], v180 offset:1024
	ds_read_b128 v[176:179], v180 offset:2048
	ds_read_b128 v[180:183], v180 offset:3072
	s_add_u32 s42, s42, 0x40000
	s_addc_u32 s43, s43, 0
	s_mov_b32 m0, s51
	v_lshl_add_u64 v[224:225], s[42:43], 0, v[134:135]
	ds_read_b128 v[184:187], v153 offset:32768
	ds_read_b128 v[188:191], v153 offset:33792
	ds_read_b128 v[192:195], v153 offset:34816
	ds_read_b128 v[196:199], v153 offset:35840
	ds_read_b128 v[200:203], v153 offset:36864
	ds_read_b128 v[204:207], v153 offset:37888
	ds_read_b128 v[208:211], v153 offset:38912
	ds_read_b128 v[212:215], v153 offset:39936
	global_load_lds_dwordx4 v[224:225], off
	v_lshl_add_u64 v[224:225], s[42:43], 0, v[130:131]
	s_mov_b32 m0, s52
	s_nop 0
	global_load_lds_dwordx4 v[224:225], off
	s_waitcnt vmcnt(8)
	s_waitcnt lgkmcnt(0)
	s_barrier
	s_setprio 1
	v_mfma_f32_16x16x32_bf16 v[124:127], v[144:147], v[184:187], v[124:127]
	v_mfma_f32_16x16x32_bf16 v[120:123], v[160:163], v[184:187], v[120:123]
	v_mfma_f32_16x16x32_bf16 v[108:111], v[144:147], v[192:195], v[108:111]
	v_mfma_f32_16x16x32_bf16 v[104:107], v[160:163], v[192:195], v[104:107]
	v_mfma_f32_16x16x32_bf16 v[92:95], v[144:147], v[200:203], v[92:95]
	v_mfma_f32_16x16x32_bf16 v[88:91], v[160:163], v[200:203], v[88:91]
	v_mfma_f32_16x16x32_bf16 v[76:79], v[144:147], v[208:211], v[76:79]
	v_mfma_f32_16x16x32_bf16 v[72:75], v[160:163], v[208:211], v[72:75]
	v_mfma_f32_16x16x32_bf16 v[124:127], v[156:159], v[188:191], v[124:127]
	v_mfma_f32_16x16x32_bf16 v[120:123], v[164:167], v[188:191], v[120:123]
	v_mfma_f32_16x16x32_bf16 v[108:111], v[156:159], v[196:199], v[108:111]
	v_mfma_f32_16x16x32_bf16 v[104:107], v[164:167], v[196:199], v[104:107]
	v_mfma_f32_16x16x32_bf16 v[92:95], v[156:159], v[204:207], v[92:95]
	v_mfma_f32_16x16x32_bf16 v[88:91], v[164:167], v[204:207], v[88:91]
	v_mfma_f32_16x16x32_bf16 v[76:79], v[156:159], v[212:215], v[76:79]
	v_mfma_f32_16x16x32_bf16 v[72:75], v[164:167], v[212:215], v[72:75]
	v_mfma_f32_16x16x32_bf16 v[116:119], v[168:171], v[184:187], v[116:119]
	v_mfma_f32_16x16x32_bf16 v[112:115], v[176:179], v[184:187], v[112:115]
	v_mfma_f32_16x16x32_bf16 v[100:103], v[168:171], v[192:195], v[100:103]
	v_mfma_f32_16x16x32_bf16 v[96:99], v[176:179], v[192:195], v[96:99]
	v_mfma_f32_16x16x32_bf16 v[84:87], v[168:171], v[200:203], v[84:87]
	v_mfma_f32_16x16x32_bf16 v[80:83], v[176:179], v[200:203], v[80:83]
	v_mfma_f32_16x16x32_bf16 v[68:71], v[168:171], v[208:211], v[68:71]
	v_mfma_f32_16x16x32_bf16 v[64:67], v[176:179], v[208:211], v[64:67]
	v_mfma_f32_16x16x32_bf16 v[116:119], v[172:175], v[188:191], v[116:119]
	v_mfma_f32_16x16x32_bf16 v[112:115], v[180:183], v[188:191], v[112:115]
	v_mfma_f32_16x16x32_bf16 v[100:103], v[172:175], v[196:199], v[100:103]
	v_mfma_f32_16x16x32_bf16 v[96:99], v[180:183], v[196:199], v[96:99]
	v_mfma_f32_16x16x32_bf16 v[84:87], v[172:175], v[204:207], v[84:87]
	v_mfma_f32_16x16x32_bf16 v[80:83], v[180:183], v[204:207], v[80:83]
	v_mfma_f32_16x16x32_bf16 v[68:71], v[172:175], v[212:215], v[68:71]
	v_mfma_f32_16x16x32_bf16 v[64:67], v[180:183], v[212:215], v[64:67]
	s_barrier
; #define PG8_STAGE(bufoff, gbase, voff) do { _Pragma("unroll") for (int _i = 0; _i < 2; ++_i) \
;         __builtin_amdgcn_global_load_lds((const unsigned*)((const char*)(gbase) + (voff)[_i]), (PG8_LAS unsigned*)(lds + (bufoff) + ldsw + _i * 8192), 16, 0, 0); } while (0)
; #define PG8_LDA(dst, b, h) do { _Pragma("unroll") for (int m = 0; m < 4; ++m) _Pragma("unroll") for (int k = 0; k < 2; ++k) dst[m][k] = *(const PG8_LAS bf16x8*)(lds + PG8_SA(b, h) + aoff + m * 2048 + k * 1024); } while (0)
; #define PG8_MMA(ai, bj, At, Bt) do { __builtin_amdgcn_s_setprio(1); _Pragma("unroll") for (int m = 0; m < 4; ++m) _Pragma("unroll") for (int n = 0; n < 2; ++n) _Pragma("unroll") for (int k = 0; k < 2; ++k) \
;         acc[ai][bj][m][n] = __builtin_amdgcn_mfma_f32_16x16x32_bf16(Bt[n][k], At[m][k], acc[ai][bj][m][n], 0, 0, 0); __builtin_amdgcn_s_setprio(0); } while (0)
; #define PG8_WAIT_V(n) asm volatile("s_waitcnt vmcnt(" #n ")" ::: "memory")
; #define PG8_WAIT_L(n) asm volatile("s_waitcnt lgkmcnt(" #n ")" ::: "memory")
; #define PG8_BAR __builtin_amdgcn_s_barrier()
; #define PG8_SCHED __builtin_amdgcn_sched_barrier(0)
; template <class Epi, class Sched, bool ALIGN_EPI = false, bool SP2 = false>
; __device__ __forceinline__ void gemm_phase(PG8_LAS unsigned char* lds, const Gemm g, const Sched& S, const Epi& E) {
;     ...
;         for (int t = 0; t < nt; t += 2) {
;             const bool last = (t == nt - 2);
;             if constexpr (Epi::PREFETCH) { if (t == nt - 4) E.prefetch(cur, lds + STAGE_BYTES + 1024, tid); }
;             const char* a1 = cA + (size_t)(t + 1) * kstep;
;             const char* a2 = last ? nA : cA + (size_t)(t + 2) * kstep; const char* b2 = last ? nB : cB + (size_t)(t + 2) * kstep;
;             const char* a3 = a2 + kstep; const char* b3 = b2 + kstep;
;     ...
;             PG8_LDA(At, 1, 1); PG8_STAGE(PG8_SB(1, 0), b3, voffB); PG8_STAGE(PG8_SB(1, 1), b3 + hstep, voffB); PG8_STAGE(PG8_SA(1, 0), a3, voffA);
;             PG8_WAIT_V(8); PG8_WAIT_L(0); PG8_BAR; PG8_MMA(1, 0, At, B0); PG8_MMA(1, 1, At, B1); PG8_BAR; PG8_SCHED;
	s_setprio 0
	s_add_i32 s42, s69, s48
	v_lshl_add_u64 v[216:217], v[216:217], 0, s[14:15]
	s_mov_b32 m0, s42
	ds_read_b128 v[184:187], v153 offset:49152
	ds_read_b128 v[188:191], v153 offset:50176
	ds_read_b128 v[192:195], v153 offset:51200
	ds_read_b128 v[196:199], v153 offset:52224
	ds_read_b128 v[200:203], v153 offset:53248
	ds_read_b128 v[204:207], v153 offset:54272
	ds_read_b128 v[208:211], v153 offset:55296
	ds_read_b128 v[212:215], v153 offset:56320
	global_load_lds_dwordx4 v[216:217], off
	s_add_i32 m0, s42, 0x2000
	s_add_u32 s40, s40, 0x40080
	v_lshl_add_u64 v[216:217], v[218:219], 0, s[14:15]
	s_addc_u32 s41, s41, 0
	s_add_i32 s42, s70, s48
	global_load_lds_dwordx4 v[216:217], off
	v_lshl_add_u64 v[216:217], s[40:41], 0, v[132:133]
	s_mov_b32 m0, s42
	s_nop 0
	global_load_lds_dwordx4 v[216:217], off
	v_lshl_add_u64 v[216:217], s[40:41], 0, v[128:129]
	s_add_i32 m0, s42, 0x2000
	s_nop 0
	global_load_lds_dwordx4 v[216:217], off
	v_lshl_add_u64 v[216:217], v[220:221], 0, s[14:15]
	s_mov_b32 m0, s53
	s_nop 0
	global_load_lds_dwordx4 v[216:217], off
	v_lshl_add_u64 v[216:217], v[222:223], 0, s[14:15]
	s_mov_b32 m0, s54
	s_nop 0
	global_load_lds_dwordx4 v[216:217], off
	s_waitcnt vmcnt(8)
	s_waitcnt lgkmcnt(0)
	s_barrier
	s_setprio 1
	v_mfma_f32_16x16x32_bf16 v[60:63], v[144:147], v[184:187], v[60:63]
	v_mfma_f32_16x16x32_bf16 v[56:59], v[160:163], v[184:187], v[56:59]
	v_mfma_f32_16x16x32_bf16 v[44:47], v[144:147], v[192:195], v[44:47]
	v_mfma_f32_16x16x32_bf16 v[40:43], v[160:163], v[192:195], v[40:43]
	v_mfma_f32_16x16x32_bf16 v[28:31], v[144:147], v[200:203], v[28:31]
	v_mfma_f32_16x16x32_bf16 v[24:27], v[160:163], v[200:203], v[24:27]
	v_mfma_f32_16x16x32_bf16 v[12:15], v[144:147], v[208:211], v[12:15]
	v_mfma_f32_16x16x32_bf16 v[8:11], v[160:163], v[208:211], v[8:11]
	v_mfma_f32_16x16x32_bf16 v[60:63], v[156:159], v[188:191], v[60:63]
	v_mfma_f32_16x16x32_bf16 v[56:59], v[164:167], v[188:191], v[56:59]
	v_mfma_f32_16x16x32_bf16 v[44:47], v[156:159], v[196:199], v[44:47]
	v_mfma_f32_16x16x32_bf16 v[40:43], v[164:167], v[196:199], v[40:43]
	v_mfma_f32_16x16x32_bf16 v[28:31], v[156:159], v[204:207], v[28:31]
	v_mfma_f32_16x16x32_bf16 v[24:27], v[164:167], v[204:207], v[24:27]
	v_mfma_f32_16x16x32_bf16 v[12:15], v[156:159], v[212:215], v[12:15]
	v_mfma_f32_16x16x32_bf16 v[8:11], v[164:167], v[212:215], v[8:11]
	v_mfma_f32_16x16x32_bf16 v[52:55], v[168:171], v[184:187], v[52:55]
	v_mfma_f32_16x16x32_bf16 v[48:51], v[176:179], v[184:187], v[48:51]
	v_mfma_f32_16x16x32_bf16 v[36:39], v[168:171], v[192:195], v[36:39]
	v_mfma_f32_16x16x32_bf16 v[32:35], v[176:179], v[192:195], v[32:35]
	v_mfma_f32_16x16x32_bf16 v[20:23], v[168:171], v[200:203], v[20:23]
	v_mfma_f32_16x16x32_bf16 v[16:19], v[176:179], v[200:203], v[16:19]
	v_mfma_f32_16x16x32_bf16 v[4:7], v[168:171], v[208:211], v[4:7]
	v_mfma_f32_16x16x32_bf16 v[0:3], v[176:179], v[208:211], v[0:3]
	v_mfma_f32_16x16x32_bf16 v[52:55], v[172:175], v[188:191], v[52:55]
	v_mfma_f32_16x16x32_bf16 v[48:51], v[180:183], v[188:191], v[48:51]
	v_mfma_f32_16x16x32_bf16 v[36:39], v[172:175], v[196:199], v[36:39]
	v_mfma_f32_16x16x32_bf16 v[32:35], v[180:183], v[196:199], v[32:35]
	v_mfma_f32_16x16x32_bf16 v[20:23], v[172:175], v[204:207], v[20:23]
	v_mfma_f32_16x16x32_bf16 v[16:19], v[180:183], v[204:207], v[16:19]
	v_mfma_f32_16x16x32_bf16 v[4:7], v[172:175], v[212:215], v[4:7]
	v_mfma_f32_16x16x32_bf16 v[0:3], v[180:183], v[212:215], v[0:3]
	s_barrier
	s_setprio 0
	s_add_i32 s68, s68, 2
	s_add_u32 s38, s38, 0x100
	s_addc_u32 s39, s39, 0
	s_add_u32 s66, s66, 0x100
	s_addc_u32 s67, s67, 0

; #define PG8_STAGE(bufoff, gbase, voff) do { _Pragma("unroll") for (int _i = 0; _i < 2; ++_i) \
;         __builtin_amdgcn_global_load_lds((const unsigned*)((const char*)(gbase) + (voff)[_i]), (PG8_LAS unsigned*)(lds + (bufoff) + ldsw + _i * 8192), 16, 0, 0); } while (0)
; #define PG8_LDA(dst, b, h) do { _Pragma("unroll") for (int m = 0; m < 4; ++m) _Pragma("unroll") for (int k = 0; k < 2; ++k) dst[m][k] = *(const PG8_LAS bf16x8*)(lds + PG8_SA(b, h) + aoff + m * 2048 + k * 1024); } while (0)
; #define PG8_LDB(dst, b, h) do { _Pragma("unroll") for (int n = 0; n < 2; ++n) _Pragma("unroll") for (int k = 0; k < 2; ++k) dst[n][k] = *(const PG8_LAS bf16x8*)(lds + PG8_SB(b, h) + boff + n * 2048 + k * 1024); } while (0)
; #define PG8_WAIT_V(n) asm volatile("s_waitcnt vmcnt(" #n ")" ::: "memory")
; #define PG8_WAIT_L(n) asm volatile("s_waitcnt lgkmcnt(" #n ")" ::: "memory")
; #define PG8_BAR __builtin_amdgcn_s_barrier()
; #define PG8_SCHED __builtin_amdgcn_sched_barrier(0)
; template <class Epi, class Sched, bool ALIGN_EPI = false, bool SP2 = false>
; __device__ __forceinline__ void gemm_phase(PG8_LAS unsigned char* lds, const Gemm g, const Sched& S, const Epi& E) {
;     ...
;         const char* nA = has_next ? (const char*)g.A + (size_t)nxt.pm * tstep : cA; const char* nB = has_next ? (const char*)g.Bt + (size_t)nxt.pn * tstep : cB;
;         for (int t = 0; t < nt; t += 2) {
;             const bool last = (t == nt - 2);
;             if constexpr (Epi::PREFETCH) { if (t == nt - 4) E.prefetch(cur, lds + STAGE_BYTES + 1024, tid); }
;             const char* a1 = cA + (size_t)(t + 1) * kstep;
;             const char* a2 = last ? nA : cA + (size_t)(t + 2) * kstep; const char* b2 = last ? nB : cB + (size_t)(t + 2) * kstep;
;             const char* a3 = a2 + kstep; const char* b3 = b2 + kstep;
;             if (last && has_next) S.a_ready(nxt);
;             if constexpr (SP2) {
;             PG8_LDB(B0, 0, 0); PG8_LDB(B1, 0, 1); PG8_SCHED; PG8_LDA(At, 0, 0); PG8_STAGE(PG8_SA(1, 1), a1 + hstep, voffA);
;             PG8_WAIT_V(8); PG8_WAIT_L(0); PG8_BAR; PG8_MMA(0, 0, At, B0); PG8_MMA(0, 1, At, B1); PG8_BAR; PG8_SCHED;
;             PG8_LDA(At, 0, 1); PG8_STAGE(PG8_SB(0, 0), b2, voffB); PG8_STAGE(PG8_SB(0, 1), b2 + hstep, voffB); PG8_STAGE(PG8_SA(0, 0), a2, voffA);
.LBB0_2596:
	s_add_u32 s38, s38, 0xb0080
	s_addc_u32 s39, s39, 0
	s_add_u32 s66, s40, 0x100
	s_addc_u32 s67, s41, 0
	s_mov_b32 s68, -2
	ds_read_b128 v[128:131], v201
	ds_read_b128 v[132:135], v201 offset:1024
	ds_read_b128 v[136:139], v201 offset:2048
	ds_read_b128 v[140:143], v201 offset:3072
	ds_read_b128 v[144:147], v202
	ds_read_b128 v[148:151], v202 offset:1024
	ds_read_b128 v[152:155], v202 offset:2048
	ds_read_b128 v[156:159], v202 offset:3072
	s_add_u32 s40, s38, 0xfff50080
	s_addc_u32 s41, s39, -1
	s_cmp_eq_u32 s68, 40
	s_cselect_b32 s43, s7, s41
	s_cselect_b32 s42, s6, s40
	s_cselect_b32 s41, s37, s67
	s_cselect_b32 s40, s36, s66
	v_lshl_add_u64 v[196:197], s[38:39], 0, v[176:177]
	s_add_i32 m0, s49, 0xc000
	ds_read_b128 v[160:163], v203
	ds_read_b128 v[164:167], v203 offset:1024
	ds_read_b128 v[184:187], v203 offset:2048
	ds_read_b128 v[188:191], v203 offset:3072
	ds_read_b128 v[192:195], v203 offset:4096
	ds_read_b128 v[204:207], v203 offset:5120
	ds_read_b128 v[208:211], v203 offset:6144
	ds_read_b128 v[212:215], v203 offset:7168
	global_load_lds_dwordx4 v[196:197], off
	v_lshl_add_u64 v[196:197], s[38:39], 0, v[178:179]
	s_add_i32 m0, s49, 0xe000
	s_nop 0
	global_load_lds_dwordx4 v[196:197], off
	s_waitcnt vmcnt(8)
	s_waitcnt lgkmcnt(0)
	s_barrier
	s_setprio 1
	v_mfma_f32_16x16x32_bf16 v[124:127], v[128:131], v[160:163], 0
	v_mfma_f32_16x16x32_bf16 v[120:123], v[136:139], v[160:163], 0
	v_mfma_f32_16x16x32_bf16 v[116:119], v[128:131], v[184:187], 0
	v_mfma_f32_16x16x32_bf16 v[104:107], v[136:139], v[184:187], 0
	v_mfma_f32_16x16x32_bf16 v[92:95], v[128:131], v[192:195], 0
	v_mfma_f32_16x16x32_bf16 v[88:91], v[136:139], v[192:195], 0
	v_mfma_f32_16x16x32_bf16 v[76:79], v[128:131], v[208:211], 0
	v_mfma_f32_16x16x32_bf16 v[72:75], v[136:139], v[208:211], 0
	v_mfma_f32_16x16x32_bf16 v[124:127], v[132:135], v[164:167], v[124:127]
	v_mfma_f32_16x16x32_bf16 v[120:123], v[140:143], v[164:167], v[120:123]
	v_mfma_f32_16x16x32_bf16 v[116:119], v[132:135], v[188:191], v[116:119]
	v_mfma_f32_16x16x32_bf16 v[104:107], v[140:143], v[188:191], v[104:107]
	v_mfma_f32_16x16x32_bf16 v[92:95], v[132:135], v[204:207], v[92:95]
	v_mfma_f32_16x16x32_bf16 v[88:91], v[140:143], v[204:207], v[88:91]
	v_mfma_f32_16x16x32_bf16 v[76:79], v[132:135], v[212:215], v[76:79]
	v_mfma_f32_16x16x32_bf16 v[72:75], v[140:143], v[212:215], v[72:75]
	v_mfma_f32_16x16x32_bf16 v[112:115], v[144:147], v[160:163], 0
	v_mfma_f32_16x16x32_bf16 v[108:111], v[152:155], v[160:163], 0
	v_mfma_f32_16x16x32_bf16 v[100:103], v[144:147], v[184:187], 0
	v_mfma_f32_16x16x32_bf16 v[96:99], v[152:155], v[184:187], 0
	v_mfma_f32_16x16x32_bf16 v[84:87], v[144:147], v[192:195], 0
	v_mfma_f32_16x16x32_bf16 v[80:83], v[152:155], v[192:195], 0
	v_mfma_f32_16x16x32_bf16 v[68:71], v[144:147], v[208:211], 0
	v_mfma_f32_16x16x32_bf16 v[64:67], v[152:155], v[208:211], 0
	v_mfma_f32_16x16x32_bf16 v[112:115], v[148:151], v[164:167], v[112:115]
	v_mfma_f32_16x16x32_bf16 v[108:111], v[156:159], v[164:167], v[108:111]
	v_mfma_f32_16x16x32_bf16 v[100:103], v[148:151], v[188:191], v[100:103]
	v_mfma_f32_16x16x32_bf16 v[96:99], v[156:159], v[188:191], v[96:99]
	v_mfma_f32_16x16x32_bf16 v[84:87], v[148:151], v[204:207], v[84:87]
	v_mfma_f32_16x16x32_bf16 v[80:83], v[156:159], v[204:207], v[80:83]
	v_mfma_f32_16x16x32_bf16 v[68:71], v[148:151], v[212:215], v[68:71]
	v_mfma_f32_16x16x32_bf16 v[64:67], v[156:159], v[212:215], v[64:67]
	s_barrier
	s_setprio 0
	s_add_i32 s69, s57, s48
	v_lshl_add_u64 v[196:197], s[40:41], 0, v[170:171]
	s_mov_b32 m0, s69
	ds_read_b128 v[160:163], v203 offset:16384
	ds_read_b128 v[164:167], v203 offset:17408
	ds_read_b128 v[184:187], v203 offset:18432
	ds_read_b128 v[188:191], v203 offset:19456
	ds_read_b128 v[192:195], v203 offset:20480
	ds_read_b128 v[204:207], v203 offset:21504
	ds_read_b128 v[208:211], v203 offset:22528
	ds_read_b128 v[212:215], v203 offset:23552
	global_load_lds_dwordx4 v[196:197], off
	s_add_i32 m0, s69, 0x2000
	s_add_u32 s70, s40, 0xb0000
	v_lshl_add_u64 v[216:217], s[40:41], 0, v[174:175]
	s_addc_u32 s71, s41, 0
	s_add_i32 s69, s58, s48
	global_load_lds_dwordx4 v[216:217], off
	v_lshl_add_u64 v[218:219], s[70:71], 0, v[170:171]
	s_mov_b32 m0, s69
	v_lshl_add_u64 v[220:221], s[42:43], 0, v[172:173]
	global_load_lds_dwordx4 v[218:219], off
	v_lshl_add_u64 v[218:219], s[70:71], 0, v[174:175]
	s_add_i32 m0, s69, 0x2000
	s_nop 0
	global_load_lds_dwordx4 v[218:219], off
	v_lshl_add_u64 v[218:219], s[42:43], 0, v[168:169]
	s_mov_b32 m0, s49
	s_nop 0
	global_load_lds_dwordx4 v[218:219], off
	s_mov_b32 m0, s50
	s_nop 0
	global_load_lds_dwordx4 v[220:221], off
	s_waitcnt vmcnt(8)
	s_waitcnt lgkmcnt(0)
	s_barrier
; #define PG8_STAGE(bufoff, gbase, voff) do { _Pragma("unroll") for (int _i = 0; _i < 2; ++_i) \
;         __builtin_amdgcn_global_load_lds((const unsigned*)((const char*)(gbase) + (voff)[_i]), (PG8_LAS unsigned*)(lds + (bufoff) + ldsw + _i * 8192), 16, 0, 0); } while (0)
; #define PG8_LDA(dst, b, h) do { _Pragma("unroll") for (int m = 0; m < 4; ++m) _Pragma("unroll") for (int k = 0; k < 2; ++k) dst[m][k] = *(const PG8_LAS bf16x8*)(lds + PG8_SA(b, h) + aoff + m * 2048 + k * 1024); } while (0)
; #define PG8_LDB(dst, b, h) do { _Pragma("unroll") for (int n = 0; n < 2; ++n) _Pragma("unroll") for (int k = 0; k < 2; ++k) dst[n][k] = *(const PG8_LAS bf16x8*)(lds + PG8_SB(b, h) + boff + n * 2048 + k * 1024); } while (0)
; #define PG8_MMA(ai, bj, At, Bt) do { __builtin_amdgcn_s_setprio(1); _Pragma("unroll") for (int m = 0; m < 4; ++m) _Pragma("unroll") for (int n = 0; n < 2; ++n) _Pragma("unroll") for (int k = 0; k < 2; ++k) \
;         acc[ai][bj][m][n] = __builtin_amdgcn_mfma_f32_16x16x32_bf16(Bt[n][k], At[m][k], acc[ai][bj][m][n], 0, 0, 0); __builtin_amdgcn_s_setprio(0); } while (0)
; #define PG8_WAIT_V(n) asm volatile("s_waitcnt vmcnt(" #n ")" ::: "memory")
; #define PG8_WAIT_L(n) asm volatile("s_waitcnt lgkmcnt(" #n ")" ::: "memory")
; #define PG8_BAR __builtin_amdgcn_s_barrier()
; #define PG8_SCHED __builtin_amdgcn_sched_barrier(0)
; template <class Epi, class Sched, bool ALIGN_EPI = false, bool SP2 = false>
; __device__ __forceinline__ void gemm_phase(PG8_LAS unsigned char* lds, const Gemm g, const Sched& S, const Epi& E) {
;     ...
;             PG8_WAIT_V(8); PG8_WAIT_L(0); PG8_BAR; PG8_MMA(1, 0, At, B0); PG8_MMA(1, 1, At, B1); PG8_BAR; PG8_SCHED;
;             PG8_LDB(B0, 1, 0); PG8_LDB(B1, 1, 1); PG8_SCHED; PG8_LDA(At, 1, 0); PG8_STAGE(PG8_SA(0, 1), a2 + hstep, voffA);
;             PG8_WAIT_V(8); PG8_WAIT_L(0); PG8_BAR; PG8_MMA(0, 0, At, B0); PG8_MMA(0, 1, At, B1); PG8_BAR; PG8_SCHED;
	s_setprio 1
	v_mfma_f32_16x16x32_bf16 v[60:63], v[128:131], v[160:163], 0
	v_mfma_f32_16x16x32_bf16 v[56:59], v[136:139], v[160:163], 0
	v_mfma_f32_16x16x32_bf16 v[44:47], v[128:131], v[184:187], 0
	v_mfma_f32_16x16x32_bf16 v[40:43], v[136:139], v[184:187], 0
	v_mfma_f32_16x16x32_bf16 v[28:31], v[128:131], v[192:195], 0
	v_mfma_f32_16x16x32_bf16 v[24:27], v[136:139], v[192:195], 0
	v_mfma_f32_16x16x32_bf16 v[12:15], v[128:131], v[208:211], 0
	v_mfma_f32_16x16x32_bf16 v[8:11], v[136:139], v[208:211], 0
	v_mfma_f32_16x16x32_bf16 v[60:63], v[132:135], v[164:167], v[60:63]
	v_mfma_f32_16x16x32_bf16 v[56:59], v[140:143], v[164:167], v[56:59]
	v_mfma_f32_16x16x32_bf16 v[44:47], v[132:135], v[188:191], v[44:47]
	v_mfma_f32_16x16x32_bf16 v[40:43], v[140:143], v[188:191], v[40:43]
	v_mfma_f32_16x16x32_bf16 v[28:31], v[132:135], v[204:207], v[28:31]
	v_mfma_f32_16x16x32_bf16 v[24:27], v[140:143], v[204:207], v[24:27]
	v_mfma_f32_16x16x32_bf16 v[12:15], v[132:135], v[212:215], v[12:15]
	v_mfma_f32_16x16x32_bf16 v[8:11], v[140:143], v[212:215], v[8:11]
	v_mfma_f32_16x16x32_bf16 v[52:55], v[144:147], v[160:163], 0
	v_mfma_f32_16x16x32_bf16 v[48:51], v[152:155], v[160:163], 0
	v_mfma_f32_16x16x32_bf16 v[36:39], v[144:147], v[184:187], 0
	v_mfma_f32_16x16x32_bf16 v[32:35], v[152:155], v[184:187], 0
	v_mfma_f32_16x16x32_bf16 v[20:23], v[144:147], v[192:195], 0
	v_mfma_f32_16x16x32_bf16 v[16:19], v[152:155], v[192:195], 0
	v_mfma_f32_16x16x32_bf16 v[4:7], v[144:147], v[208:211], 0
	v_mfma_f32_16x16x32_bf16 v[0:3], v[152:155], v[208:211], 0
	v_mfma_f32_16x16x32_bf16 v[52:55], v[148:151], v[164:167], v[52:55]
	v_mfma_f32_16x16x32_bf16 v[48:51], v[156:159], v[164:167], v[48:51]
	v_mfma_f32_16x16x32_bf16 v[36:39], v[148:151], v[188:191], v[36:39]
	v_mfma_f32_16x16x32_bf16 v[32:35], v[156:159], v[188:191], v[32:35]
	v_mfma_f32_16x16x32_bf16 v[20:23], v[148:151], v[204:207], v[20:23]
	v_mfma_f32_16x16x32_bf16 v[16:19], v[156:159], v[204:207], v[16:19]
	v_mfma_f32_16x16x32_bf16 v[4:7], v[148:151], v[212:215], v[4:7]
	v_mfma_f32_16x16x32_bf16 v[0:3], v[156:159], v[212:215], v[0:3]
	s_barrier
	s_setprio 0
	s_add_i32 s69, 0, 0x18000
	s_add_i32 s70, 0, 0x1c000
	v_add_u32_e32 v140, s69, v199
	v_add_u32_e32 v156, s70, v199
	ds_read_b128 v[128:131], v140
	ds_read_b128 v[132:135], v140 offset:1024
	ds_read_b128 v[136:139], v140 offset:2048
	ds_read_b128 v[140:143], v140 offset:3072
	ds_read_b128 v[144:147], v156
	ds_read_b128 v[148:151], v156 offset:1024
	ds_read_b128 v[152:155], v156 offset:2048
	ds_read_b128 v[156:159], v156 offset:3072
	s_add_u32 s42, s42, 0xb0000
	s_addc_u32 s43, s43, 0
	s_mov_b32 m0, s51
	v_lshl_add_u64 v[222:223], s[42:43], 0, v[168:169]
	ds_read_b128 v[160:163], v203 offset:32768
	ds_read_b128 v[164:167], v203 offset:33792
	ds_read_b128 v[184:187], v203 offset:34816
	ds_read_b128 v[188:191], v203 offset:35840
	ds_read_b128 v[192:195], v203 offset:36864
	ds_read_b128 v[204:207], v203 offset:37888
	ds_read_b128 v[208:211], v203 offset:38912
	ds_read_b128 v[212:215], v203 offset:39936
	global_load_lds_dwordx4 v[222:223], off
	v_lshl_add_u64 v[222:223], s[42:43], 0, v[172:173]
	s_mov_b32 m0, s52
	s_nop 0
	global_load_lds_dwordx4 v[222:223], off
	s_waitcnt vmcnt(8)
	s_waitcnt lgkmcnt(0)
	s_barrier
	s_setprio 1
	v_mfma_f32_16x16x32_bf16 v[124:127], v[128:131], v[160:163], v[124:127]
	v_mfma_f32_16x16x32_bf16 v[120:123], v[136:139], v[160:163], v[120:123]
	v_mfma_f32_16x16x32_bf16 v[116:119], v[128:131], v[184:187], v[116:119]
	v_mfma_f32_16x16x32_bf16 v[104:107], v[136:139], v[184:187], v[104:107]
	v_mfma_f32_16x16x32_bf16 v[92:95], v[128:131], v[192:195], v[92:95]
	v_mfma_f32_16x16x32_bf16 v[88:91], v[136:139], v[192:195], v[88:91]
	v_mfma_f32_16x16x32_bf16 v[76:79], v[128:131], v[208:211], v[76:79]
	v_mfma_f32_16x16x32_bf16 v[72:75], v[136:139], v[208:211], v[72:75]
	v_mfma_f32_16x16x32_bf16 v[124:127], v[132:135], v[164:167], v[124:127]
	v_mfma_f32_16x16x32_bf16 v[120:123], v[140:143], v[164:167], v[120:123]
	v_mfma_f32_16x16x32_bf16 v[116:119], v[132:135], v[188:191], v[116:119]
	v_mfma_f32_16x16x32_bf16 v[104:107], v[140:143], v[188:191], v[104:107]
	v_mfma_f32_16x16x32_bf16 v[92:95], v[132:135], v[204:207], v[92:95]
	v_mfma_f32_16x16x32_bf16 v[88:91], v[140:143], v[204:207], v[88:91]
	v_mfma_f32_16x16x32_bf16 v[76:79], v[132:135], v[212:215], v[76:79]
	v_mfma_f32_16x16x32_bf16 v[72:75], v[140:143], v[212:215], v[72:75]
	v_mfma_f32_16x16x32_bf16 v[112:115], v[144:147], v[160:163], v[112:115]
	v_mfma_f32_16x16x32_bf16 v[108:111], v[152:155], v[160:163], v[108:111]
	v_mfma_f32_16x16x32_bf16 v[100:103], v[144:147], v[184:187], v[100:103]
	v_mfma_f32_16x16x32_bf16 v[96:99], v[152:155], v[184:187], v[96:99]
	v_mfma_f32_16x16x32_bf16 v[84:87], v[144:147], v[192:195], v[84:87]
	v_mfma_f32_16x16x32_bf16 v[80:83], v[152:155], v[192:195], v[80:83]
	v_mfma_f32_16x16x32_bf16 v[68:71], v[144:147], v[208:211], v[68:71]
	v_mfma_f32_16x16x32_bf16 v[64:67], v[152:155], v[208:211], v[64:67]
	v_mfma_f32_16x16x32_bf16 v[112:115], v[148:151], v[164:167], v[112:115]
	v_mfma_f32_16x16x32_bf16 v[108:111], v[156:159], v[164:167], v[108:111]
	v_mfma_f32_16x16x32_bf16 v[100:103], v[148:151], v[188:191], v[100:103]
	v_mfma_f32_16x16x32_bf16 v[96:99], v[156:159], v[188:191], v[96:99]
	v_mfma_f32_16x16x32_bf16 v[84:87], v[148:151], v[204:207], v[84:87]
	v_mfma_f32_16x16x32_bf16 v[80:83], v[156:159], v[204:207], v[80:83]
	v_mfma_f32_16x16x32_bf16 v[68:71], v[148:151], v[212:215], v[68:71]
	v_mfma_f32_16x16x32_bf16 v[64:67], v[156:159], v[212:215], v[64:67]
	s_barrier
; #define PG8_STAGE(bufoff, gbase, voff) do { _Pragma("unroll") for (int _i = 0; _i < 2; ++_i) \
;         __builtin_amdgcn_global_load_lds((const unsigned*)((const char*)(gbase) + (voff)[_i]), (PG8_LAS unsigned*)(lds + (bufoff) + ldsw + _i * 8192), 16, 0, 0); } while (0)
; #define PG8_LDA(dst, b, h) do { _Pragma("unroll") for (int m = 0; m < 4; ++m) _Pragma("unroll") for (int k = 0; k < 2; ++k) dst[m][k] = *(const PG8_LAS bf16x8*)(lds + PG8_SA(b, h) + aoff + m * 2048 + k * 1024); } while (0)
; #define PG8_MMA(ai, bj, At, Bt) do { __builtin_amdgcn_s_setprio(1); _Pragma("unroll") for (int m = 0; m < 4; ++m) _Pragma("unroll") for (int n = 0; n < 2; ++n) _Pragma("unroll") for (int k = 0; k < 2; ++k) \
;         acc[ai][bj][m][n] = __builtin_amdgcn_mfma_f32_16x16x32_bf16(Bt[n][k], At[m][k], acc[ai][bj][m][n], 0, 0, 0); __builtin_amdgcn_s_setprio(0); } while (0)
; #define PG8_WAIT_V(n) asm volatile("s_waitcnt vmcnt(" #n ")" ::: "memory")
; #define PG8_WAIT_L(n) asm volatile("s_waitcnt lgkmcnt(" #n ")" ::: "memory")
; #define PG8_BAR __builtin_amdgcn_s_barrier()
; #define PG8_SCHED __builtin_amdgcn_sched_barrier(0)
; template <class Epi, class Sched, bool ALIGN_EPI = false, bool SP2 = false>
; __device__ __forceinline__ void gemm_phase(PG8_LAS unsigned char* lds, const Gemm g, const Sched& S, const Epi& E) {
;     ...
;         for (int t = 0; t < nt; t += 2) {
;             const bool last = (t == nt - 2);
;             if constexpr (Epi::PREFETCH) { if (t == nt - 4) E.prefetch(cur, lds + STAGE_BYTES + 1024, tid); }
;             const char* a1 = cA + (size_t)(t + 1) * kstep;
;             const char* a2 = last ? nA : cA + (size_t)(t + 2) * kstep; const char* b2 = last ? nB : cB + (size_t)(t + 2) * kstep;
;             const char* a3 = a2 + kstep; const char* b3 = b2 + kstep;
;     ...
;             PG8_LDA(At, 1, 1); PG8_STAGE(PG8_SB(1, 0), b3, voffB); PG8_STAGE(PG8_SB(1, 1), b3 + hstep, voffB); PG8_STAGE(PG8_SA(1, 0), a3, voffA);
;             PG8_WAIT_V(8); PG8_WAIT_L(0); PG8_BAR; PG8_MMA(1, 0, At, B0); PG8_MMA(1, 1, At, B1); PG8_BAR; PG8_SCHED;
	s_setprio 0
	s_add_i32 s42, s69, s48
	v_lshl_add_u64 v[196:197], v[196:197], 0, s[14:15]
	s_mov_b32 m0, s42
	ds_read_b128 v[160:163], v203 offset:49152
	ds_read_b128 v[164:167], v203 offset:50176
	ds_read_b128 v[184:187], v203 offset:51200
	ds_read_b128 v[188:191], v203 offset:52224
	ds_read_b128 v[192:195], v203 offset:53248
	ds_read_b128 v[204:207], v203 offset:54272
	ds_read_b128 v[208:211], v203 offset:55296
	ds_read_b128 v[212:215], v203 offset:56320
	global_load_lds_dwordx4 v[196:197], off
	s_add_i32 m0, s42, 0x2000
	s_add_u32 s40, s40, 0xb0080
	v_lshl_add_u64 v[196:197], v[216:217], 0, s[14:15]
	s_addc_u32 s41, s41, 0
	s_add_i32 s42, s70, s48
	global_load_lds_dwordx4 v[196:197], off
	v_lshl_add_u64 v[196:197], s[40:41], 0, v[170:171]
	s_mov_b32 m0, s42
	s_nop 0
	global_load_lds_dwordx4 v[196:197], off
	v_lshl_add_u64 v[196:197], s[40:41], 0, v[174:175]
	s_add_i32 m0, s42, 0x2000
	s_nop 0
	global_load_lds_dwordx4 v[196:197], off
	v_lshl_add_u64 v[196:197], v[218:219], 0, s[14:15]
	s_mov_b32 m0, s54
	s_nop 0
	global_load_lds_dwordx4 v[196:197], off
	v_lshl_add_u64 v[196:197], v[220:221], 0, s[14:15]
	s_mov_b32 m0, s55
	s_nop 0
	global_load_lds_dwordx4 v[196:197], off
	s_waitcnt vmcnt(8)
	s_waitcnt lgkmcnt(0)
	s_barrier
	s_setprio 1
	v_mfma_f32_16x16x32_bf16 v[60:63], v[128:131], v[160:163], v[60:63]
	v_mfma_f32_16x16x32_bf16 v[56:59], v[136:139], v[160:163], v[56:59]
	v_mfma_f32_16x16x32_bf16 v[44:47], v[128:131], v[184:187], v[44:47]
	v_mfma_f32_16x16x32_bf16 v[40:43], v[136:139], v[184:187], v[40:43]
	v_mfma_f32_16x16x32_bf16 v[28:31], v[128:131], v[192:195], v[28:31]
	v_mfma_f32_16x16x32_bf16 v[24:27], v[136:139], v[192:195], v[24:27]
	v_mfma_f32_16x16x32_bf16 v[12:15], v[128:131], v[208:211], v[12:15]
	v_mfma_f32_16x16x32_bf16 v[8:11], v[136:139], v[208:211], v[8:11]
	v_mfma_f32_16x16x32_bf16 v[60:63], v[132:135], v[164:167], v[60:63]
	v_mfma_f32_16x16x32_bf16 v[56:59], v[140:143], v[164:167], v[56:59]
	v_mfma_f32_16x16x32_bf16 v[44:47], v[132:135], v[188:191], v[44:47]
	v_mfma_f32_16x16x32_bf16 v[40:43], v[140:143], v[188:191], v[40:43]
	v_mfma_f32_16x16x32_bf16 v[28:31], v[132:135], v[204:207], v[28:31]
	v_mfma_f32_16x16x32_bf16 v[24:27], v[140:143], v[204:207], v[24:27]
	v_mfma_f32_16x16x32_bf16 v[12:15], v[132:135], v[212:215], v[12:15]
	v_mfma_f32_16x16x32_bf16 v[8:11], v[140:143], v[212:215], v[8:11]
	v_mfma_f32_16x16x32_bf16 v[52:55], v[144:147], v[160:163], v[52:55]
	v_mfma_f32_16x16x32_bf16 v[48:51], v[152:155], v[160:163], v[48:51]
	v_mfma_f32_16x16x32_bf16 v[36:39], v[144:147], v[184:187], v[36:39]
	v_mfma_f32_16x16x32_bf16 v[32:35], v[152:155], v[184:187], v[32:35]
	v_mfma_f32_16x16x32_bf16 v[20:23], v[144:147], v[192:195], v[20:23]
	v_mfma_f32_16x16x32_bf16 v[16:19], v[152:155], v[192:195], v[16:19]
	v_mfma_f32_16x16x32_bf16 v[4:7], v[144:147], v[208:211], v[4:7]
	v_mfma_f32_16x16x32_bf16 v[0:3], v[152:155], v[208:211], v[0:3]
	v_mfma_f32_16x16x32_bf16 v[52:55], v[148:151], v[164:167], v[52:55]
	v_mfma_f32_16x16x32_bf16 v[48:51], v[156:159], v[164:167], v[48:51]
	v_mfma_f32_16x16x32_bf16 v[36:39], v[148:151], v[188:191], v[36:39]
	v_mfma_f32_16x16x32_bf16 v[32:35], v[156:159], v[188:191], v[32:35]
	v_mfma_f32_16x16x32_bf16 v[20:23], v[148:151], v[204:207], v[20:23]
	v_mfma_f32_16x16x32_bf16 v[16:19], v[156:159], v[204:207], v[16:19]
	v_mfma_f32_16x16x32_bf16 v[4:7], v[148:151], v[212:215], v[4:7]
	v_mfma_f32_16x16x32_bf16 v[0:3], v[156:159], v[212:215], v[0:3]
	s_barrier
	s_setprio 0
	s_add_i32 s68, s68, 2
	s_add_u32 s38, s38, 0x100
	s_addc_u32 s39, s39, 0
	s_add_u32 s66, s66, 0x100
	s_addc_u32 s67, s67, 0
